# speedup vs baseline: 1.0483x; 1.0022x over previous
.Lh2_loop:
	ds_read_b128 v[140:143], v138
	ds_read_b128 v[144:147], v138 offset:1024
	ds_read_b128 v[148:151], v138 offset:2048
	ds_read_b128 v[152:155], v138 offset:3072
	s_add_u32 s8, s6, s65
	s_addc_u32 s9, s7, s66
	ds_read_b128 v[156:159], v134
	ds_read_b128 v[160:163], v134 offset:1024
	ds_read_b128 v[164:167], v133
	ds_read_b128 v[168:171], v133 offset:1024
	ds_read_b128 v[172:175], v132
	ds_read_b128 v[176:179], v132 offset:1024
	ds_read_b128 v[180:183], v131
	ds_read_b128 v[184:187], v131 offset:1024
	s_mov_b32 m0, s76
	s_mov_b32 m0, s75
	s_nop 0
	s_waitcnt lgkmcnt(8)
	s_barrier
	s_waitcnt lgkmcnt(0)
	s_waitcnt lgkmcnt(0)
	v_mfma_f32_16x16x32_bf16 v[124:127], v[140:143], v[156:159], v[124:127]
	v_mfma_f32_16x16x32_bf16 v[120:123], v[148:151], v[156:159], v[120:123]
	v_mfma_f32_16x16x32_bf16 v[116:119], v[140:143], v[164:167], v[116:119]
	v_mfma_f32_16x16x32_bf16 v[112:115], v[148:151], v[164:167], v[112:115]
	v_mfma_f32_16x16x32_bf16 v[108:111], v[140:143], v[172:175], v[108:111]
	v_mfma_f32_16x16x32_bf16 v[104:107], v[148:151], v[172:175], v[104:107]
	v_mfma_f32_16x16x32_bf16 v[100:103], v[140:143], v[180:183], v[100:103]
	v_mfma_f32_16x16x32_bf16 v[96:99], v[148:151], v[180:183], v[96:99]
	v_mfma_f32_16x16x32_bf16 v[124:127], v[144:147], v[160:163], v[124:127]
	v_mfma_f32_16x16x32_bf16 v[120:123], v[152:155], v[160:163], v[120:123]
	v_mfma_f32_16x16x32_bf16 v[116:119], v[144:147], v[168:171], v[116:119]
	v_mfma_f32_16x16x32_bf16 v[112:115], v[152:155], v[168:171], v[112:115]
	v_mfma_f32_16x16x32_bf16 v[108:111], v[144:147], v[176:179], v[108:111]
	v_mfma_f32_16x16x32_bf16 v[104:107], v[152:155], v[176:179], v[104:107]
	v_mfma_f32_16x16x32_bf16 v[100:103], v[144:147], v[184:187], v[100:103]
	v_mfma_f32_16x16x32_bf16 v[96:99], v[152:155], v[184:187], v[96:99]
	s_barrier
	s_add_u32 s10, s6, s36
	s_addc_u32 s11, s7, s37
	ds_read_b128 v[188:191], v137
	ds_read_b128 v[192:195], v137 offset:1024
	ds_read_b128 v[202:205], v137 offset:2048
	ds_read_b128 v[206:209], v137 offset:3072
	s_mov_b32 m0, s63
	s_add_u32 s98, s10, s46
	s_addc_u32 s99, s11, s47
	global_load_lds_dwordx4 v129, s[98:99]
	s_mov_b32 m0, s64
	s_nop 0
	global_load_lds_dwordx4 v130, s[98:99]
	s_barrier
	s_waitcnt lgkmcnt(0)
	s_waitcnt lgkmcnt(0)
	v_mfma_f32_16x16x32_bf16 v[92:95], v[188:191], v[156:159], v[92:95]
	v_mfma_f32_16x16x32_bf16 v[88:91], v[202:205], v[156:159], v[88:91]
	v_mfma_f32_16x16x32_bf16 v[84:87], v[188:191], v[164:167], v[84:87]
	v_mfma_f32_16x16x32_bf16 v[80:83], v[202:205], v[164:167], v[80:83]
	v_mfma_f32_16x16x32_bf16 v[76:79], v[188:191], v[172:175], v[76:79]
	v_mfma_f32_16x16x32_bf16 v[72:75], v[202:205], v[172:175], v[72:75]
	v_mfma_f32_16x16x32_bf16 v[68:71], v[188:191], v[180:183], v[68:71]
	v_mfma_f32_16x16x32_bf16 v[64:67], v[202:205], v[180:183], v[64:67]
	v_mfma_f32_16x16x32_bf16 v[92:95], v[192:195], v[160:163], v[92:95]
	v_mfma_f32_16x16x32_bf16 v[88:91], v[206:209], v[160:163], v[88:91]
	v_mfma_f32_16x16x32_bf16 v[84:87], v[192:195], v[168:171], v[84:87]
	v_mfma_f32_16x16x32_bf16 v[80:83], v[206:209], v[168:171], v[80:83]
	v_mfma_f32_16x16x32_bf16 v[76:79], v[192:195], v[176:179], v[76:79]
	v_mfma_f32_16x16x32_bf16 v[72:75], v[206:209], v[176:179], v[72:75]
	v_mfma_f32_16x16x32_bf16 v[68:71], v[192:195], v[184:187], v[68:71]
	v_mfma_f32_16x16x32_bf16 v[64:67], v[206:209], v[184:187], v[64:67]
	s_barrier
	s_mov_b32 m0, s62
	s_add_u32 s98, s8, s48
	s_addc_u32 s99, s9, s49
	global_load_lds_dwordx4 v129, s[98:99]
	s_mov_b32 m0, s67
	s_nop 0
	global_load_lds_dwordx4 v130, s[98:99]
	s_waitcnt vmcnt(4)
	s_barrier
	s_mov_b32 m0, s68
	s_add_u32 s98, s10, s50
	s_addc_u32 s99, s11, s51
	global_load_lds_dwordx4 v129, s[98:99]
	s_mov_b32 m0, s69
	s_nop 0
	global_load_lds_dwordx4 v130, s[98:99]
	s_barrier
	ds_read_b128 v[140:143], v136
	ds_read_b128 v[144:147], v136 offset:1024
	ds_read_b128 v[148:151], v136 offset:2048
	ds_read_b128 v[152:155], v136 offset:3072
	ds_read_b128 v[156:159], v134 offset:32768
	ds_read_b128 v[160:163], v134 offset:33792
	ds_read_b128 v[164:167], v133 offset:32768
	ds_read_b128 v[168:171], v133 offset:33792
	ds_read_b128 v[172:175], v132 offset:32768
	ds_read_b128 v[176:179], v132 offset:33792
	ds_read_b128 v[180:183], v131 offset:32768
	ds_read_b128 v[184:187], v131 offset:33792
	s_mov_b32 m0, s70
	s_mov_b32 m0, s71
	s_nop 0
	s_waitcnt lgkmcnt(8)
	s_barrier
	s_waitcnt lgkmcnt(0)
	s_waitcnt lgkmcnt(0)
	v_mfma_f32_16x16x32_bf16 v[124:127], v[140:143], v[156:159], v[124:127]
	v_mfma_f32_16x16x32_bf16 v[120:123], v[148:151], v[156:159], v[120:123]
	v_mfma_f32_16x16x32_bf16 v[116:119], v[140:143], v[164:167], v[116:119]
	v_mfma_f32_16x16x32_bf16 v[112:115], v[148:151], v[164:167], v[112:115]
	v_mfma_f32_16x16x32_bf16 v[108:111], v[140:143], v[172:175], v[108:111]
	v_mfma_f32_16x16x32_bf16 v[104:107], v[148:151], v[172:175], v[104:107]
	v_mfma_f32_16x16x32_bf16 v[100:103], v[140:143], v[180:183], v[100:103]
	v_mfma_f32_16x16x32_bf16 v[96:99], v[148:151], v[180:183], v[96:99]
	v_mfma_f32_16x16x32_bf16 v[124:127], v[144:147], v[160:163], v[124:127]
	v_mfma_f32_16x16x32_bf16 v[120:123], v[152:155], v[160:163], v[120:123]
	v_mfma_f32_16x16x32_bf16 v[116:119], v[144:147], v[168:171], v[116:119]
	v_mfma_f32_16x16x32_bf16 v[112:115], v[152:155], v[168:171], v[112:115]
	v_mfma_f32_16x16x32_bf16 v[108:111], v[144:147], v[176:179], v[108:111]
	v_mfma_f32_16x16x32_bf16 v[104:107], v[152:155], v[176:179], v[104:107]
	v_mfma_f32_16x16x32_bf16 v[100:103], v[144:147], v[184:187], v[100:103]
	v_mfma_f32_16x16x32_bf16 v[96:99], v[152:155], v[184:187], v[96:99]
	s_barrier
	ds_read_b128 v[188:191], v135
	ds_read_b128 v[192:195], v135 offset:1024
	ds_read_b128 v[202:205], v135 offset:2048
	ds_read_b128 v[206:209], v135 offset:3072
	s_mov_b32 m0, s28
	s_add_u32 s98, s10, s92
	s_addc_u32 s99, s11, s93
	global_load_lds_dwordx4 v129, s[98:99]
	s_mov_b32 m0, s29
	s_nop 0
	global_load_lds_dwordx4 v130, s[98:99]
	s_barrier
	s_waitcnt lgkmcnt(0)
	s_waitcnt lgkmcnt(0)
	v_mfma_f32_16x16x32_bf16 v[92:95], v[188:191], v[156:159], v[92:95]
	v_mfma_f32_16x16x32_bf16 v[88:91], v[202:205], v[156:159], v[88:91]
	v_mfma_f32_16x16x32_bf16 v[84:87], v[188:191], v[164:167], v[84:87]
	v_mfma_f32_16x16x32_bf16 v[80:83], v[202:205], v[164:167], v[80:83]
	v_mfma_f32_16x16x32_bf16 v[76:79], v[188:191], v[172:175], v[76:79]
	v_mfma_f32_16x16x32_bf16 v[72:75], v[202:205], v[172:175], v[72:75]
	v_mfma_f32_16x16x32_bf16 v[68:71], v[188:191], v[180:183], v[68:71]
	v_mfma_f32_16x16x32_bf16 v[64:67], v[202:205], v[180:183], v[64:67]
	v_mfma_f32_16x16x32_bf16 v[92:95], v[192:195], v[160:163], v[92:95]
	v_mfma_f32_16x16x32_bf16 v[88:91], v[206:209], v[160:163], v[88:91]
	v_mfma_f32_16x16x32_bf16 v[84:87], v[192:195], v[168:171], v[84:87]
	v_mfma_f32_16x16x32_bf16 v[80:83], v[206:209], v[168:171], v[80:83]
	v_mfma_f32_16x16x32_bf16 v[76:79], v[192:195], v[176:179], v[76:79]
	v_mfma_f32_16x16x32_bf16 v[72:75], v[206:209], v[176:179], v[72:75]
	v_mfma_f32_16x16x32_bf16 v[68:71], v[192:195], v[184:187], v[68:71]
	v_mfma_f32_16x16x32_bf16 v[64:67], v[206:209], v[184:187], v[64:67]
	v_mov_b32_e32 v210, v130
	s_barrier
	v_mov_b32_e32 v211, v197
	s_mov_b32 m0, s72
	s_add_u32 s98, s8, s96
	s_addc_u32 s99, s9, s97
	global_load_lds_dwordx4 v129, s[98:99]
	s_mov_b32 m0, s73
	s_nop 0
	global_load_lds_dwordx4 v130, s[98:99]
	s_waitcnt vmcnt(4)
	s_barrier
	v_mov_b32_e32 v196, v129
	s_mov_b32 m0, s33
	s_add_u32 s98, s10, vcc_lo
	s_addc_u32 s99, s11, vcc_hi
	global_load_lds_dwordx4 v129, s[98:99]
	s_mov_b32 m0, s74
	s_nop 0
	global_load_lds_dwordx4 v130, s[98:99]
	s_barrier
	s_add_i32 s38, s38, 2
	s_add_u32 s6, s6, 0x100
	s_addc_u32 s7, s7, 0
	s_cmpk_lt_u32 s38, 0x54
	s_cbranch_scc1 .Lh2_loop
	s_add_u32 s4, s4, 0x2b80
	s_addc_u32 s5, s5, 0
	s_mov_b32 m0, s76
	ds_read_b128 v[140:143], v138
	ds_read_b128 v[144:147], v138 offset:1024
	ds_read_b128 v[148:151], v138 offset:2048
	ds_read_b128 v[152:155], v138 offset:3072
	ds_read_b128 v[156:159], v134
	ds_read_b128 v[160:163], v134 offset:1024
	ds_read_b128 v[164:167], v133
	ds_read_b128 v[168:171], v133 offset:1024
	ds_read_b128 v[172:175], v132
	ds_read_b128 v[176:179], v132 offset:1024
	ds_read_b128 v[180:183], v131
	ds_read_b128 v[184:187], v131 offset:1024
	s_nop 0
	s_mov_b32 m0, s75
	s_nop 0
	s_barrier
	s_waitcnt lgkmcnt(0)
	s_setprio 1
	s_waitcnt lgkmcnt(0)
	v_mfma_f32_16x16x32_bf16 v[124:127], v[140:143], v[156:159], v[124:127]
	v_mfma_f32_16x16x32_bf16 v[120:123], v[148:151], v[156:159], v[120:123]
	v_mfma_f32_16x16x32_bf16 v[116:119], v[140:143], v[164:167], v[116:119]
	v_mfma_f32_16x16x32_bf16 v[112:115], v[148:151], v[164:167], v[112:115]
	v_mfma_f32_16x16x32_bf16 v[108:111], v[140:143], v[172:175], v[108:111]
	v_mfma_f32_16x16x32_bf16 v[100:103], v[140:143], v[180:183], v[100:103]
	v_mfma_f32_16x16x32_bf16 v[96:99], v[148:151], v[180:183], v[96:99]
	v_mfma_f32_16x16x32_bf16 v[124:127], v[144:147], v[160:163], v[124:127]
	v_mfma_f32_16x16x32_bf16 v[120:123], v[152:155], v[160:163], v[120:123]
	v_mfma_f32_16x16x32_bf16 v[116:119], v[144:147], v[168:171], v[116:119]
	v_mfma_f32_16x16x32_bf16 v[112:115], v[152:155], v[168:171], v[112:115]
	v_mfma_f32_16x16x32_bf16 v[108:111], v[144:147], v[176:179], v[108:111]
	v_mfma_f32_16x16x32_bf16 v[104:107], v[148:151], v[172:175], v[104:107]
	v_mfma_f32_16x16x32_bf16 v[100:103], v[144:147], v[184:187], v[100:103]
	v_mfma_f32_16x16x32_bf16 v[96:99], v[152:155], v[184:187], v[96:99]
	v_mfma_f32_16x16x32_bf16 v[188:191], v[152:155], v[176:179], v[104:107]
	s_setprio 0
	s_barrier
	s_nop 2
	ds_read_b128 v[104:107], v137
	ds_read_b128 v[192:195], v137 offset:1024
	ds_read_b128 v[202:205], v137 offset:2048
	ds_read_b128 v[206:209], v137 offset:3072
	s_barrier
	s_waitcnt lgkmcnt(0)
	s_setprio 1
	s_waitcnt lgkmcnt(0)
	v_mfma_f32_16x16x32_bf16 v[92:95], v[104:107], v[156:159], v[92:95]
	v_mfma_f32_16x16x32_bf16 v[88:91], v[202:205], v[156:159], v[88:91]
	v_mfma_f32_16x16x32_bf16 v[80:83], v[202:205], v[164:167], v[80:83]
	v_mfma_f32_16x16x32_bf16 v[72:75], v[202:205], v[172:175], v[72:75]
	v_mfma_f32_16x16x32_bf16 v[64:67], v[202:205], v[180:183], v[64:67]
	v_mfma_f32_16x16x32_bf16 v[92:95], v[192:195], v[160:163], v[92:95]
	v_mfma_f32_16x16x32_bf16 v[88:91], v[206:209], v[160:163], v[88:91]
	v_mfma_f32_16x16x32_bf16 v[84:87], v[104:107], v[164:167], v[84:87]
	v_mfma_f32_16x16x32_bf16 v[80:83], v[206:209], v[168:171], v[80:83]
	v_mfma_f32_16x16x32_bf16 v[76:79], v[104:107], v[172:175], v[76:79]
	v_mfma_f32_16x16x32_bf16 v[72:75], v[206:209], v[176:179], v[72:75]
	v_mfma_f32_16x16x32_bf16 v[68:71], v[104:107], v[180:183], v[68:71]
	v_mfma_f32_16x16x32_bf16 v[64:67], v[206:209], v[184:187], v[64:67]
	v_mfma_f32_16x16x32_bf16 v[156:159], v[192:195], v[168:171], v[84:87]
	v_mfma_f32_16x16x32_bf16 v[160:163], v[192:195], v[176:179], v[76:79]
	v_mfma_f32_16x16x32_bf16 v[164:167], v[192:195], v[184:187], v[68:71]
	s_setprio 0
	s_barrier
	s_nop 1
	s_waitcnt vmcnt(2)
	s_barrier
	s_waitcnt lgkmcnt(0)
	s_setprio 1
	s_waitcnt lgkmcnt(0)
	s_setprio 0
	s_setprio 1
	s_setprio 0
	s_barrier
	ds_read_b128 v[16:19], v136
	ds_read_b128 v[180:183], v136 offset:1024
	ds_read_b128 v[184:187], v136 offset:2048
	ds_read_b128 v[192:195], v136 offset:3072
	ds_read_b128 v[0:3], v134 offset:32768
	ds_read_b128 v[4:7], v134 offset:33792
	ds_read_b128 v[8:11], v133 offset:32768
	ds_read_b128 v[12:15], v133 offset:33792
	ds_read_b128 v[44:47], v132 offset:32768
	ds_read_b128 v[202:205], v132 offset:33792
	ds_read_b128 v[206:209], v131 offset:32768
	ds_read_b128 v[222:225], v131 offset:33792
	s_waitcnt vmcnt(0)
	s_barrier
	s_waitcnt lgkmcnt(0)
	s_setprio 1
	s_waitcnt lgkmcnt(0)
	v_mfma_f32_16x16x32_bf16 v[28:31], v[16:19], v[0:3], v[124:127]
	v_mfma_f32_16x16x32_bf16 v[52:55], v[180:183], v[4:7], v[28:31]
	v_mfma_f32_16x16x32_bf16 v[28:31], v[184:187], v[0:3], v[120:123]
	v_mfma_f32_16x16x32_bf16 v[104:107], v[192:195], v[4:7], v[28:31]
	v_mfma_f32_16x16x32_bf16 v[28:31], v[16:19], v[8:11], v[116:119]
	v_mfma_f32_16x16x32_bf16 v[68:71], v[180:183], v[12:15], v[28:31]
	v_mfma_f32_16x16x32_bf16 v[28:31], v[184:187], v[8:11], v[112:115]
	v_mfma_f32_16x16x32_bf16 v[116:119], v[192:195], v[12:15], v[28:31]
	v_mfma_f32_16x16x32_bf16 v[28:31], v[16:19], v[44:47], v[108:111]
	v_mfma_f32_16x16x32_bf16 v[76:79], v[180:183], v[202:205], v[28:31]
	v_mfma_f32_16x16x32_bf16 v[28:31], v[184:187], v[44:47], v[188:191]
	v_mfma_f32_16x16x32_bf16 v[108:111], v[192:195], v[202:205], v[28:31]
	v_mfma_f32_16x16x32_bf16 v[28:31], v[16:19], v[206:209], v[100:103]
	v_mfma_f32_16x16x32_bf16 v[84:87], v[180:183], v[222:225], v[28:31]
	v_mfma_f32_16x16x32_bf16 v[28:31], v[184:187], v[206:209], v[96:99]
	v_mfma_f32_16x16x32_bf16 v[96:99], v[192:195], v[222:225], v[28:31]
	s_setprio 0
	s_barrier
	ds_read_b128 v[188:191], v135
	ds_read_b128 v[228:231], v135 offset:1024
	ds_read_b128 v[232:235], v135 offset:2048
	ds_read_b128 v[236:239], v135 offset:3072
	s_waitcnt vmcnt(0)
	s_barrier
	s_waitcnt lgkmcnt(0)
	s_setprio 1
	s_waitcnt lgkmcnt(0)
	v_mfma_f32_16x16x32_bf16 v[28:31], v[188:191], v[0:3], v[92:95]
	v_mfma_f32_16x16x32_bf16 v[0:3], v[232:235], v[0:3], v[88:91]
	v_mfma_f32_16x16x32_bf16 v[28:31], v[228:231], v[4:7], v[28:31]
	v_mfma_f32_16x16x32_bf16 v[0:3], v[236:239], v[4:7], v[0:3]
	v_mfma_f32_16x16x32_bf16 v[4:7], v[188:191], v[8:11], v[156:159]
	v_mfma_f32_16x16x32_bf16 v[36:39], v[228:231], v[12:15], v[4:7]
	v_mfma_f32_16x16x32_bf16 v[4:7], v[232:235], v[8:11], v[80:83]
	v_mfma_f32_16x16x32_bf16 v[4:7], v[236:239], v[12:15], v[4:7]
	v_mfma_f32_16x16x32_bf16 v[8:11], v[188:191], v[44:47], v[160:163]
	v_mfma_f32_16x16x32_bf16 v[12:15], v[188:191], v[206:209], v[164:167]
	v_mfma_f32_16x16x32_bf16 v[40:43], v[228:231], v[202:205], v[8:11]
	v_mfma_f32_16x16x32_bf16 v[8:11], v[232:235], v[44:47], v[72:75]
	v_mfma_f32_16x16x32_bf16 v[44:47], v[228:231], v[222:225], v[12:15]
	v_mfma_f32_16x16x32_bf16 v[12:15], v[232:235], v[206:209], v[64:67]
	v_mfma_f32_16x16x32_bf16 v[8:11], v[236:239], v[202:205], v[8:11]
	v_mfma_f32_16x16x32_bf16 v[12:15], v[236:239], v[222:225], v[12:15]
	s_setprio 0
	s_barrier
	s_barrier
	s_waitcnt lgkmcnt(0)
	s_setprio 1
	s_waitcnt lgkmcnt(0)
	s_setprio 0
	s_setprio 1
	s_setprio 0
	s_movk_i32 s4, 0x100
	v_cmp_gt_u32_e32 vcc, s4, v128
	s_barrier
	s_and_saveexec_b64 s[4:5], vcc
	s_cbranch_execz .Lh2_epi
	s_barrier

.LBB0_138:
	ds_read_b128 v[140:143], v138
	ds_read_b128 v[144:147], v138 offset:1024
	ds_read_b128 v[148:151], v138 offset:2048
	ds_read_b128 v[152:155], v138 offset:3072
	s_add_u32 s8, s6, s65
	s_addc_u32 s9, s7, s66
	ds_read_b128 v[156:159], v134
	ds_read_b128 v[160:163], v134 offset:1024
	ds_read_b128 v[164:167], v133
	ds_read_b128 v[168:171], v133 offset:1024
	ds_read_b128 v[172:175], v132
	ds_read_b128 v[176:179], v132 offset:1024
	ds_read_b128 v[180:183], v131
	ds_read_b128 v[184:187], v131 offset:1024
	s_mov_b32 m0, s76
	s_add_u32 s98, s8, s44
	s_addc_u32 s99, s9, s45
	global_load_lds_dwordx4 v129, s[98:99]
	s_mov_b32 m0, s75
	s_nop 0
	global_load_lds_dwordx4 v130, s[98:99]
	s_waitcnt lgkmcnt(8)
	s_barrier
	s_waitcnt lgkmcnt(0)
	s_waitcnt lgkmcnt(0)
	v_mfma_f32_16x16x32_bf16 v[124:127], v[140:143], v[156:159], v[124:127]
	v_mfma_f32_16x16x32_bf16 v[120:123], v[148:151], v[156:159], v[120:123]
	v_mfma_f32_16x16x32_bf16 v[116:119], v[140:143], v[164:167], v[116:119]
	v_mfma_f32_16x16x32_bf16 v[112:115], v[148:151], v[164:167], v[112:115]
	v_mfma_f32_16x16x32_bf16 v[108:111], v[140:143], v[172:175], v[108:111]
	v_mfma_f32_16x16x32_bf16 v[104:107], v[148:151], v[172:175], v[104:107]
	v_mfma_f32_16x16x32_bf16 v[100:103], v[140:143], v[180:183], v[100:103]
	v_mfma_f32_16x16x32_bf16 v[96:99], v[148:151], v[180:183], v[96:99]
	v_mfma_f32_16x16x32_bf16 v[124:127], v[144:147], v[160:163], v[124:127]
	v_mfma_f32_16x16x32_bf16 v[120:123], v[152:155], v[160:163], v[120:123]
	v_mfma_f32_16x16x32_bf16 v[116:119], v[144:147], v[168:171], v[116:119]
	v_mfma_f32_16x16x32_bf16 v[112:115], v[152:155], v[168:171], v[112:115]
	v_mfma_f32_16x16x32_bf16 v[108:111], v[144:147], v[176:179], v[108:111]
	v_mfma_f32_16x16x32_bf16 v[104:107], v[152:155], v[176:179], v[104:107]
	v_mfma_f32_16x16x32_bf16 v[100:103], v[144:147], v[184:187], v[100:103]
	v_mfma_f32_16x16x32_bf16 v[96:99], v[152:155], v[184:187], v[96:99]
	s_barrier
	s_add_u32 s10, s6, s36
	s_addc_u32 s11, s7, s37
	ds_read_b128 v[188:191], v137
	ds_read_b128 v[192:195], v137 offset:1024
	ds_read_b128 v[202:205], v137 offset:2048
	ds_read_b128 v[206:209], v137 offset:3072
	s_mov_b32 m0, s63
	s_add_u32 s98, s10, s46
	s_addc_u32 s99, s11, s47
	global_load_lds_dwordx4 v129, s[98:99]
	s_mov_b32 m0, s64
	s_nop 0
	global_load_lds_dwordx4 v130, s[98:99]
	s_barrier
	s_waitcnt lgkmcnt(0)
	s_waitcnt lgkmcnt(0)
	v_mfma_f32_16x16x32_bf16 v[92:95], v[188:191], v[156:159], v[92:95]
	v_mfma_f32_16x16x32_bf16 v[88:91], v[202:205], v[156:159], v[88:91]
	v_mfma_f32_16x16x32_bf16 v[84:87], v[188:191], v[164:167], v[84:87]
	v_mfma_f32_16x16x32_bf16 v[80:83], v[202:205], v[164:167], v[80:83]
	v_mfma_f32_16x16x32_bf16 v[76:79], v[188:191], v[172:175], v[76:79]
	v_mfma_f32_16x16x32_bf16 v[72:75], v[202:205], v[172:175], v[72:75]
	v_mfma_f32_16x16x32_bf16 v[68:71], v[188:191], v[180:183], v[68:71]
	v_mfma_f32_16x16x32_bf16 v[64:67], v[202:205], v[180:183], v[64:67]
	v_mfma_f32_16x16x32_bf16 v[92:95], v[192:195], v[160:163], v[92:95]
	v_mfma_f32_16x16x32_bf16 v[88:91], v[206:209], v[160:163], v[88:91]
	v_mfma_f32_16x16x32_bf16 v[84:87], v[192:195], v[168:171], v[84:87]
	v_mfma_f32_16x16x32_bf16 v[80:83], v[206:209], v[168:171], v[80:83]
	v_mfma_f32_16x16x32_bf16 v[76:79], v[192:195], v[176:179], v[76:79]
	v_mfma_f32_16x16x32_bf16 v[72:75], v[206:209], v[176:179], v[72:75]
	v_mfma_f32_16x16x32_bf16 v[68:71], v[192:195], v[184:187], v[68:71]
	v_mfma_f32_16x16x32_bf16 v[64:67], v[206:209], v[184:187], v[64:67]
	s_barrier
	ds_read_b128 v[156:159], v134 offset:16384
	ds_read_b128 v[160:163], v134 offset:17408
	ds_read_b128 v[164:167], v133 offset:16384
	ds_read_b128 v[168:171], v133 offset:17408
	ds_read_b128 v[172:175], v132 offset:16384
	ds_read_b128 v[176:179], v132 offset:17408
	ds_read_b128 v[180:183], v131 offset:16384
	ds_read_b128 v[184:187], v131 offset:17408
	s_mov_b32 m0, s62
	s_add_u32 s98, s8, s48
	s_addc_u32 s99, s9, s49
	global_load_lds_dwordx4 v129, s[98:99]
	s_mov_b32 m0, s67
	s_nop 0
	global_load_lds_dwordx4 v130, s[98:99]
	s_barrier
	s_waitcnt lgkmcnt(0)
	s_waitcnt lgkmcnt(0)
	v_mfma_f32_16x16x32_bf16 v[60:63], v[140:143], v[156:159], v[60:63]
	v_mfma_f32_16x16x32_bf16 v[56:59], v[148:151], v[156:159], v[56:59]
	v_mfma_f32_16x16x32_bf16 v[52:55], v[140:143], v[164:167], v[52:55]
	v_mfma_f32_16x16x32_bf16 v[48:51], v[148:151], v[164:167], v[48:51]
	v_mfma_f32_16x16x32_bf16 v[44:47], v[140:143], v[172:175], v[44:47]
	v_mfma_f32_16x16x32_bf16 v[40:43], v[148:151], v[172:175], v[40:43]
	v_mfma_f32_16x16x32_bf16 v[36:39], v[140:143], v[180:183], v[36:39]
	v_mfma_f32_16x16x32_bf16 v[32:35], v[148:151], v[180:183], v[32:35]
	v_mfma_f32_16x16x32_bf16 v[60:63], v[144:147], v[160:163], v[60:63]
	v_mfma_f32_16x16x32_bf16 v[56:59], v[152:155], v[160:163], v[56:59]
	v_mfma_f32_16x16x32_bf16 v[52:55], v[144:147], v[168:171], v[52:55]
	v_mfma_f32_16x16x32_bf16 v[48:51], v[152:155], v[168:171], v[48:51]
	v_mfma_f32_16x16x32_bf16 v[44:47], v[144:147], v[176:179], v[44:47]
	v_mfma_f32_16x16x32_bf16 v[40:43], v[152:155], v[176:179], v[40:43]
	v_mfma_f32_16x16x32_bf16 v[36:39], v[144:147], v[184:187], v[36:39]
	v_mfma_f32_16x16x32_bf16 v[32:35], v[152:155], v[184:187], v[32:35]
	s_barrier
	s_mov_b32 m0, s68
	s_add_u32 s98, s10, s50
	s_addc_u32 s99, s11, s51
	global_load_lds_dwordx4 v129, s[98:99]
	s_mov_b32 m0, s69
	s_nop 0
	global_load_lds_dwordx4 v130, s[98:99]
	s_waitcnt vmcnt(6)
	s_barrier
	v_mfma_f32_16x16x32_bf16 v[28:31], v[188:191], v[156:159], v[28:31]
	v_mfma_f32_16x16x32_bf16 v[24:27], v[202:205], v[156:159], v[24:27]
	v_mfma_f32_16x16x32_bf16 v[20:23], v[188:191], v[164:167], v[20:23]
	v_mfma_f32_16x16x32_bf16 v[16:19], v[202:205], v[164:167], v[16:19]
	v_mfma_f32_16x16x32_bf16 v[12:15], v[188:191], v[172:175], v[12:15]
	v_mfma_f32_16x16x32_bf16 v[8:11], v[202:205], v[172:175], v[8:11]
	v_mfma_f32_16x16x32_bf16 v[4:7], v[188:191], v[180:183], v[4:7]
	v_mfma_f32_16x16x32_bf16 v[0:3], v[202:205], v[180:183], v[0:3]
	v_mfma_f32_16x16x32_bf16 v[28:31], v[192:195], v[160:163], v[28:31]
	v_mfma_f32_16x16x32_bf16 v[24:27], v[206:209], v[160:163], v[24:27]
	v_mfma_f32_16x16x32_bf16 v[20:23], v[192:195], v[168:171], v[20:23]
	v_mfma_f32_16x16x32_bf16 v[16:19], v[206:209], v[168:171], v[16:19]
	v_mfma_f32_16x16x32_bf16 v[12:15], v[192:195], v[176:179], v[12:15]
	v_mfma_f32_16x16x32_bf16 v[8:11], v[206:209], v[176:179], v[8:11]
	v_mfma_f32_16x16x32_bf16 v[4:7], v[192:195], v[184:187], v[4:7]
	v_mfma_f32_16x16x32_bf16 v[0:3], v[206:209], v[184:187], v[0:3]
	s_barrier
	ds_read_b128 v[140:143], v136
	ds_read_b128 v[144:147], v136 offset:1024
	ds_read_b128 v[148:151], v136 offset:2048
	ds_read_b128 v[152:155], v136 offset:3072
	ds_read_b128 v[156:159], v134 offset:32768
	ds_read_b128 v[160:163], v134 offset:33792
	ds_read_b128 v[164:167], v133 offset:32768
	ds_read_b128 v[168:171], v133 offset:33792
	ds_read_b128 v[172:175], v132 offset:32768
	ds_read_b128 v[176:179], v132 offset:33792
	ds_read_b128 v[180:183], v131 offset:32768
	ds_read_b128 v[184:187], v131 offset:33792
	s_mov_b32 m0, s70
	s_add_u32 s98, s8, s90
	s_addc_u32 s99, s9, s91
	global_load_lds_dwordx4 v129, s[98:99]
	s_mov_b32 m0, s71
	s_nop 0
	global_load_lds_dwordx4 v130, s[98:99]
	s_waitcnt lgkmcnt(8)
	s_barrier
	s_waitcnt lgkmcnt(0)
	s_waitcnt lgkmcnt(0)
	v_mfma_f32_16x16x32_bf16 v[124:127], v[140:143], v[156:159], v[124:127]
	v_mfma_f32_16x16x32_bf16 v[120:123], v[148:151], v[156:159], v[120:123]
	v_mfma_f32_16x16x32_bf16 v[116:119], v[140:143], v[164:167], v[116:119]
	v_mfma_f32_16x16x32_bf16 v[112:115], v[148:151], v[164:167], v[112:115]
	v_mfma_f32_16x16x32_bf16 v[108:111], v[140:143], v[172:175], v[108:111]
	v_mfma_f32_16x16x32_bf16 v[104:107], v[148:151], v[172:175], v[104:107]
	v_mfma_f32_16x16x32_bf16 v[100:103], v[140:143], v[180:183], v[100:103]
	v_mfma_f32_16x16x32_bf16 v[96:99], v[148:151], v[180:183], v[96:99]
	v_mfma_f32_16x16x32_bf16 v[124:127], v[144:147], v[160:163], v[124:127]
	v_mfma_f32_16x16x32_bf16 v[120:123], v[152:155], v[160:163], v[120:123]
	v_mfma_f32_16x16x32_bf16 v[116:119], v[144:147], v[168:171], v[116:119]
	v_mfma_f32_16x16x32_bf16 v[112:115], v[152:155], v[168:171], v[112:115]
	v_mfma_f32_16x16x32_bf16 v[108:111], v[144:147], v[176:179], v[108:111]
	v_mfma_f32_16x16x32_bf16 v[104:107], v[152:155], v[176:179], v[104:107]
	v_mfma_f32_16x16x32_bf16 v[100:103], v[144:147], v[184:187], v[100:103]
	v_mfma_f32_16x16x32_bf16 v[96:99], v[152:155], v[184:187], v[96:99]
	s_barrier
	ds_read_b128 v[188:191], v135
	ds_read_b128 v[192:195], v135 offset:1024
	ds_read_b128 v[202:205], v135 offset:2048
	ds_read_b128 v[206:209], v135 offset:3072
	s_mov_b32 m0, s28
	s_add_u32 s98, s10, s92
	s_addc_u32 s99, s11, s93
	global_load_lds_dwordx4 v129, s[98:99]
	s_mov_b32 m0, s29
	s_nop 0
	global_load_lds_dwordx4 v130, s[98:99]
	s_barrier
	s_waitcnt lgkmcnt(0)
	s_waitcnt lgkmcnt(0)
	v_mfma_f32_16x16x32_bf16 v[92:95], v[188:191], v[156:159], v[92:95]
	v_mfma_f32_16x16x32_bf16 v[88:91], v[202:205], v[156:159], v[88:91]
	v_mfma_f32_16x16x32_bf16 v[84:87], v[188:191], v[164:167], v[84:87]
	v_mfma_f32_16x16x32_bf16 v[80:83], v[202:205], v[164:167], v[80:83]
	v_mfma_f32_16x16x32_bf16 v[76:79], v[188:191], v[172:175], v[76:79]
	v_mfma_f32_16x16x32_bf16 v[72:75], v[202:205], v[172:175], v[72:75]
	v_mfma_f32_16x16x32_bf16 v[68:71], v[188:191], v[180:183], v[68:71]
	v_mfma_f32_16x16x32_bf16 v[64:67], v[202:205], v[180:183], v[64:67]
	v_mfma_f32_16x16x32_bf16 v[92:95], v[192:195], v[160:163], v[92:95]
	v_mfma_f32_16x16x32_bf16 v[88:91], v[206:209], v[160:163], v[88:91]
	v_mfma_f32_16x16x32_bf16 v[84:87], v[192:195], v[168:171], v[84:87]
	v_mfma_f32_16x16x32_bf16 v[80:83], v[206:209], v[168:171], v[80:83]
	v_mfma_f32_16x16x32_bf16 v[76:79], v[192:195], v[176:179], v[76:79]
	v_mfma_f32_16x16x32_bf16 v[72:75], v[206:209], v[176:179], v[72:75]
	v_mfma_f32_16x16x32_bf16 v[68:71], v[192:195], v[184:187], v[68:71]
	v_mfma_f32_16x16x32_bf16 v[64:67], v[206:209], v[184:187], v[64:67]
	v_mov_b32_e32 v210, v130
	s_barrier
	ds_read_b128 v[156:159], v134 offset:49152
	ds_read_b128 v[160:163], v134 offset:50176
	ds_read_b128 v[164:167], v133 offset:49152
	ds_read_b128 v[168:171], v133 offset:50176
	ds_read_b128 v[172:175], v132 offset:49152
	ds_read_b128 v[176:179], v132 offset:50176
	ds_read_b128 v[180:183], v131 offset:49152
	ds_read_b128 v[184:187], v131 offset:50176
	v_mov_b32_e32 v211, v197
	s_mov_b32 m0, s72
	s_add_u32 s98, s8, s96
	s_addc_u32 s99, s9, s97
	global_load_lds_dwordx4 v129, s[98:99]
	s_mov_b32 m0, s73
	s_nop 0
	global_load_lds_dwordx4 v130, s[98:99]
	s_barrier
	s_waitcnt lgkmcnt(0)
	s_waitcnt lgkmcnt(0)
	v_mfma_f32_16x16x32_bf16 v[60:63], v[140:143], v[156:159], v[60:63]
	v_mfma_f32_16x16x32_bf16 v[56:59], v[148:151], v[156:159], v[56:59]
	v_mfma_f32_16x16x32_bf16 v[52:55], v[140:143], v[164:167], v[52:55]
	v_mfma_f32_16x16x32_bf16 v[48:51], v[148:151], v[164:167], v[48:51]
	v_mfma_f32_16x16x32_bf16 v[44:47], v[140:143], v[172:175], v[44:47]
	v_mfma_f32_16x16x32_bf16 v[40:43], v[148:151], v[172:175], v[40:43]
	v_mfma_f32_16x16x32_bf16 v[36:39], v[140:143], v[180:183], v[36:39]
	v_mfma_f32_16x16x32_bf16 v[32:35], v[148:151], v[180:183], v[32:35]
	v_mfma_f32_16x16x32_bf16 v[60:63], v[144:147], v[160:163], v[60:63]
	v_mfma_f32_16x16x32_bf16 v[56:59], v[152:155], v[160:163], v[56:59]
	v_mfma_f32_16x16x32_bf16 v[52:55], v[144:147], v[168:171], v[52:55]
	v_mfma_f32_16x16x32_bf16 v[48:51], v[152:155], v[168:171], v[48:51]
	v_mfma_f32_16x16x32_bf16 v[44:47], v[144:147], v[176:179], v[44:47]
	v_mfma_f32_16x16x32_bf16 v[40:43], v[152:155], v[176:179], v[40:43]
	v_mfma_f32_16x16x32_bf16 v[36:39], v[144:147], v[184:187], v[36:39]
	v_mfma_f32_16x16x32_bf16 v[32:35], v[152:155], v[184:187], v[32:35]
	s_barrier
	v_mov_b32_e32 v196, v129
	s_mov_b32 m0, s33
	s_add_u32 s98, s10, vcc_lo
	s_addc_u32 s99, s11, vcc_hi
	global_load_lds_dwordx4 v129, s[98:99]
	s_mov_b32 m0, s74
	s_nop 0
	global_load_lds_dwordx4 v130, s[98:99]
	s_waitcnt vmcnt(6)
	s_barrier
	v_mfma_f32_16x16x32_bf16 v[28:31], v[188:191], v[156:159], v[28:31]
	v_mfma_f32_16x16x32_bf16 v[24:27], v[202:205], v[156:159], v[24:27]
	v_mfma_f32_16x16x32_bf16 v[20:23], v[188:191], v[164:167], v[20:23]
	v_mfma_f32_16x16x32_bf16 v[16:19], v[202:205], v[164:167], v[16:19]
	v_mfma_f32_16x16x32_bf16 v[12:15], v[188:191], v[172:175], v[12:15]
	v_mfma_f32_16x16x32_bf16 v[8:11], v[202:205], v[172:175], v[8:11]
	v_mfma_f32_16x16x32_bf16 v[4:7], v[188:191], v[180:183], v[4:7]
	v_mfma_f32_16x16x32_bf16 v[0:3], v[202:205], v[180:183], v[0:3]
	v_mfma_f32_16x16x32_bf16 v[28:31], v[192:195], v[160:163], v[28:31]
	v_mfma_f32_16x16x32_bf16 v[24:27], v[206:209], v[160:163], v[24:27]
	v_mfma_f32_16x16x32_bf16 v[20:23], v[192:195], v[168:171], v[20:23]
	v_mfma_f32_16x16x32_bf16 v[16:19], v[206:209], v[168:171], v[16:19]
	v_mfma_f32_16x16x32_bf16 v[12:15], v[192:195], v[176:179], v[12:15]
	v_mfma_f32_16x16x32_bf16 v[8:11], v[206:209], v[176:179], v[8:11]
	v_mfma_f32_16x16x32_bf16 v[4:7], v[192:195], v[184:187], v[4:7]
	v_mfma_f32_16x16x32_bf16 v[0:3], v[206:209], v[184:187], v[0:3]
	s_add_i32 s38, s38, 2
	s_add_u32 s6, s6, 0x100
	s_addc_u32 s7, s7, 0
	s_cmpk_lt_u32 s38, 0x54
	s_barrier
	s_cbranch_scc1 .LBB0_138
	s_add_u32 s4, s4, 0x2b80
	s_addc_u32 s5, s5, 0
	s_mov_b32 m0, s76
	ds_read_b128 v[140:143], v138
	ds_read_b128 v[144:147], v138 offset:1024
	ds_read_b128 v[148:151], v138 offset:2048
	ds_read_b128 v[152:155], v138 offset:3072
	ds_read_b128 v[156:159], v134
	ds_read_b128 v[160:163], v134 offset:1024
	ds_read_b128 v[164:167], v133
	ds_read_b128 v[168:171], v133 offset:1024
	ds_read_b128 v[172:175], v132
	ds_read_b128 v[176:179], v132 offset:1024
	ds_read_b128 v[180:183], v131
	ds_read_b128 v[184:187], v131 offset:1024
	s_nop 0
	global_load_lds_dwordx4 v129, s[4:5]
	s_mov_b32 m0, s75
	s_nop 0
	global_load_lds_dwordx4 v130, s[4:5]
	s_barrier
	s_waitcnt lgkmcnt(0)
	s_setprio 1
	s_waitcnt lgkmcnt(0)
	v_mfma_f32_16x16x32_bf16 v[124:127], v[140:143], v[156:159], v[124:127]
	v_mfma_f32_16x16x32_bf16 v[120:123], v[148:151], v[156:159], v[120:123]
	v_mfma_f32_16x16x32_bf16 v[116:119], v[140:143], v[164:167], v[116:119]
	v_mfma_f32_16x16x32_bf16 v[112:115], v[148:151], v[164:167], v[112:115]
	v_mfma_f32_16x16x32_bf16 v[108:111], v[140:143], v[172:175], v[108:111]
	v_mfma_f32_16x16x32_bf16 v[100:103], v[140:143], v[180:183], v[100:103]
	v_mfma_f32_16x16x32_bf16 v[96:99], v[148:151], v[180:183], v[96:99]
	v_mfma_f32_16x16x32_bf16 v[124:127], v[144:147], v[160:163], v[124:127]
	v_mfma_f32_16x16x32_bf16 v[120:123], v[152:155], v[160:163], v[120:123]
	v_mfma_f32_16x16x32_bf16 v[116:119], v[144:147], v[168:171], v[116:119]
	v_mfma_f32_16x16x32_bf16 v[112:115], v[152:155], v[168:171], v[112:115]
	v_mfma_f32_16x16x32_bf16 v[108:111], v[144:147], v[176:179], v[108:111]
	v_mfma_f32_16x16x32_bf16 v[104:107], v[148:151], v[172:175], v[104:107]
	v_mfma_f32_16x16x32_bf16 v[100:103], v[144:147], v[184:187], v[100:103]
	v_mfma_f32_16x16x32_bf16 v[96:99], v[152:155], v[184:187], v[96:99]
	v_mfma_f32_16x16x32_bf16 v[188:191], v[152:155], v[176:179], v[104:107]
	s_setprio 0
	s_barrier
	s_nop 2
	ds_read_b128 v[104:107], v137
	ds_read_b128 v[192:195], v137 offset:1024
	ds_read_b128 v[202:205], v137 offset:2048
	ds_read_b128 v[206:209], v137 offset:3072
	s_barrier
	s_waitcnt lgkmcnt(0)
	s_setprio 1
	s_waitcnt lgkmcnt(0)
	v_mfma_f32_16x16x32_bf16 v[92:95], v[104:107], v[156:159], v[92:95]
	v_mfma_f32_16x16x32_bf16 v[88:91], v[202:205], v[156:159], v[88:91]
	v_mfma_f32_16x16x32_bf16 v[80:83], v[202:205], v[164:167], v[80:83]
	v_mfma_f32_16x16x32_bf16 v[72:75], v[202:205], v[172:175], v[72:75]
	v_mfma_f32_16x16x32_bf16 v[64:67], v[202:205], v[180:183], v[64:67]
	v_mfma_f32_16x16x32_bf16 v[92:95], v[192:195], v[160:163], v[92:95]
	v_mfma_f32_16x16x32_bf16 v[88:91], v[206:209], v[160:163], v[88:91]
	v_mfma_f32_16x16x32_bf16 v[84:87], v[104:107], v[164:167], v[84:87]
	v_mfma_f32_16x16x32_bf16 v[80:83], v[206:209], v[168:171], v[80:83]
	v_mfma_f32_16x16x32_bf16 v[76:79], v[104:107], v[172:175], v[76:79]
	v_mfma_f32_16x16x32_bf16 v[72:75], v[206:209], v[176:179], v[72:75]
	v_mfma_f32_16x16x32_bf16 v[68:71], v[104:107], v[180:183], v[68:71]
	v_mfma_f32_16x16x32_bf16 v[64:67], v[206:209], v[184:187], v[64:67]
	v_mfma_f32_16x16x32_bf16 v[156:159], v[192:195], v[168:171], v[84:87]
	v_mfma_f32_16x16x32_bf16 v[160:163], v[192:195], v[176:179], v[76:79]
	v_mfma_f32_16x16x32_bf16 v[164:167], v[192:195], v[184:187], v[68:71]
	s_setprio 0
	s_barrier
	s_nop 1
	ds_read_b128 v[68:71], v134 offset:16384
	ds_read_b128 v[76:79], v134 offset:17408
	ds_read_b128 v[84:87], v133 offset:16384
	ds_read_b128 v[168:171], v133 offset:17408
	ds_read_b128 v[172:175], v132 offset:16384
	ds_read_b128 v[176:179], v132 offset:17408
	ds_read_b128 v[180:183], v131 offset:16384
	ds_read_b128 v[184:187], v131 offset:17408
	s_waitcnt vmcnt(4)
	s_barrier
	s_waitcnt lgkmcnt(0)
	s_setprio 1
	s_waitcnt lgkmcnt(0)
	v_mfma_f32_16x16x32_bf16 v[60:63], v[140:143], v[68:71], v[60:63]
	v_mfma_f32_16x16x32_bf16 v[56:59], v[148:151], v[68:71], v[56:59]
	v_mfma_f32_16x16x32_bf16 v[48:51], v[148:151], v[84:87], v[48:51]
	v_mfma_f32_16x16x32_bf16 v[32:35], v[148:151], v[180:183], v[32:35]
	v_mfma_f32_16x16x32_bf16 v[60:63], v[144:147], v[76:79], v[60:63]
	v_mfma_f32_16x16x32_bf16 v[56:59], v[152:155], v[76:79], v[56:59]
	v_mfma_f32_16x16x32_bf16 v[52:55], v[140:143], v[84:87], v[52:55]
	v_mfma_f32_16x16x32_bf16 v[48:51], v[152:155], v[168:171], v[48:51]
	v_mfma_f32_16x16x32_bf16 v[44:47], v[140:143], v[172:175], v[44:47]
	v_mfma_f32_16x16x32_bf16 v[40:43], v[148:151], v[172:175], v[40:43]
	v_mfma_f32_16x16x32_bf16 v[36:39], v[140:143], v[180:183], v[36:39]
	v_mfma_f32_16x16x32_bf16 v[32:35], v[152:155], v[184:187], v[32:35]
	v_mfma_f32_16x16x32_bf16 v[210:213], v[144:147], v[168:171], v[52:55]
	v_mfma_f32_16x16x32_bf16 v[214:217], v[144:147], v[176:179], v[44:47]
	v_mfma_f32_16x16x32_bf16 v[218:221], v[152:155], v[176:179], v[40:43]
	v_mfma_f32_16x16x32_bf16 v[138:141], v[144:147], v[184:187], v[36:39]
	s_setprio 0
	s_setprio 1
	v_mfma_f32_16x16x32_bf16 v[24:27], v[202:205], v[68:71], v[24:27]
	v_mfma_f32_16x16x32_bf16 v[20:23], v[104:107], v[84:87], v[20:23]
	v_mfma_f32_16x16x32_bf16 v[28:31], v[104:107], v[68:71], v[28:31]
	v_mfma_f32_16x16x32_bf16 v[24:27], v[206:209], v[76:79], v[24:27]
	v_mfma_f32_16x16x32_bf16 v[20:23], v[192:195], v[168:171], v[20:23]
	v_mfma_f32_16x16x32_bf16 v[16:19], v[202:205], v[84:87], v[16:19]
	v_mfma_f32_16x16x32_bf16 v[12:15], v[104:107], v[172:175], v[12:15]
	v_mfma_f32_16x16x32_bf16 v[8:11], v[202:205], v[172:175], v[8:11]
	v_mfma_f32_16x16x32_bf16 v[4:7], v[104:107], v[180:183], v[4:7]
	v_mfma_f32_16x16x32_bf16 v[0:3], v[202:205], v[180:183], v[0:3]
	v_mfma_f32_16x16x32_bf16 v[142:145], v[192:195], v[76:79], v[28:31]
	v_mfma_f32_16x16x32_bf16 v[146:149], v[206:209], v[168:171], v[16:19]
	v_mfma_f32_16x16x32_bf16 v[150:153], v[192:195], v[176:179], v[12:15]
	v_mfma_f32_16x16x32_bf16 v[168:171], v[206:209], v[176:179], v[8:11]
	v_mfma_f32_16x16x32_bf16 v[172:175], v[192:195], v[184:187], v[4:7]
	v_mfma_f32_16x16x32_bf16 v[176:179], v[206:209], v[184:187], v[0:3]
	s_setprio 0
	s_barrier
	ds_read_b128 v[16:19], v136
	ds_read_b128 v[180:183], v136 offset:1024
	ds_read_b128 v[184:187], v136 offset:2048
	ds_read_b128 v[192:195], v136 offset:3072
	ds_read_b128 v[0:3], v134 offset:32768
	ds_read_b128 v[4:7], v134 offset:33792
	ds_read_b128 v[8:11], v133 offset:32768
	ds_read_b128 v[12:15], v133 offset:33792
	ds_read_b128 v[44:47], v132 offset:32768
	ds_read_b128 v[202:205], v132 offset:33792
	ds_read_b128 v[206:209], v131 offset:32768
	ds_read_b128 v[222:225], v131 offset:33792
	s_waitcnt vmcnt(2)
	s_barrier
	s_waitcnt lgkmcnt(0)
	s_setprio 1
	s_waitcnt lgkmcnt(0)
	v_mfma_f32_16x16x32_bf16 v[28:31], v[16:19], v[0:3], v[124:127]
	v_mfma_f32_16x16x32_bf16 v[52:55], v[180:183], v[4:7], v[28:31]
	v_mfma_f32_16x16x32_bf16 v[28:31], v[184:187], v[0:3], v[120:123]
	v_mfma_f32_16x16x32_bf16 v[104:107], v[192:195], v[4:7], v[28:31]
	v_mfma_f32_16x16x32_bf16 v[28:31], v[16:19], v[8:11], v[116:119]
	v_mfma_f32_16x16x32_bf16 v[68:71], v[180:183], v[12:15], v[28:31]
	v_mfma_f32_16x16x32_bf16 v[28:31], v[184:187], v[8:11], v[112:115]
	v_mfma_f32_16x16x32_bf16 v[116:119], v[192:195], v[12:15], v[28:31]
	v_mfma_f32_16x16x32_bf16 v[28:31], v[16:19], v[44:47], v[108:111]
	v_mfma_f32_16x16x32_bf16 v[76:79], v[180:183], v[202:205], v[28:31]
	v_mfma_f32_16x16x32_bf16 v[28:31], v[184:187], v[44:47], v[188:191]
	v_mfma_f32_16x16x32_bf16 v[108:111], v[192:195], v[202:205], v[28:31]
	v_mfma_f32_16x16x32_bf16 v[28:31], v[16:19], v[206:209], v[100:103]
	v_mfma_f32_16x16x32_bf16 v[84:87], v[180:183], v[222:225], v[28:31]
	v_mfma_f32_16x16x32_bf16 v[28:31], v[184:187], v[206:209], v[96:99]
	v_mfma_f32_16x16x32_bf16 v[96:99], v[192:195], v[222:225], v[28:31]
	s_setprio 0
	s_barrier
	ds_read_b128 v[188:191], v135
	ds_read_b128 v[228:231], v135 offset:1024
	ds_read_b128 v[232:235], v135 offset:2048
	ds_read_b128 v[236:239], v135 offset:3072
	s_waitcnt vmcnt(0)
	s_barrier
	s_waitcnt lgkmcnt(0)
	s_setprio 1
	s_waitcnt lgkmcnt(0)
	v_mfma_f32_16x16x32_bf16 v[28:31], v[188:191], v[0:3], v[92:95]
	v_mfma_f32_16x16x32_bf16 v[0:3], v[232:235], v[0:3], v[88:91]
	v_mfma_f32_16x16x32_bf16 v[28:31], v[228:231], v[4:7], v[28:31]
	v_mfma_f32_16x16x32_bf16 v[0:3], v[236:239], v[4:7], v[0:3]
	v_mfma_f32_16x16x32_bf16 v[4:7], v[188:191], v[8:11], v[156:159]
	v_mfma_f32_16x16x32_bf16 v[36:39], v[228:231], v[12:15], v[4:7]
	v_mfma_f32_16x16x32_bf16 v[4:7], v[232:235], v[8:11], v[80:83]
	v_mfma_f32_16x16x32_bf16 v[4:7], v[236:239], v[12:15], v[4:7]
	v_mfma_f32_16x16x32_bf16 v[8:11], v[188:191], v[44:47], v[160:163]
	v_mfma_f32_16x16x32_bf16 v[12:15], v[188:191], v[206:209], v[164:167]
	v_mfma_f32_16x16x32_bf16 v[40:43], v[228:231], v[202:205], v[8:11]
	v_mfma_f32_16x16x32_bf16 v[8:11], v[232:235], v[44:47], v[72:75]
	v_mfma_f32_16x16x32_bf16 v[44:47], v[228:231], v[222:225], v[12:15]
	v_mfma_f32_16x16x32_bf16 v[12:15], v[232:235], v[206:209], v[64:67]
	v_mfma_f32_16x16x32_bf16 v[8:11], v[236:239], v[202:205], v[8:11]
	v_mfma_f32_16x16x32_bf16 v[12:15], v[236:239], v[222:225], v[12:15]
	s_setprio 0
	s_barrier
	ds_read_b128 v[64:67], v134 offset:49152
	ds_read_b128 v[134:137], v134 offset:50176
	ds_read_b128 v[154:157], v133 offset:49152
	ds_read_b128 v[158:161], v133 offset:50176
	ds_read_b128 v[162:165], v132 offset:49152
	ds_read_b128 v[202:205], v132 offset:50176
	ds_read_b128 v[206:209], v131 offset:49152
	ds_read_b128 v[130:133], v131 offset:50176
	s_barrier
	s_waitcnt lgkmcnt(0)
	s_setprio 1
	s_waitcnt lgkmcnt(0)
	v_mfma_f32_16x16x32_bf16 v[56:59], v[184:187], v[64:67], v[56:59]
	v_mfma_f32_16x16x32_bf16 v[48:51], v[184:187], v[154:157], v[48:51]
	v_mfma_f32_16x16x32_bf16 v[60:63], v[16:19], v[64:67], v[60:63]
	v_mfma_f32_16x16x32_bf16 v[92:95], v[192:195], v[134:137], v[56:59]
	v_mfma_f32_16x16x32_bf16 v[56:59], v[16:19], v[154:157], v[210:213]
	v_mfma_f32_16x16x32_bf16 v[88:91], v[192:195], v[158:161], v[48:51]
	v_mfma_f32_16x16x32_bf16 v[48:51], v[16:19], v[162:165], v[214:217]
	v_mfma_f32_16x16x32_bf16 v[16:19], v[16:19], v[206:209], v[138:141]
	v_mfma_f32_16x16x32_bf16 v[120:123], v[180:183], v[202:205], v[48:51]
	v_mfma_f32_16x16x32_bf16 v[48:51], v[184:187], v[162:165], v[218:221]
	v_mfma_f32_16x16x32_bf16 v[124:127], v[180:183], v[130:133], v[16:19]
	v_mfma_f32_16x16x32_bf16 v[16:19], v[184:187], v[206:209], v[32:35]
	v_mfma_f32_16x16x32_bf16 v[100:103], v[180:183], v[134:137], v[60:63]
	v_mfma_f32_16x16x32_bf16 v[112:115], v[180:183], v[158:161], v[56:59]
	v_mfma_f32_16x16x32_bf16 v[80:83], v[192:195], v[202:205], v[48:51]
	v_mfma_f32_16x16x32_bf16 v[72:75], v[192:195], v[130:133], v[16:19]
	s_setprio 0
	s_setprio 1
	v_mfma_f32_16x16x32_bf16 v[16:19], v[188:191], v[64:67], v[142:145]
	v_mfma_f32_16x16x32_bf16 v[48:51], v[228:231], v[134:137], v[16:19]
	v_mfma_f32_16x16x32_bf16 v[16:19], v[232:235], v[64:67], v[24:27]
	v_mfma_f32_16x16x32_bf16 v[20:23], v[188:191], v[154:157], v[20:23]
	v_mfma_f32_16x16x32_bf16 v[24:27], v[188:191], v[162:165], v[150:153]
	v_mfma_f32_16x16x32_bf16 v[32:35], v[188:191], v[206:209], v[172:175]
	v_mfma_f32_16x16x32_bf16 v[56:59], v[228:231], v[158:161], v[20:23]
	v_mfma_f32_16x16x32_bf16 v[20:23], v[232:235], v[154:157], v[146:149]
	v_mfma_f32_16x16x32_bf16 v[60:63], v[228:231], v[202:205], v[24:27]
	v_mfma_f32_16x16x32_bf16 v[24:27], v[232:235], v[162:165], v[168:171]
	v_mfma_f32_16x16x32_bf16 v[64:67], v[228:231], v[130:133], v[32:35]
	v_mfma_f32_16x16x32_bf16 v[32:35], v[232:235], v[206:209], v[176:179]
	v_mfma_f32_16x16x32_bf16 v[16:19], v[236:239], v[134:137], v[16:19]
	v_mfma_f32_16x16x32_bf16 v[20:23], v[236:239], v[158:161], v[20:23]
	v_mfma_f32_16x16x32_bf16 v[24:27], v[236:239], v[202:205], v[24:27]
	v_mfma_f32_16x16x32_bf16 v[32:35], v[236:239], v[130:133], v[32:35]
	s_setprio 0
	s_movk_i32 s4, 0x100
	v_cmp_gt_u32_e32 vcc, s4, v128
	s_barrier
	s_and_saveexec_b64 s[4:5], vcc
	s_cbranch_execz .LBB0_95
	s_barrier
	s_branch .LBB0_95

.Lhf_192:
	ds_read_b128 v[140:143], v129
	ds_read_b128 v[144:147], v129 offset:1024
	ds_read_b128 v[148:151], v129 offset:2048
	ds_read_b128 v[152:155], v129 offset:3072
	s_add_u32 s28, s56, s4
	s_addc_u32 s29, s57, s5
	ds_read_b128 v[156:159], v136
	ds_read_b128 v[160:163], v136 offset:1024
	ds_read_b128 v[164:167], v135
	ds_read_b128 v[168:171], v135 offset:1024
	ds_read_b128 v[172:175], v134
	ds_read_b128 v[176:179], v134 offset:1024
	ds_read_b128 v[180:183], v133
	ds_read_b128 v[184:187], v133 offset:1024
	s_add_i32 s40, s52, 0xc000
	s_mov_b32 m0, s40
	s_add_i32 s39, s52, 0xe000
	s_mov_b32 m0, s39
	s_nop 0
	s_waitcnt lgkmcnt(8)
	s_barrier
	s_waitcnt lgkmcnt(0)
	s_waitcnt lgkmcnt(0)
	v_mfma_f32_16x16x32_bf16 v[124:127], v[140:143], v[156:159], v[124:127]
	v_mfma_f32_16x16x32_bf16 v[120:123], v[148:151], v[156:159], v[120:123]
	v_mfma_f32_16x16x32_bf16 v[116:119], v[140:143], v[164:167], v[116:119]
	v_mfma_f32_16x16x32_bf16 v[112:115], v[148:151], v[164:167], v[112:115]
	v_mfma_f32_16x16x32_bf16 v[108:111], v[140:143], v[172:175], v[108:111]
	v_mfma_f32_16x16x32_bf16 v[104:107], v[148:151], v[172:175], v[104:107]
	v_mfma_f32_16x16x32_bf16 v[100:103], v[140:143], v[180:183], v[100:103]
	v_mfma_f32_16x16x32_bf16 v[96:99], v[148:151], v[180:183], v[96:99]
	v_mfma_f32_16x16x32_bf16 v[124:127], v[144:147], v[160:163], v[124:127]
	v_mfma_f32_16x16x32_bf16 v[120:123], v[152:155], v[160:163], v[120:123]
	v_mfma_f32_16x16x32_bf16 v[116:119], v[144:147], v[168:171], v[116:119]
	v_mfma_f32_16x16x32_bf16 v[112:115], v[152:155], v[168:171], v[112:115]
	v_mfma_f32_16x16x32_bf16 v[108:111], v[144:147], v[176:179], v[108:111]
	v_mfma_f32_16x16x32_bf16 v[104:107], v[152:155], v[176:179], v[104:107]
	v_mfma_f32_16x16x32_bf16 v[100:103], v[144:147], v[184:187], v[100:103]
	v_mfma_f32_16x16x32_bf16 v[96:99], v[152:155], v[184:187], v[96:99]
	s_barrier
	s_add_u32 s58, s56, s36
	s_addc_u32 s59, s57, s37
	ds_read_b128 v[188:191], v139
	ds_read_b128 v[192:195], v139 offset:1024
	ds_read_b128 v[202:205], v139 offset:2048
	ds_read_b128 v[206:209], v139 offset:3072
	s_add_i32 m0, s52, 0x10000
	s_add_u32 s98, s58, s46
	s_addc_u32 s99, s59, s47
	global_load_lds_dwordx4 v128, s[98:99]
	s_add_i32 m0, s52, 0x12000
	s_nop 0
	global_load_lds_dwordx4 v130, s[98:99]
	s_barrier
	s_waitcnt lgkmcnt(0)
	s_waitcnt lgkmcnt(0)
	v_mfma_f32_16x16x32_bf16 v[92:95], v[188:191], v[156:159], v[92:95]
	v_mfma_f32_16x16x32_bf16 v[88:91], v[202:205], v[156:159], v[88:91]
	v_mfma_f32_16x16x32_bf16 v[84:87], v[188:191], v[164:167], v[84:87]
	v_mfma_f32_16x16x32_bf16 v[80:83], v[202:205], v[164:167], v[80:83]
	v_mfma_f32_16x16x32_bf16 v[76:79], v[188:191], v[172:175], v[76:79]
	v_mfma_f32_16x16x32_bf16 v[72:75], v[202:205], v[172:175], v[72:75]
	v_mfma_f32_16x16x32_bf16 v[68:71], v[188:191], v[180:183], v[68:71]
	v_mfma_f32_16x16x32_bf16 v[64:67], v[202:205], v[180:183], v[64:67]
	v_mfma_f32_16x16x32_bf16 v[92:95], v[192:195], v[160:163], v[92:95]
	v_mfma_f32_16x16x32_bf16 v[88:91], v[206:209], v[160:163], v[88:91]
	v_mfma_f32_16x16x32_bf16 v[84:87], v[192:195], v[168:171], v[84:87]
	v_mfma_f32_16x16x32_bf16 v[80:83], v[206:209], v[168:171], v[80:83]
	v_mfma_f32_16x16x32_bf16 v[76:79], v[192:195], v[176:179], v[76:79]
	v_mfma_f32_16x16x32_bf16 v[72:75], v[206:209], v[176:179], v[72:75]
	v_mfma_f32_16x16x32_bf16 v[68:71], v[192:195], v[184:187], v[68:71]
	v_mfma_f32_16x16x32_bf16 v[64:67], v[206:209], v[184:187], v[64:67]
	s_barrier
	s_mov_b32 m0, s52
	s_add_u32 s98, s28, s48
	s_addc_u32 s99, s29, s49
	global_load_lds_dwordx4 v128, s[98:99]
	s_add_i32 m0, s52, 0x2000
	s_nop 0
	global_load_lds_dwordx4 v130, s[98:99]
	s_waitcnt vmcnt(4)
	s_barrier
	s_add_i32 m0, s52, 0x14000
	s_add_u32 s98, s58, s50
	s_addc_u32 s99, s59, s51
	global_load_lds_dwordx4 v128, s[98:99]
	s_add_i32 m0, s52, 0x16000
	s_nop 0
	global_load_lds_dwordx4 v130, s[98:99]
	s_barrier
	ds_read_b128 v[140:143], v138
	ds_read_b128 v[144:147], v138 offset:1024
	ds_read_b128 v[148:151], v138 offset:2048
	ds_read_b128 v[152:155], v138 offset:3072
	ds_read_b128 v[156:159], v136 offset:32768
	ds_read_b128 v[160:163], v136 offset:33792
	ds_read_b128 v[164:167], v135 offset:32768
	ds_read_b128 v[168:171], v135 offset:33792
	ds_read_b128 v[172:175], v134 offset:32768
	ds_read_b128 v[176:179], v134 offset:33792
	ds_read_b128 v[180:183], v133 offset:32768
	ds_read_b128 v[184:187], v133 offset:33792
	s_add_i32 m0, s52, 0x4000
	s_add_i32 m0, s52, 0x6000
	s_nop 0
	s_waitcnt lgkmcnt(8)
	s_barrier
	s_waitcnt lgkmcnt(0)
	s_waitcnt lgkmcnt(0)
	v_mfma_f32_16x16x32_bf16 v[124:127], v[140:143], v[156:159], v[124:127]
	v_mfma_f32_16x16x32_bf16 v[120:123], v[148:151], v[156:159], v[120:123]
	v_mfma_f32_16x16x32_bf16 v[116:119], v[140:143], v[164:167], v[116:119]
	v_mfma_f32_16x16x32_bf16 v[112:115], v[148:151], v[164:167], v[112:115]
	v_mfma_f32_16x16x32_bf16 v[108:111], v[140:143], v[172:175], v[108:111]
	v_mfma_f32_16x16x32_bf16 v[104:107], v[148:151], v[172:175], v[104:107]
	v_mfma_f32_16x16x32_bf16 v[100:103], v[140:143], v[180:183], v[100:103]
	v_mfma_f32_16x16x32_bf16 v[96:99], v[148:151], v[180:183], v[96:99]
	v_mfma_f32_16x16x32_bf16 v[124:127], v[144:147], v[160:163], v[124:127]
	v_mfma_f32_16x16x32_bf16 v[120:123], v[152:155], v[160:163], v[120:123]
	v_mfma_f32_16x16x32_bf16 v[116:119], v[144:147], v[168:171], v[116:119]
	v_mfma_f32_16x16x32_bf16 v[112:115], v[152:155], v[168:171], v[112:115]
	v_mfma_f32_16x16x32_bf16 v[108:111], v[144:147], v[176:179], v[108:111]
	v_mfma_f32_16x16x32_bf16 v[104:107], v[152:155], v[176:179], v[104:107]
	v_mfma_f32_16x16x32_bf16 v[100:103], v[144:147], v[184:187], v[100:103]
	v_mfma_f32_16x16x32_bf16 v[96:99], v[152:155], v[184:187], v[96:99]
	s_barrier
	ds_read_b128 v[188:191], v137
	ds_read_b128 v[192:195], v137 offset:1024
	ds_read_b128 v[202:205], v137 offset:2048
	ds_read_b128 v[206:209], v137 offset:3072
	s_mov_b32 m0, s7
	s_add_u32 s98, s58, s68
	s_addc_u32 s99, s59, s69
	global_load_lds_dwordx4 v128, s[98:99]
	s_mov_b32 m0, s53
	s_nop 0
	global_load_lds_dwordx4 v130, s[98:99]
	s_barrier
	s_waitcnt lgkmcnt(0)
	s_waitcnt lgkmcnt(0)
	v_mfma_f32_16x16x32_bf16 v[92:95], v[188:191], v[156:159], v[92:95]
	v_mfma_f32_16x16x32_bf16 v[88:91], v[202:205], v[156:159], v[88:91]
	v_mfma_f32_16x16x32_bf16 v[84:87], v[188:191], v[164:167], v[84:87]
	v_mfma_f32_16x16x32_bf16 v[80:83], v[202:205], v[164:167], v[80:83]
	v_mfma_f32_16x16x32_bf16 v[76:79], v[188:191], v[172:175], v[76:79]
	v_mfma_f32_16x16x32_bf16 v[72:75], v[202:205], v[172:175], v[72:75]
	v_mfma_f32_16x16x32_bf16 v[68:71], v[188:191], v[180:183], v[68:71]
	v_mfma_f32_16x16x32_bf16 v[64:67], v[202:205], v[180:183], v[64:67]
	v_mfma_f32_16x16x32_bf16 v[92:95], v[192:195], v[160:163], v[92:95]
	v_mfma_f32_16x16x32_bf16 v[88:91], v[206:209], v[160:163], v[88:91]
	v_mfma_f32_16x16x32_bf16 v[84:87], v[192:195], v[168:171], v[84:87]
	v_mfma_f32_16x16x32_bf16 v[80:83], v[206:209], v[168:171], v[80:83]
	v_mfma_f32_16x16x32_bf16 v[76:79], v[192:195], v[176:179], v[76:79]
	v_mfma_f32_16x16x32_bf16 v[72:75], v[206:209], v[176:179], v[72:75]
	v_mfma_f32_16x16x32_bf16 v[68:71], v[192:195], v[184:187], v[68:71]
	v_mfma_f32_16x16x32_bf16 v[64:67], v[206:209], v[184:187], v[64:67]
	v_mov_b32_e32 v210, v130
	s_barrier
	v_mov_b32_e32 v211, v197
	s_mov_b32 m0, s9
	s_add_u32 s98, s28, s70
	s_addc_u32 s99, s29, s71
	global_load_lds_dwordx4 v128, s[98:99]
	s_mov_b32 m0, s33
	s_nop 0
	global_load_lds_dwordx4 v130, s[98:99]
	s_waitcnt vmcnt(4)
	s_barrier
	v_mov_b32_e32 v196, v128
	s_mov_b32 m0, s65
	s_add_u32 s98, s58, s72
	s_addc_u32 s99, s59, s73
	global_load_lds_dwordx4 v128, s[98:99]
	s_mov_b32 m0, s66
	s_nop 0
	global_load_lds_dwordx4 v130, s[98:99]
	s_barrier
	s_add_i32 s38, s38, 2
	s_add_u32 s56, s56, 0x100
	s_addc_u32 s57, s57, 0
	s_cmp_lt_u32 s38, 28
	s_cbranch_scc1 .Lhf_192
	s_lshl_b64 s[4:5], s[10:11], 12
	v_readlane_b32 s10, v254, 12
	v_readlane_b32 s11, v254, 13
	s_add_u32 s4, s10, s4
	s_addc_u32 s5, s11, s5
	ds_read_b128 v[140:143], v129
	ds_read_b128 v[144:147], v129 offset:1024
	ds_read_b128 v[148:151], v129 offset:2048
	ds_read_b128 v[152:155], v129 offset:3072
	ds_read_b128 v[156:159], v136
	ds_read_b128 v[160:163], v136 offset:1024
	ds_read_b128 v[164:167], v135
	ds_read_b128 v[168:171], v135 offset:1024
	ds_read_b128 v[172:175], v134
	ds_read_b128 v[176:179], v134 offset:1024
	ds_read_b128 v[180:183], v133
	ds_read_b128 v[184:187], v133 offset:1024
	v_mov_b32_e32 v129, v197
	v_lshl_add_u64 v[128:129], s[4:5], 0, v[128:129]
	s_mov_b64 s[10:11], 0xf80
	s_mov_b32 m0, s40
	v_lshl_add_u64 v[128:129], v[128:129], 0, s[10:11]
	v_mov_b32_e32 v131, v197
	v_lshl_add_u64 v[128:129], s[4:5], 0, v[130:131]
	v_lshl_add_u64 v[128:129], v[128:129], 0, s[10:11]
	s_mov_b32 m0, s39
	s_nop 0
	s_barrier
	s_waitcnt lgkmcnt(0)
	s_setprio 1
	s_waitcnt lgkmcnt(0)
	v_mfma_f32_16x16x32_bf16 v[124:127], v[140:143], v[156:159], v[124:127]
	v_mfma_f32_16x16x32_bf16 v[116:119], v[140:143], v[164:167], v[116:119]
	v_mfma_f32_16x16x32_bf16 v[112:115], v[148:151], v[164:167], v[112:115]
	v_mfma_f32_16x16x32_bf16 v[108:111], v[140:143], v[172:175], v[108:111]
	v_mfma_f32_16x16x32_bf16 v[104:107], v[148:151], v[172:175], v[104:107]
	v_mfma_f32_16x16x32_bf16 v[100:103], v[140:143], v[180:183], v[100:103]
	v_mfma_f32_16x16x32_bf16 v[96:99], v[148:151], v[180:183], v[96:99]
	v_mfma_f32_16x16x32_bf16 v[124:127], v[144:147], v[160:163], v[124:127]
	v_mfma_f32_16x16x32_bf16 v[120:123], v[148:151], v[156:159], v[120:123]
	v_mfma_f32_16x16x32_bf16 v[116:119], v[144:147], v[168:171], v[116:119]
	v_mfma_f32_16x16x32_bf16 v[112:115], v[152:155], v[168:171], v[112:115]
	v_mfma_f32_16x16x32_bf16 v[108:111], v[144:147], v[176:179], v[108:111]
	v_mfma_f32_16x16x32_bf16 v[104:107], v[152:155], v[176:179], v[104:107]
	v_mfma_f32_16x16x32_bf16 v[100:103], v[144:147], v[184:187], v[100:103]
	v_mfma_f32_16x16x32_bf16 v[96:99], v[152:155], v[184:187], v[96:99]
	v_mfma_f32_16x16x32_bf16 v[128:131], v[152:155], v[160:163], v[120:123]
	s_setprio 0
	s_barrier
	s_nop 0
	ds_read_b128 v[120:123], v139
	ds_read_b128 v[188:191], v139 offset:1024
	ds_read_b128 v[192:195], v139 offset:2048
	ds_read_b128 v[202:205], v139 offset:3072
	s_barrier
	s_waitcnt lgkmcnt(0)
	s_setprio 1
	s_waitcnt lgkmcnt(0)
	v_mfma_f32_16x16x32_bf16 v[76:79], v[120:123], v[172:175], v[76:79]
	v_mfma_f32_16x16x32_bf16 v[68:71], v[120:123], v[180:183], v[68:71]
	v_mfma_f32_16x16x32_bf16 v[64:67], v[192:195], v[180:183], v[64:67]
	v_mfma_f32_16x16x32_bf16 v[92:95], v[120:123], v[156:159], v[92:95]
	v_mfma_f32_16x16x32_bf16 v[88:91], v[192:195], v[156:159], v[88:91]
	v_mfma_f32_16x16x32_bf16 v[84:87], v[120:123], v[164:167], v[84:87]
	v_mfma_f32_16x16x32_bf16 v[80:83], v[192:195], v[164:167], v[80:83]
	v_mfma_f32_16x16x32_bf16 v[76:79], v[188:191], v[176:179], v[76:79]
	v_mfma_f32_16x16x32_bf16 v[72:75], v[192:195], v[172:175], v[72:75]
	v_mfma_f32_16x16x32_bf16 v[68:71], v[188:191], v[184:187], v[68:71]
	v_mfma_f32_16x16x32_bf16 v[64:67], v[202:205], v[184:187], v[64:67]
	v_mfma_f32_16x16x32_bf16 v[206:209], v[188:191], v[160:163], v[92:95]
	v_mfma_f32_16x16x32_bf16 v[156:159], v[202:205], v[160:163], v[88:91]
	v_mfma_f32_16x16x32_bf16 v[160:163], v[188:191], v[168:171], v[84:87]
	v_mfma_f32_16x16x32_bf16 v[164:167], v[202:205], v[168:171], v[80:83]
	v_mfma_f32_16x16x32_bf16 v[168:171], v[202:205], v[176:179], v[72:75]
	s_setprio 0
	s_barrier
	s_nop 0
	s_waitcnt vmcnt(2)
	s_barrier
	s_waitcnt lgkmcnt(0)
	s_setprio 1
	s_waitcnt lgkmcnt(0)
	s_setprio 0
	s_setprio 1
	s_setprio 0
	s_barrier
	s_nop 0
	ds_read_b128 v[8:11], v138
	ds_read_b128 v[16:19], v138 offset:1024
	ds_read_b128 v[176:179], v138 offset:2048
	ds_read_b128 v[180:183], v138 offset:3072
	ds_read_b128 v[20:23], v136 offset:32768
	ds_read_b128 v[24:27], v136 offset:33792
	ds_read_b128 v[28:31], v135 offset:32768
	ds_read_b128 v[56:59], v135 offset:33792
	ds_read_b128 v[188:191], v134 offset:32768
	ds_read_b128 v[192:195], v134 offset:33792
	ds_read_b128 v[202:205], v133 offset:32768
	ds_read_b128 v[210:213], v133 offset:33792
	s_waitcnt vmcnt(0)
	s_barrier
	s_waitcnt lgkmcnt(0)
	s_setprio 1
	s_waitcnt lgkmcnt(0)
	v_mfma_f32_16x16x32_bf16 v[72:75], v[8:11], v[20:23], v[124:127]
	v_mfma_f32_16x16x32_bf16 v[120:123], v[16:19], v[24:27], v[72:75]
	v_mfma_f32_16x16x32_bf16 v[72:75], v[176:179], v[20:23], v[128:131]
	v_mfma_f32_16x16x32_bf16 v[124:127], v[180:183], v[24:27], v[72:75]
	v_mfma_f32_16x16x32_bf16 v[72:75], v[8:11], v[28:31], v[116:119]
	v_mfma_f32_16x16x32_bf16 v[116:119], v[16:19], v[56:59], v[72:75]
	v_mfma_f32_16x16x32_bf16 v[72:75], v[176:179], v[28:31], v[112:115]
	v_mfma_f32_16x16x32_bf16 v[112:115], v[180:183], v[56:59], v[72:75]
	v_mfma_f32_16x16x32_bf16 v[72:75], v[8:11], v[188:191], v[108:111]
	v_mfma_f32_16x16x32_bf16 v[88:91], v[16:19], v[192:195], v[72:75]
	v_mfma_f32_16x16x32_bf16 v[72:75], v[176:179], v[188:191], v[104:107]
	v_mfma_f32_16x16x32_bf16 v[92:95], v[180:183], v[192:195], v[72:75]
	v_mfma_f32_16x16x32_bf16 v[72:75], v[8:11], v[202:205], v[100:103]
	v_mfma_f32_16x16x32_bf16 v[84:87], v[16:19], v[210:213], v[72:75]
	v_mfma_f32_16x16x32_bf16 v[72:75], v[176:179], v[202:205], v[96:99]
	v_mfma_f32_16x16x32_bf16 v[80:83], v[180:183], v[210:213], v[72:75]
	s_setprio 0
	s_barrier
	ds_read_b128 v[128:131], v137
	ds_read_b128 v[214:217], v137 offset:1024
	ds_read_b128 v[218:221], v137 offset:2048
	ds_read_b128 v[222:225], v137 offset:3072
	s_waitcnt vmcnt(0)
	s_barrier
	s_waitcnt lgkmcnt(0)
	s_setprio 1
	s_waitcnt lgkmcnt(0)
	v_mfma_f32_16x16x32_bf16 v[72:75], v[128:131], v[20:23], v[206:209]
	v_mfma_f32_16x16x32_bf16 v[20:23], v[218:221], v[20:23], v[156:159]
	v_mfma_f32_16x16x32_bf16 v[108:111], v[222:225], v[24:27], v[20:23]
	v_mfma_f32_16x16x32_bf16 v[20:23], v[128:131], v[28:31], v[160:163]
	v_mfma_f32_16x16x32_bf16 v[100:103], v[214:217], v[56:59], v[20:23]
	v_mfma_f32_16x16x32_bf16 v[20:23], v[218:221], v[28:31], v[164:167]
	v_mfma_f32_16x16x32_bf16 v[96:99], v[222:225], v[56:59], v[20:23]
	v_mfma_f32_16x16x32_bf16 v[20:23], v[128:131], v[188:191], v[76:79]
	v_mfma_f32_16x16x32_bf16 v[104:107], v[214:217], v[24:27], v[72:75]
	v_mfma_f32_16x16x32_bf16 v[72:75], v[214:217], v[192:195], v[20:23]
	v_mfma_f32_16x16x32_bf16 v[20:23], v[218:221], v[188:191], v[168:171]
	v_mfma_f32_16x16x32_bf16 v[76:79], v[222:225], v[192:195], v[20:23]
	v_mfma_f32_16x16x32_bf16 v[20:23], v[128:131], v[202:205], v[68:71]
	v_mfma_f32_16x16x32_bf16 v[68:71], v[214:217], v[210:213], v[20:23]
	v_mfma_f32_16x16x32_bf16 v[20:23], v[218:221], v[202:205], v[64:67]
	v_mfma_f32_16x16x32_bf16 v[64:67], v[222:225], v[210:213], v[20:23]
	s_setprio 0
	s_barrier
	s_barrier
	s_waitcnt lgkmcnt(0)
	s_setprio 1
	s_waitcnt lgkmcnt(0)
	s_setprio 0
	s_setprio 1
	s_setprio 0
	s_movk_i32 s4, 0x100
	v_cmp_gt_u32_e32 vcc, s4, v132
	s_barrier
	s_and_saveexec_b64 s[4:5], vcc
	s_cbranch_execz .Lhf_195
	s_barrier

.LBB0_192:
	ds_read_b128 v[140:143], v129
	ds_read_b128 v[144:147], v129 offset:1024
	ds_read_b128 v[148:151], v129 offset:2048
	ds_read_b128 v[152:155], v129 offset:3072
	s_add_u32 s28, s56, s4
	s_addc_u32 s29, s57, s5
	ds_read_b128 v[156:159], v136
	ds_read_b128 v[160:163], v136 offset:1024
	ds_read_b128 v[164:167], v135
	ds_read_b128 v[168:171], v135 offset:1024
	ds_read_b128 v[172:175], v134
	ds_read_b128 v[176:179], v134 offset:1024
	ds_read_b128 v[180:183], v133
	ds_read_b128 v[184:187], v133 offset:1024
	s_add_i32 s40, s52, 0xc000
	s_mov_b32 m0, s40
	s_add_i32 s39, s52, 0xe000
	s_add_u32 s98, s28, s44
	s_addc_u32 s99, s29, s45
	global_load_lds_dwordx4 v128, s[98:99]
	s_mov_b32 m0, s39
	s_nop 0
	global_load_lds_dwordx4 v130, s[98:99]
	s_waitcnt lgkmcnt(8)
	s_barrier
	s_waitcnt lgkmcnt(0)
	s_waitcnt lgkmcnt(0)
	v_mfma_f32_16x16x32_bf16 v[124:127], v[140:143], v[156:159], v[124:127]
	v_mfma_f32_16x16x32_bf16 v[120:123], v[148:151], v[156:159], v[120:123]
	v_mfma_f32_16x16x32_bf16 v[116:119], v[140:143], v[164:167], v[116:119]
	v_mfma_f32_16x16x32_bf16 v[112:115], v[148:151], v[164:167], v[112:115]
	v_mfma_f32_16x16x32_bf16 v[108:111], v[140:143], v[172:175], v[108:111]
	v_mfma_f32_16x16x32_bf16 v[104:107], v[148:151], v[172:175], v[104:107]
	v_mfma_f32_16x16x32_bf16 v[100:103], v[140:143], v[180:183], v[100:103]
	v_mfma_f32_16x16x32_bf16 v[96:99], v[148:151], v[180:183], v[96:99]
	v_mfma_f32_16x16x32_bf16 v[124:127], v[144:147], v[160:163], v[124:127]
	v_mfma_f32_16x16x32_bf16 v[120:123], v[152:155], v[160:163], v[120:123]
	v_mfma_f32_16x16x32_bf16 v[116:119], v[144:147], v[168:171], v[116:119]
	v_mfma_f32_16x16x32_bf16 v[112:115], v[152:155], v[168:171], v[112:115]
	v_mfma_f32_16x16x32_bf16 v[108:111], v[144:147], v[176:179], v[108:111]
	v_mfma_f32_16x16x32_bf16 v[104:107], v[152:155], v[176:179], v[104:107]
	v_mfma_f32_16x16x32_bf16 v[100:103], v[144:147], v[184:187], v[100:103]
	v_mfma_f32_16x16x32_bf16 v[96:99], v[152:155], v[184:187], v[96:99]
	s_barrier
	s_add_u32 s58, s56, s36
	s_addc_u32 s59, s57, s37
	ds_read_b128 v[188:191], v139
	ds_read_b128 v[192:195], v139 offset:1024
	ds_read_b128 v[202:205], v139 offset:2048
	ds_read_b128 v[206:209], v139 offset:3072
	s_add_i32 m0, s52, 0x10000
	s_add_u32 s98, s58, s46
	s_addc_u32 s99, s59, s47
	global_load_lds_dwordx4 v128, s[98:99]
	s_add_i32 m0, s52, 0x12000
	s_nop 0
	global_load_lds_dwordx4 v130, s[98:99]
	s_barrier
	s_waitcnt lgkmcnt(0)
	s_waitcnt lgkmcnt(0)
	v_mfma_f32_16x16x32_bf16 v[92:95], v[188:191], v[156:159], v[92:95]
	v_mfma_f32_16x16x32_bf16 v[88:91], v[202:205], v[156:159], v[88:91]
	v_mfma_f32_16x16x32_bf16 v[84:87], v[188:191], v[164:167], v[84:87]
	v_mfma_f32_16x16x32_bf16 v[80:83], v[202:205], v[164:167], v[80:83]
	v_mfma_f32_16x16x32_bf16 v[76:79], v[188:191], v[172:175], v[76:79]
	v_mfma_f32_16x16x32_bf16 v[72:75], v[202:205], v[172:175], v[72:75]
	v_mfma_f32_16x16x32_bf16 v[68:71], v[188:191], v[180:183], v[68:71]
	v_mfma_f32_16x16x32_bf16 v[64:67], v[202:205], v[180:183], v[64:67]
	v_mfma_f32_16x16x32_bf16 v[92:95], v[192:195], v[160:163], v[92:95]
	v_mfma_f32_16x16x32_bf16 v[88:91], v[206:209], v[160:163], v[88:91]
	v_mfma_f32_16x16x32_bf16 v[84:87], v[192:195], v[168:171], v[84:87]
	v_mfma_f32_16x16x32_bf16 v[80:83], v[206:209], v[168:171], v[80:83]
	v_mfma_f32_16x16x32_bf16 v[76:79], v[192:195], v[176:179], v[76:79]
	v_mfma_f32_16x16x32_bf16 v[72:75], v[206:209], v[176:179], v[72:75]
	v_mfma_f32_16x16x32_bf16 v[68:71], v[192:195], v[184:187], v[68:71]
	v_mfma_f32_16x16x32_bf16 v[64:67], v[206:209], v[184:187], v[64:67]
	s_barrier
	ds_read_b128 v[156:159], v136 offset:16384
	ds_read_b128 v[160:163], v136 offset:17408
	ds_read_b128 v[164:167], v135 offset:16384
	ds_read_b128 v[168:171], v135 offset:17408
	ds_read_b128 v[172:175], v134 offset:16384
	ds_read_b128 v[176:179], v134 offset:17408
	ds_read_b128 v[180:183], v133 offset:16384
	ds_read_b128 v[184:187], v133 offset:17408
	s_mov_b32 m0, s52
	s_add_u32 s98, s28, s48
	s_addc_u32 s99, s29, s49
	global_load_lds_dwordx4 v128, s[98:99]
	s_add_i32 m0, s52, 0x2000
	s_nop 0
	global_load_lds_dwordx4 v130, s[98:99]
	s_barrier
	s_waitcnt lgkmcnt(0)
	s_waitcnt lgkmcnt(0)
	v_mfma_f32_16x16x32_bf16 v[60:63], v[140:143], v[156:159], v[60:63]
	v_mfma_f32_16x16x32_bf16 v[56:59], v[148:151], v[156:159], v[56:59]
	v_mfma_f32_16x16x32_bf16 v[52:55], v[140:143], v[164:167], v[52:55]
	v_mfma_f32_16x16x32_bf16 v[48:51], v[148:151], v[164:167], v[48:51]
	v_mfma_f32_16x16x32_bf16 v[44:47], v[140:143], v[172:175], v[44:47]
	v_mfma_f32_16x16x32_bf16 v[40:43], v[148:151], v[172:175], v[40:43]
	v_mfma_f32_16x16x32_bf16 v[36:39], v[140:143], v[180:183], v[36:39]
	v_mfma_f32_16x16x32_bf16 v[32:35], v[148:151], v[180:183], v[32:35]
	v_mfma_f32_16x16x32_bf16 v[60:63], v[144:147], v[160:163], v[60:63]
	v_mfma_f32_16x16x32_bf16 v[56:59], v[152:155], v[160:163], v[56:59]
	v_mfma_f32_16x16x32_bf16 v[52:55], v[144:147], v[168:171], v[52:55]
	v_mfma_f32_16x16x32_bf16 v[48:51], v[152:155], v[168:171], v[48:51]
	v_mfma_f32_16x16x32_bf16 v[44:47], v[144:147], v[176:179], v[44:47]
	v_mfma_f32_16x16x32_bf16 v[40:43], v[152:155], v[176:179], v[40:43]
	v_mfma_f32_16x16x32_bf16 v[36:39], v[144:147], v[184:187], v[36:39]
	v_mfma_f32_16x16x32_bf16 v[32:35], v[152:155], v[184:187], v[32:35]
	s_barrier
	s_add_i32 m0, s52, 0x14000
	s_add_u32 s98, s58, s50
	s_addc_u32 s99, s59, s51
	global_load_lds_dwordx4 v128, s[98:99]
	s_add_i32 m0, s52, 0x16000
	s_nop 0
	global_load_lds_dwordx4 v130, s[98:99]
	s_waitcnt vmcnt(6)
	s_barrier
	v_mfma_f32_16x16x32_bf16 v[28:31], v[188:191], v[156:159], v[28:31]
	v_mfma_f32_16x16x32_bf16 v[24:27], v[202:205], v[156:159], v[24:27]
	v_mfma_f32_16x16x32_bf16 v[20:23], v[188:191], v[164:167], v[20:23]
	v_mfma_f32_16x16x32_bf16 v[16:19], v[202:205], v[164:167], v[16:19]
	v_mfma_f32_16x16x32_bf16 v[12:15], v[188:191], v[172:175], v[12:15]
	v_mfma_f32_16x16x32_bf16 v[8:11], v[202:205], v[172:175], v[8:11]
	v_mfma_f32_16x16x32_bf16 v[4:7], v[188:191], v[180:183], v[4:7]
	v_mfma_f32_16x16x32_bf16 v[0:3], v[202:205], v[180:183], v[0:3]
	v_mfma_f32_16x16x32_bf16 v[28:31], v[192:195], v[160:163], v[28:31]
	v_mfma_f32_16x16x32_bf16 v[24:27], v[206:209], v[160:163], v[24:27]
	v_mfma_f32_16x16x32_bf16 v[20:23], v[192:195], v[168:171], v[20:23]
	v_mfma_f32_16x16x32_bf16 v[16:19], v[206:209], v[168:171], v[16:19]
	v_mfma_f32_16x16x32_bf16 v[12:15], v[192:195], v[176:179], v[12:15]
	v_mfma_f32_16x16x32_bf16 v[8:11], v[206:209], v[176:179], v[8:11]
	v_mfma_f32_16x16x32_bf16 v[4:7], v[192:195], v[184:187], v[4:7]
	v_mfma_f32_16x16x32_bf16 v[0:3], v[206:209], v[184:187], v[0:3]
	s_barrier
	ds_read_b128 v[140:143], v138
	ds_read_b128 v[144:147], v138 offset:1024
	ds_read_b128 v[148:151], v138 offset:2048
	ds_read_b128 v[152:155], v138 offset:3072
	ds_read_b128 v[156:159], v136 offset:32768
	ds_read_b128 v[160:163], v136 offset:33792
	ds_read_b128 v[164:167], v135 offset:32768
	ds_read_b128 v[168:171], v135 offset:33792
	ds_read_b128 v[172:175], v134 offset:32768
	ds_read_b128 v[176:179], v134 offset:33792
	ds_read_b128 v[180:183], v133 offset:32768
	ds_read_b128 v[184:187], v133 offset:33792
	s_add_i32 m0, s52, 0x4000
	s_add_u32 s98, s28, s54
	s_addc_u32 s99, s29, s55
	global_load_lds_dwordx4 v128, s[98:99]
	s_add_i32 m0, s52, 0x6000
	s_nop 0
	global_load_lds_dwordx4 v130, s[98:99]
	s_waitcnt lgkmcnt(8)
	s_barrier
	s_waitcnt lgkmcnt(0)
	s_waitcnt lgkmcnt(0)
	v_mfma_f32_16x16x32_bf16 v[124:127], v[140:143], v[156:159], v[124:127]
	v_mfma_f32_16x16x32_bf16 v[120:123], v[148:151], v[156:159], v[120:123]
	v_mfma_f32_16x16x32_bf16 v[116:119], v[140:143], v[164:167], v[116:119]
	v_mfma_f32_16x16x32_bf16 v[112:115], v[148:151], v[164:167], v[112:115]
	v_mfma_f32_16x16x32_bf16 v[108:111], v[140:143], v[172:175], v[108:111]
	v_mfma_f32_16x16x32_bf16 v[104:107], v[148:151], v[172:175], v[104:107]
	v_mfma_f32_16x16x32_bf16 v[100:103], v[140:143], v[180:183], v[100:103]
	v_mfma_f32_16x16x32_bf16 v[96:99], v[148:151], v[180:183], v[96:99]
	v_mfma_f32_16x16x32_bf16 v[124:127], v[144:147], v[160:163], v[124:127]
	v_mfma_f32_16x16x32_bf16 v[120:123], v[152:155], v[160:163], v[120:123]
	v_mfma_f32_16x16x32_bf16 v[116:119], v[144:147], v[168:171], v[116:119]
	v_mfma_f32_16x16x32_bf16 v[112:115], v[152:155], v[168:171], v[112:115]
	v_mfma_f32_16x16x32_bf16 v[108:111], v[144:147], v[176:179], v[108:111]
	v_mfma_f32_16x16x32_bf16 v[104:107], v[152:155], v[176:179], v[104:107]
	v_mfma_f32_16x16x32_bf16 v[100:103], v[144:147], v[184:187], v[100:103]
	v_mfma_f32_16x16x32_bf16 v[96:99], v[152:155], v[184:187], v[96:99]
	s_barrier
	ds_read_b128 v[188:191], v137
	ds_read_b128 v[192:195], v137 offset:1024
	ds_read_b128 v[202:205], v137 offset:2048
	ds_read_b128 v[206:209], v137 offset:3072
	s_mov_b32 m0, s7
	s_add_u32 s98, s58, s68
	s_addc_u32 s99, s59, s69
	global_load_lds_dwordx4 v128, s[98:99]
	s_mov_b32 m0, s53
	s_nop 0
	global_load_lds_dwordx4 v130, s[98:99]
	s_barrier
	s_waitcnt lgkmcnt(0)
	s_waitcnt lgkmcnt(0)
	v_mfma_f32_16x16x32_bf16 v[92:95], v[188:191], v[156:159], v[92:95]
	v_mfma_f32_16x16x32_bf16 v[88:91], v[202:205], v[156:159], v[88:91]
	v_mfma_f32_16x16x32_bf16 v[84:87], v[188:191], v[164:167], v[84:87]
	v_mfma_f32_16x16x32_bf16 v[80:83], v[202:205], v[164:167], v[80:83]
	v_mfma_f32_16x16x32_bf16 v[76:79], v[188:191], v[172:175], v[76:79]
	v_mfma_f32_16x16x32_bf16 v[72:75], v[202:205], v[172:175], v[72:75]
	v_mfma_f32_16x16x32_bf16 v[68:71], v[188:191], v[180:183], v[68:71]
	v_mfma_f32_16x16x32_bf16 v[64:67], v[202:205], v[180:183], v[64:67]
	v_mfma_f32_16x16x32_bf16 v[92:95], v[192:195], v[160:163], v[92:95]
	v_mfma_f32_16x16x32_bf16 v[88:91], v[206:209], v[160:163], v[88:91]
	v_mfma_f32_16x16x32_bf16 v[84:87], v[192:195], v[168:171], v[84:87]
	v_mfma_f32_16x16x32_bf16 v[80:83], v[206:209], v[168:171], v[80:83]
	v_mfma_f32_16x16x32_bf16 v[76:79], v[192:195], v[176:179], v[76:79]
	v_mfma_f32_16x16x32_bf16 v[72:75], v[206:209], v[176:179], v[72:75]
	v_mfma_f32_16x16x32_bf16 v[68:71], v[192:195], v[184:187], v[68:71]
	v_mfma_f32_16x16x32_bf16 v[64:67], v[206:209], v[184:187], v[64:67]
	v_mov_b32_e32 v210, v130
	s_barrier
	ds_read_b128 v[156:159], v136 offset:49152
	ds_read_b128 v[160:163], v136 offset:50176
	ds_read_b128 v[164:167], v135 offset:49152
	ds_read_b128 v[168:171], v135 offset:50176
	ds_read_b128 v[172:175], v134 offset:49152
	ds_read_b128 v[176:179], v134 offset:50176
	ds_read_b128 v[180:183], v133 offset:49152
	ds_read_b128 v[184:187], v133 offset:50176
	v_mov_b32_e32 v211, v197
	s_mov_b32 m0, s9
	s_add_u32 s98, s28, s70
	s_addc_u32 s99, s29, s71
	global_load_lds_dwordx4 v128, s[98:99]
	s_mov_b32 m0, s33
	s_nop 0
	global_load_lds_dwordx4 v130, s[98:99]
	s_barrier
	s_waitcnt lgkmcnt(0)
	s_waitcnt lgkmcnt(0)
	v_mfma_f32_16x16x32_bf16 v[60:63], v[140:143], v[156:159], v[60:63]
	v_mfma_f32_16x16x32_bf16 v[56:59], v[148:151], v[156:159], v[56:59]
	v_mfma_f32_16x16x32_bf16 v[52:55], v[140:143], v[164:167], v[52:55]
	v_mfma_f32_16x16x32_bf16 v[48:51], v[148:151], v[164:167], v[48:51]
	v_mfma_f32_16x16x32_bf16 v[44:47], v[140:143], v[172:175], v[44:47]
	v_mfma_f32_16x16x32_bf16 v[40:43], v[148:151], v[172:175], v[40:43]
	v_mfma_f32_16x16x32_bf16 v[36:39], v[140:143], v[180:183], v[36:39]
	v_mfma_f32_16x16x32_bf16 v[32:35], v[148:151], v[180:183], v[32:35]
	v_mfma_f32_16x16x32_bf16 v[60:63], v[144:147], v[160:163], v[60:63]
	v_mfma_f32_16x16x32_bf16 v[56:59], v[152:155], v[160:163], v[56:59]
	v_mfma_f32_16x16x32_bf16 v[52:55], v[144:147], v[168:171], v[52:55]
	v_mfma_f32_16x16x32_bf16 v[48:51], v[152:155], v[168:171], v[48:51]
	v_mfma_f32_16x16x32_bf16 v[44:47], v[144:147], v[176:179], v[44:47]
	v_mfma_f32_16x16x32_bf16 v[40:43], v[152:155], v[176:179], v[40:43]
	v_mfma_f32_16x16x32_bf16 v[36:39], v[144:147], v[184:187], v[36:39]
	v_mfma_f32_16x16x32_bf16 v[32:35], v[152:155], v[184:187], v[32:35]
	s_barrier
	v_mov_b32_e32 v196, v128
	s_mov_b32 m0, s65
	s_add_u32 s98, s58, s72
	s_addc_u32 s99, s59, s73
	global_load_lds_dwordx4 v128, s[98:99]
	s_mov_b32 m0, s66
	s_nop 0
	global_load_lds_dwordx4 v130, s[98:99]
	s_waitcnt vmcnt(6)
	s_barrier
	v_mfma_f32_16x16x32_bf16 v[28:31], v[188:191], v[156:159], v[28:31]
	v_mfma_f32_16x16x32_bf16 v[24:27], v[202:205], v[156:159], v[24:27]
	v_mfma_f32_16x16x32_bf16 v[20:23], v[188:191], v[164:167], v[20:23]
	v_mfma_f32_16x16x32_bf16 v[16:19], v[202:205], v[164:167], v[16:19]
	v_mfma_f32_16x16x32_bf16 v[12:15], v[188:191], v[172:175], v[12:15]
	v_mfma_f32_16x16x32_bf16 v[8:11], v[202:205], v[172:175], v[8:11]
	v_mfma_f32_16x16x32_bf16 v[4:7], v[188:191], v[180:183], v[4:7]
	v_mfma_f32_16x16x32_bf16 v[0:3], v[202:205], v[180:183], v[0:3]
	v_mfma_f32_16x16x32_bf16 v[28:31], v[192:195], v[160:163], v[28:31]
	v_mfma_f32_16x16x32_bf16 v[24:27], v[206:209], v[160:163], v[24:27]
	v_mfma_f32_16x16x32_bf16 v[20:23], v[192:195], v[168:171], v[20:23]
	v_mfma_f32_16x16x32_bf16 v[16:19], v[206:209], v[168:171], v[16:19]
	v_mfma_f32_16x16x32_bf16 v[12:15], v[192:195], v[176:179], v[12:15]
	v_mfma_f32_16x16x32_bf16 v[8:11], v[206:209], v[176:179], v[8:11]
	v_mfma_f32_16x16x32_bf16 v[4:7], v[192:195], v[184:187], v[4:7]
	v_mfma_f32_16x16x32_bf16 v[0:3], v[206:209], v[184:187], v[0:3]
	s_add_i32 s38, s38, 2
	s_add_u32 s56, s56, 0x100
	s_addc_u32 s57, s57, 0
	s_cmp_lt_u32 s38, 28
	s_barrier
	s_cbranch_scc1 .LBB0_192
	s_lshl_b64 s[4:5], s[10:11], 12
	v_readlane_b32 s10, v254, 12
	v_readlane_b32 s11, v254, 13
	s_add_u32 s4, s10, s4
	s_addc_u32 s5, s11, s5
	ds_read_b128 v[140:143], v129
	ds_read_b128 v[144:147], v129 offset:1024
	ds_read_b128 v[148:151], v129 offset:2048
	ds_read_b128 v[152:155], v129 offset:3072
	ds_read_b128 v[156:159], v136
	ds_read_b128 v[160:163], v136 offset:1024
	ds_read_b128 v[164:167], v135
	ds_read_b128 v[168:171], v135 offset:1024
	ds_read_b128 v[172:175], v134
	ds_read_b128 v[176:179], v134 offset:1024
	ds_read_b128 v[180:183], v133
	ds_read_b128 v[184:187], v133 offset:1024
	v_mov_b32_e32 v129, v197
	v_lshl_add_u64 v[128:129], s[4:5], 0, v[128:129]
	s_mov_b64 s[10:11], 0xf80
	s_mov_b32 m0, s40
	v_lshl_add_u64 v[128:129], v[128:129], 0, s[10:11]
	v_mov_b32_e32 v131, v197
	global_load_lds_dwordx4 v[128:129], off
	v_lshl_add_u64 v[128:129], s[4:5], 0, v[130:131]
	v_lshl_add_u64 v[128:129], v[128:129], 0, s[10:11]
	s_mov_b32 m0, s39
	s_nop 0
	global_load_lds_dwordx4 v[128:129], off
	s_barrier
	s_waitcnt lgkmcnt(0)
	s_setprio 1
	s_waitcnt lgkmcnt(0)
	v_mfma_f32_16x16x32_bf16 v[124:127], v[140:143], v[156:159], v[124:127]
	v_mfma_f32_16x16x32_bf16 v[116:119], v[140:143], v[164:167], v[116:119]
	v_mfma_f32_16x16x32_bf16 v[112:115], v[148:151], v[164:167], v[112:115]
	v_mfma_f32_16x16x32_bf16 v[108:111], v[140:143], v[172:175], v[108:111]
	v_mfma_f32_16x16x32_bf16 v[104:107], v[148:151], v[172:175], v[104:107]
	v_mfma_f32_16x16x32_bf16 v[100:103], v[140:143], v[180:183], v[100:103]
	v_mfma_f32_16x16x32_bf16 v[96:99], v[148:151], v[180:183], v[96:99]
	v_mfma_f32_16x16x32_bf16 v[124:127], v[144:147], v[160:163], v[124:127]
	v_mfma_f32_16x16x32_bf16 v[120:123], v[148:151], v[156:159], v[120:123]
	v_mfma_f32_16x16x32_bf16 v[116:119], v[144:147], v[168:171], v[116:119]
	v_mfma_f32_16x16x32_bf16 v[112:115], v[152:155], v[168:171], v[112:115]
	v_mfma_f32_16x16x32_bf16 v[108:111], v[144:147], v[176:179], v[108:111]
	v_mfma_f32_16x16x32_bf16 v[104:107], v[152:155], v[176:179], v[104:107]
	v_mfma_f32_16x16x32_bf16 v[100:103], v[144:147], v[184:187], v[100:103]
	v_mfma_f32_16x16x32_bf16 v[96:99], v[152:155], v[184:187], v[96:99]
	v_mfma_f32_16x16x32_bf16 v[128:131], v[152:155], v[160:163], v[120:123]
	s_setprio 0
	s_barrier
	s_nop 0
	ds_read_b128 v[120:123], v139
	ds_read_b128 v[188:191], v139 offset:1024
	ds_read_b128 v[192:195], v139 offset:2048
	ds_read_b128 v[202:205], v139 offset:3072
	s_barrier
	s_waitcnt lgkmcnt(0)
	s_setprio 1
	s_waitcnt lgkmcnt(0)
	v_mfma_f32_16x16x32_bf16 v[76:79], v[120:123], v[172:175], v[76:79]
	v_mfma_f32_16x16x32_bf16 v[68:71], v[120:123], v[180:183], v[68:71]
	v_mfma_f32_16x16x32_bf16 v[64:67], v[192:195], v[180:183], v[64:67]
	v_mfma_f32_16x16x32_bf16 v[92:95], v[120:123], v[156:159], v[92:95]
	v_mfma_f32_16x16x32_bf16 v[88:91], v[192:195], v[156:159], v[88:91]
	v_mfma_f32_16x16x32_bf16 v[84:87], v[120:123], v[164:167], v[84:87]
	v_mfma_f32_16x16x32_bf16 v[80:83], v[192:195], v[164:167], v[80:83]
	v_mfma_f32_16x16x32_bf16 v[76:79], v[188:191], v[176:179], v[76:79]
	v_mfma_f32_16x16x32_bf16 v[72:75], v[192:195], v[172:175], v[72:75]
	v_mfma_f32_16x16x32_bf16 v[68:71], v[188:191], v[184:187], v[68:71]
	v_mfma_f32_16x16x32_bf16 v[64:67], v[202:205], v[184:187], v[64:67]
	v_mfma_f32_16x16x32_bf16 v[206:209], v[188:191], v[160:163], v[92:95]
	v_mfma_f32_16x16x32_bf16 v[156:159], v[202:205], v[160:163], v[88:91]
	v_mfma_f32_16x16x32_bf16 v[160:163], v[188:191], v[168:171], v[84:87]
	v_mfma_f32_16x16x32_bf16 v[164:167], v[202:205], v[168:171], v[80:83]
	v_mfma_f32_16x16x32_bf16 v[168:171], v[202:205], v[176:179], v[72:75]
	s_setprio 0
	s_barrier
	s_nop 0
	ds_read_b128 v[72:75], v136 offset:16384
	ds_read_b128 v[80:83], v136 offset:17408
	ds_read_b128 v[84:87], v135 offset:16384
	ds_read_b128 v[88:91], v135 offset:17408
	ds_read_b128 v[92:95], v134 offset:16384
	ds_read_b128 v[172:175], v134 offset:17408
	ds_read_b128 v[176:179], v133 offset:16384
	ds_read_b128 v[180:183], v133 offset:17408
	s_waitcnt vmcnt(4)
	s_barrier
	s_waitcnt lgkmcnt(0)
	s_setprio 1
	s_waitcnt lgkmcnt(0)
	v_mfma_f32_16x16x32_bf16 v[60:63], v[140:143], v[72:75], v[60:63]
	v_mfma_f32_16x16x32_bf16 v[52:55], v[140:143], v[84:87], v[52:55]
	v_mfma_f32_16x16x32_bf16 v[48:51], v[148:151], v[84:87], v[48:51]
	v_mfma_f32_16x16x32_bf16 v[44:47], v[140:143], v[92:95], v[44:47]
	v_mfma_f32_16x16x32_bf16 v[40:43], v[148:151], v[92:95], v[40:43]
	v_mfma_f32_16x16x32_bf16 v[36:39], v[140:143], v[176:179], v[36:39]
	v_mfma_f32_16x16x32_bf16 v[32:35], v[148:151], v[176:179], v[32:35]
	v_mfma_f32_16x16x32_bf16 v[60:63], v[144:147], v[80:83], v[60:63]
	v_mfma_f32_16x16x32_bf16 v[56:59], v[148:151], v[72:75], v[56:59]
	v_mfma_f32_16x16x32_bf16 v[52:55], v[144:147], v[88:91], v[52:55]
	v_mfma_f32_16x16x32_bf16 v[48:51], v[152:155], v[88:91], v[48:51]
	v_mfma_f32_16x16x32_bf16 v[44:47], v[144:147], v[172:175], v[44:47]
	v_mfma_f32_16x16x32_bf16 v[40:43], v[152:155], v[172:175], v[40:43]
	v_mfma_f32_16x16x32_bf16 v[36:39], v[144:147], v[180:183], v[36:39]
	v_mfma_f32_16x16x32_bf16 v[32:35], v[152:155], v[180:183], v[32:35]
	v_mfma_f32_16x16x32_bf16 v[184:187], v[152:155], v[80:83], v[56:59]
	s_setprio 0
	s_setprio 1
	v_mfma_f32_16x16x32_bf16 v[12:15], v[120:123], v[92:95], v[12:15]
	v_mfma_f32_16x16x32_bf16 v[4:7], v[120:123], v[176:179], v[4:7]
	v_mfma_f32_16x16x32_bf16 v[0:3], v[192:195], v[176:179], v[0:3]
	v_mfma_f32_16x16x32_bf16 v[28:31], v[120:123], v[72:75], v[28:31]
	v_mfma_f32_16x16x32_bf16 v[24:27], v[192:195], v[72:75], v[24:27]
	v_mfma_f32_16x16x32_bf16 v[20:23], v[120:123], v[84:87], v[20:23]
	v_mfma_f32_16x16x32_bf16 v[16:19], v[192:195], v[84:87], v[16:19]
	v_mfma_f32_16x16x32_bf16 v[12:15], v[188:191], v[172:175], v[12:15]
	v_mfma_f32_16x16x32_bf16 v[8:11], v[192:195], v[92:95], v[8:11]
	v_mfma_f32_16x16x32_bf16 v[4:7], v[188:191], v[180:183], v[4:7]
	v_mfma_f32_16x16x32_bf16 v[0:3], v[202:205], v[180:183], v[0:3]
	v_mfma_f32_16x16x32_bf16 v[140:143], v[188:191], v[80:83], v[28:31]
	v_mfma_f32_16x16x32_bf16 v[144:147], v[202:205], v[80:83], v[24:27]
	v_mfma_f32_16x16x32_bf16 v[148:151], v[188:191], v[88:91], v[20:23]
	v_mfma_f32_16x16x32_bf16 v[152:155], v[202:205], v[88:91], v[16:19]
	v_mfma_f32_16x16x32_bf16 v[172:175], v[202:205], v[172:175], v[8:11]
	s_setprio 0
	s_barrier
	s_nop 0
	ds_read_b128 v[8:11], v138
	ds_read_b128 v[16:19], v138 offset:1024
	ds_read_b128 v[176:179], v138 offset:2048
	ds_read_b128 v[180:183], v138 offset:3072
	ds_read_b128 v[20:23], v136 offset:32768
	ds_read_b128 v[24:27], v136 offset:33792
	ds_read_b128 v[28:31], v135 offset:32768
	ds_read_b128 v[56:59], v135 offset:33792
	ds_read_b128 v[188:191], v134 offset:32768
	ds_read_b128 v[192:195], v134 offset:33792
	ds_read_b128 v[202:205], v133 offset:32768
	ds_read_b128 v[210:213], v133 offset:33792
	s_waitcnt vmcnt(2)
	s_barrier
	s_waitcnt lgkmcnt(0)
	s_setprio 1
	s_waitcnt lgkmcnt(0)
	v_mfma_f32_16x16x32_bf16 v[72:75], v[8:11], v[20:23], v[124:127]
	v_mfma_f32_16x16x32_bf16 v[120:123], v[16:19], v[24:27], v[72:75]
	v_mfma_f32_16x16x32_bf16 v[72:75], v[176:179], v[20:23], v[128:131]
	v_mfma_f32_16x16x32_bf16 v[124:127], v[180:183], v[24:27], v[72:75]
	v_mfma_f32_16x16x32_bf16 v[72:75], v[8:11], v[28:31], v[116:119]
	v_mfma_f32_16x16x32_bf16 v[116:119], v[16:19], v[56:59], v[72:75]
	v_mfma_f32_16x16x32_bf16 v[72:75], v[176:179], v[28:31], v[112:115]
	v_mfma_f32_16x16x32_bf16 v[112:115], v[180:183], v[56:59], v[72:75]
	v_mfma_f32_16x16x32_bf16 v[72:75], v[8:11], v[188:191], v[108:111]
	v_mfma_f32_16x16x32_bf16 v[88:91], v[16:19], v[192:195], v[72:75]
	v_mfma_f32_16x16x32_bf16 v[72:75], v[176:179], v[188:191], v[104:107]
	v_mfma_f32_16x16x32_bf16 v[92:95], v[180:183], v[192:195], v[72:75]
	v_mfma_f32_16x16x32_bf16 v[72:75], v[8:11], v[202:205], v[100:103]
	v_mfma_f32_16x16x32_bf16 v[84:87], v[16:19], v[210:213], v[72:75]
	v_mfma_f32_16x16x32_bf16 v[72:75], v[176:179], v[202:205], v[96:99]
	v_mfma_f32_16x16x32_bf16 v[80:83], v[180:183], v[210:213], v[72:75]
	s_setprio 0
	s_barrier
	ds_read_b128 v[128:131], v137
	ds_read_b128 v[214:217], v137 offset:1024
	ds_read_b128 v[218:221], v137 offset:2048
	ds_read_b128 v[222:225], v137 offset:3072
	s_waitcnt vmcnt(0)
	s_barrier
	s_waitcnt lgkmcnt(0)
	s_setprio 1
	s_waitcnt lgkmcnt(0)
	v_mfma_f32_16x16x32_bf16 v[72:75], v[128:131], v[20:23], v[206:209]
	v_mfma_f32_16x16x32_bf16 v[20:23], v[218:221], v[20:23], v[156:159]
	v_mfma_f32_16x16x32_bf16 v[108:111], v[222:225], v[24:27], v[20:23]
	v_mfma_f32_16x16x32_bf16 v[20:23], v[128:131], v[28:31], v[160:163]
	v_mfma_f32_16x16x32_bf16 v[100:103], v[214:217], v[56:59], v[20:23]
	v_mfma_f32_16x16x32_bf16 v[20:23], v[218:221], v[28:31], v[164:167]
	v_mfma_f32_16x16x32_bf16 v[96:99], v[222:225], v[56:59], v[20:23]
	v_mfma_f32_16x16x32_bf16 v[20:23], v[128:131], v[188:191], v[76:79]
	v_mfma_f32_16x16x32_bf16 v[104:107], v[214:217], v[24:27], v[72:75]
	v_mfma_f32_16x16x32_bf16 v[72:75], v[214:217], v[192:195], v[20:23]
	v_mfma_f32_16x16x32_bf16 v[20:23], v[218:221], v[188:191], v[168:171]
	v_mfma_f32_16x16x32_bf16 v[76:79], v[222:225], v[192:195], v[20:23]
	v_mfma_f32_16x16x32_bf16 v[20:23], v[128:131], v[202:205], v[68:71]
	v_mfma_f32_16x16x32_bf16 v[68:71], v[214:217], v[210:213], v[20:23]
	v_mfma_f32_16x16x32_bf16 v[20:23], v[218:221], v[202:205], v[64:67]
	v_mfma_f32_16x16x32_bf16 v[64:67], v[222:225], v[210:213], v[20:23]
	s_setprio 0
	s_barrier
	ds_read_b128 v[156:159], v136 offset:49152
	ds_read_b128 v[136:139], v136 offset:50176
	ds_read_b128 v[160:163], v135 offset:49152
	ds_read_b128 v[164:167], v135 offset:50176
	ds_read_b128 v[168:171], v134 offset:49152
	ds_read_b128 v[188:191], v134 offset:50176
	ds_read_b128 v[192:195], v133 offset:49152
	ds_read_b128 v[202:205], v133 offset:50176
	s_barrier
	s_waitcnt lgkmcnt(0)
	s_setprio 1
	s_waitcnt lgkmcnt(0)
	v_mfma_f32_16x16x32_bf16 v[20:23], v[8:11], v[156:159], v[60:63]
	v_mfma_f32_16x16x32_bf16 v[56:59], v[16:19], v[136:139], v[20:23]
	v_mfma_f32_16x16x32_bf16 v[20:23], v[176:179], v[156:159], v[184:187]
	v_mfma_f32_16x16x32_bf16 v[60:63], v[180:183], v[136:139], v[20:23]
	v_mfma_f32_16x16x32_bf16 v[20:23], v[8:11], v[160:163], v[52:55]
	v_mfma_f32_16x16x32_bf16 v[52:55], v[16:19], v[164:167], v[20:23]
	v_mfma_f32_16x16x32_bf16 v[20:23], v[176:179], v[160:163], v[48:51]
	v_mfma_f32_16x16x32_bf16 v[48:51], v[180:183], v[164:167], v[20:23]
	v_mfma_f32_16x16x32_bf16 v[20:23], v[8:11], v[168:171], v[44:47]
	v_mfma_f32_16x16x32_bf16 v[24:27], v[16:19], v[188:191], v[20:23]
	v_mfma_f32_16x16x32_bf16 v[20:23], v[176:179], v[168:171], v[40:43]
	v_mfma_f32_16x16x32_bf16 v[8:11], v[8:11], v[192:195], v[36:39]
	v_mfma_f32_16x16x32_bf16 v[28:31], v[180:183], v[188:191], v[20:23]
	v_mfma_f32_16x16x32_bf16 v[20:23], v[16:19], v[202:205], v[8:11]
	v_mfma_f32_16x16x32_bf16 v[8:11], v[176:179], v[192:195], v[32:35]
	v_mfma_f32_16x16x32_bf16 v[16:19], v[180:183], v[202:205], v[8:11]
	s_setprio 0
	s_setprio 1
	v_mfma_f32_16x16x32_bf16 v[8:11], v[128:131], v[156:159], v[140:143]
	v_mfma_f32_16x16x32_bf16 v[40:43], v[214:217], v[136:139], v[8:11]
	v_mfma_f32_16x16x32_bf16 v[8:11], v[218:221], v[156:159], v[144:147]
	v_mfma_f32_16x16x32_bf16 v[44:47], v[222:225], v[136:139], v[8:11]
	v_mfma_f32_16x16x32_bf16 v[8:11], v[128:131], v[160:163], v[148:151]
	v_mfma_f32_16x16x32_bf16 v[36:39], v[214:217], v[164:167], v[8:11]
	v_mfma_f32_16x16x32_bf16 v[8:11], v[218:221], v[160:163], v[152:155]
	v_mfma_f32_16x16x32_bf16 v[32:35], v[222:225], v[164:167], v[8:11]
	v_mfma_f32_16x16x32_bf16 v[8:11], v[128:131], v[168:171], v[12:15]
	v_mfma_f32_16x16x32_bf16 v[12:15], v[218:221], v[168:171], v[172:175]
	v_mfma_f32_16x16x32_bf16 v[4:7], v[128:131], v[192:195], v[4:7]
	v_mfma_f32_16x16x32_bf16 v[0:3], v[218:221], v[192:195], v[0:3]
	v_mfma_f32_16x16x32_bf16 v[8:11], v[214:217], v[188:191], v[8:11]
	v_mfma_f32_16x16x32_bf16 v[12:15], v[222:225], v[188:191], v[12:15]
	v_mfma_f32_16x16x32_bf16 v[4:7], v[214:217], v[202:205], v[4:7]
	v_mfma_f32_16x16x32_bf16 v[0:3], v[222:225], v[202:205], v[0:3]
	s_setprio 0
	s_movk_i32 s4, 0x100
	v_cmp_gt_u32_e32 vcc, s4, v132
	s_barrier
	s_and_saveexec_b64 s[4:5], vcc
	s_cbranch_execz .LBB0_195
	s_barrier

.Lh1_loop:
	ds_read_b128 v[140:143], v129
	ds_read_b128 v[144:147], v129 offset:1024
	ds_read_b128 v[148:151], v129 offset:2048
	ds_read_b128 v[152:155], v129 offset:3072
	s_add_u32 s28, s60, s56
	s_addc_u32 s29, s61, s57
	ds_read_b128 v[156:159], v136
	ds_read_b128 v[160:163], v136 offset:1024
	ds_read_b128 v[164:167], v135
	ds_read_b128 v[168:171], v135 offset:1024
	ds_read_b128 v[172:175], v134
	ds_read_b128 v[176:179], v134 offset:1024
	ds_read_b128 v[180:183], v133
	ds_read_b128 v[184:187], v133 offset:1024
	s_add_i32 s40, s53, 0xc000
	s_mov_b32 m0, s40
	s_add_i32 s39, s53, 0xe000
	s_mov_b32 m0, s39
	s_nop 0
	s_waitcnt lgkmcnt(8)
	s_barrier
	s_waitcnt lgkmcnt(0)
	s_waitcnt lgkmcnt(0)
	v_mfma_f32_16x16x32_bf16 v[124:127], v[140:143], v[156:159], v[124:127]
	v_mfma_f32_16x16x32_bf16 v[120:123], v[148:151], v[156:159], v[120:123]
	v_mfma_f32_16x16x32_bf16 v[116:119], v[140:143], v[164:167], v[116:119]
	v_mfma_f32_16x16x32_bf16 v[112:115], v[148:151], v[164:167], v[112:115]
	v_mfma_f32_16x16x32_bf16 v[108:111], v[140:143], v[172:175], v[108:111]
	v_mfma_f32_16x16x32_bf16 v[104:107], v[148:151], v[172:175], v[104:107]
	v_mfma_f32_16x16x32_bf16 v[100:103], v[140:143], v[180:183], v[100:103]
	v_mfma_f32_16x16x32_bf16 v[96:99], v[148:151], v[180:183], v[96:99]
	v_mfma_f32_16x16x32_bf16 v[124:127], v[144:147], v[160:163], v[124:127]
	v_mfma_f32_16x16x32_bf16 v[120:123], v[152:155], v[160:163], v[120:123]
	v_mfma_f32_16x16x32_bf16 v[116:119], v[144:147], v[168:171], v[116:119]
	v_mfma_f32_16x16x32_bf16 v[112:115], v[152:155], v[168:171], v[112:115]
	v_mfma_f32_16x16x32_bf16 v[108:111], v[144:147], v[176:179], v[108:111]
	v_mfma_f32_16x16x32_bf16 v[104:107], v[152:155], v[176:179], v[104:107]
	v_mfma_f32_16x16x32_bf16 v[100:103], v[144:147], v[184:187], v[100:103]
	v_mfma_f32_16x16x32_bf16 v[96:99], v[152:155], v[184:187], v[96:99]
	s_barrier
	s_add_u32 s62, s60, s36
	s_addc_u32 s63, s61, s37
	ds_read_b128 v[188:191], v139
	ds_read_b128 v[192:195], v139 offset:1024
	ds_read_b128 v[202:205], v139 offset:2048
	ds_read_b128 v[206:209], v139 offset:3072
	s_mov_b32 m0, s68
	s_add_u32 s98, s62, s46
	s_addc_u32 s99, s63, s47
	global_load_lds_dwordx4 v128, s[98:99]
	s_mov_b32 m0, s69
	s_nop 0
	global_load_lds_dwordx4 v130, s[98:99]
	s_barrier
	s_waitcnt lgkmcnt(0)
	s_waitcnt lgkmcnt(0)
	v_mfma_f32_16x16x32_bf16 v[92:95], v[188:191], v[156:159], v[92:95]
	v_mfma_f32_16x16x32_bf16 v[88:91], v[202:205], v[156:159], v[88:91]
	v_mfma_f32_16x16x32_bf16 v[84:87], v[188:191], v[164:167], v[84:87]
	v_mfma_f32_16x16x32_bf16 v[80:83], v[202:205], v[164:167], v[80:83]
	v_mfma_f32_16x16x32_bf16 v[76:79], v[188:191], v[172:175], v[76:79]
	v_mfma_f32_16x16x32_bf16 v[72:75], v[202:205], v[172:175], v[72:75]
	v_mfma_f32_16x16x32_bf16 v[68:71], v[188:191], v[180:183], v[68:71]
	v_mfma_f32_16x16x32_bf16 v[64:67], v[202:205], v[180:183], v[64:67]
	v_mfma_f32_16x16x32_bf16 v[92:95], v[192:195], v[160:163], v[92:95]
	v_mfma_f32_16x16x32_bf16 v[88:91], v[206:209], v[160:163], v[88:91]
	v_mfma_f32_16x16x32_bf16 v[84:87], v[192:195], v[168:171], v[84:87]
	v_mfma_f32_16x16x32_bf16 v[80:83], v[206:209], v[168:171], v[80:83]
	v_mfma_f32_16x16x32_bf16 v[76:79], v[192:195], v[176:179], v[76:79]
	v_mfma_f32_16x16x32_bf16 v[72:75], v[206:209], v[176:179], v[72:75]
	v_mfma_f32_16x16x32_bf16 v[68:71], v[192:195], v[184:187], v[68:71]
	v_mfma_f32_16x16x32_bf16 v[64:67], v[206:209], v[184:187], v[64:67]
	s_barrier
	s_mov_b32 m0, s53
	s_add_u32 s98, s28, s48
	s_addc_u32 s99, s29, s49
	global_load_lds_dwordx4 v128, s[98:99]
	s_mov_b32 m0, s11
	s_nop 0
	global_load_lds_dwordx4 v130, s[98:99]
	s_waitcnt vmcnt(4)
	s_barrier
	s_mov_b32 m0, s9
	s_add_u32 s98, s62, s50
	s_addc_u32 s99, s63, s51
	global_load_lds_dwordx4 v128, s[98:99]
	s_mov_b32 m0, s70
	s_nop 0
	global_load_lds_dwordx4 v130, s[98:99]
	s_barrier
	ds_read_b128 v[140:143], v138
	ds_read_b128 v[144:147], v138 offset:1024
	ds_read_b128 v[148:151], v138 offset:2048
	ds_read_b128 v[152:155], v138 offset:3072
	ds_read_b128 v[156:159], v136 offset:32768
	ds_read_b128 v[160:163], v136 offset:33792
	ds_read_b128 v[164:167], v135 offset:32768
	ds_read_b128 v[168:171], v135 offset:33792
	ds_read_b128 v[172:175], v134 offset:32768
	ds_read_b128 v[176:179], v134 offset:33792
	ds_read_b128 v[180:183], v133 offset:32768
	ds_read_b128 v[184:187], v133 offset:33792
	s_mov_b32 m0, s71
	s_mov_b32 m0, s72
	s_nop 0
	s_waitcnt lgkmcnt(8)
	s_barrier
	s_waitcnt lgkmcnt(0)
	s_waitcnt lgkmcnt(0)
	v_mfma_f32_16x16x32_bf16 v[124:127], v[140:143], v[156:159], v[124:127]
	v_mfma_f32_16x16x32_bf16 v[120:123], v[148:151], v[156:159], v[120:123]
	v_mfma_f32_16x16x32_bf16 v[116:119], v[140:143], v[164:167], v[116:119]
	v_mfma_f32_16x16x32_bf16 v[112:115], v[148:151], v[164:167], v[112:115]
	v_mfma_f32_16x16x32_bf16 v[108:111], v[140:143], v[172:175], v[108:111]
	v_mfma_f32_16x16x32_bf16 v[104:107], v[148:151], v[172:175], v[104:107]
	v_mfma_f32_16x16x32_bf16 v[100:103], v[140:143], v[180:183], v[100:103]
	v_mfma_f32_16x16x32_bf16 v[96:99], v[148:151], v[180:183], v[96:99]
	v_mfma_f32_16x16x32_bf16 v[124:127], v[144:147], v[160:163], v[124:127]
	v_mfma_f32_16x16x32_bf16 v[120:123], v[152:155], v[160:163], v[120:123]
	v_mfma_f32_16x16x32_bf16 v[116:119], v[144:147], v[168:171], v[116:119]
	v_mfma_f32_16x16x32_bf16 v[112:115], v[152:155], v[168:171], v[112:115]
	v_mfma_f32_16x16x32_bf16 v[108:111], v[144:147], v[176:179], v[108:111]
	v_mfma_f32_16x16x32_bf16 v[104:107], v[152:155], v[176:179], v[104:107]
	v_mfma_f32_16x16x32_bf16 v[100:103], v[144:147], v[184:187], v[100:103]
	v_mfma_f32_16x16x32_bf16 v[96:99], v[152:155], v[184:187], v[96:99]
	s_barrier
	ds_read_b128 v[188:191], v137
	ds_read_b128 v[192:195], v137 offset:1024
	ds_read_b128 v[202:205], v137 offset:2048
	ds_read_b128 v[206:209], v137 offset:3072
	s_mov_b32 m0, s66
	s_add_u32 s98, s62, s90
	s_addc_u32 s99, s63, s91
	global_load_lds_dwordx4 v128, s[98:99]
	s_mov_b32 m0, s64
	s_nop 0
	global_load_lds_dwordx4 v130, s[98:99]
	s_barrier
	s_waitcnt lgkmcnt(0)
	s_waitcnt lgkmcnt(0)
	v_mfma_f32_16x16x32_bf16 v[92:95], v[188:191], v[156:159], v[92:95]
	v_mfma_f32_16x16x32_bf16 v[88:91], v[202:205], v[156:159], v[88:91]
	v_mfma_f32_16x16x32_bf16 v[84:87], v[188:191], v[164:167], v[84:87]
	v_mfma_f32_16x16x32_bf16 v[80:83], v[202:205], v[164:167], v[80:83]
	v_mfma_f32_16x16x32_bf16 v[76:79], v[188:191], v[172:175], v[76:79]
	v_mfma_f32_16x16x32_bf16 v[72:75], v[202:205], v[172:175], v[72:75]
	v_mfma_f32_16x16x32_bf16 v[68:71], v[188:191], v[180:183], v[68:71]
	v_mfma_f32_16x16x32_bf16 v[64:67], v[202:205], v[180:183], v[64:67]
	v_mfma_f32_16x16x32_bf16 v[92:95], v[192:195], v[160:163], v[92:95]
	v_mfma_f32_16x16x32_bf16 v[88:91], v[206:209], v[160:163], v[88:91]
	v_mfma_f32_16x16x32_bf16 v[84:87], v[192:195], v[168:171], v[84:87]
	v_mfma_f32_16x16x32_bf16 v[80:83], v[206:209], v[168:171], v[80:83]
	v_mfma_f32_16x16x32_bf16 v[76:79], v[192:195], v[176:179], v[76:79]
	v_mfma_f32_16x16x32_bf16 v[72:75], v[206:209], v[176:179], v[72:75]
	v_mfma_f32_16x16x32_bf16 v[68:71], v[192:195], v[184:187], v[68:71]
	v_mfma_f32_16x16x32_bf16 v[64:67], v[206:209], v[184:187], v[64:67]
	v_mov_b32_e32 v210, v130
	s_barrier
	v_mov_b32_e32 v211, v197
	s_mov_b32 m0, s65
	s_add_u32 s98, s28, s92
	s_addc_u32 s99, s29, s93
	global_load_lds_dwordx4 v128, s[98:99]
	s_mov_b32 m0, s67
	s_nop 0
	global_load_lds_dwordx4 v130, s[98:99]
	s_waitcnt vmcnt(4)
	s_barrier
	v_mov_b32_e32 v196, v128
	s_mov_b32 m0, s33
	s_add_u32 s98, s62, s96
	s_addc_u32 s99, s63, s97
	global_load_lds_dwordx4 v128, s[98:99]
	s_mov_b32 m0, s73
	s_nop 0
	global_load_lds_dwordx4 v130, s[98:99]
	s_barrier
	s_add_i32 s38, s38, 2
	s_add_u32 s60, s60, 0x100
	s_addc_u32 s61, s61, 0
	s_cmp_lt_u32 s38, 28
	s_cbranch_scc1 .Lh1_loop
	ds_read_b128 v[140:143], v129
	ds_read_b128 v[144:147], v129 offset:1024
	ds_read_b128 v[148:151], v129 offset:2048
	ds_read_b128 v[152:155], v129 offset:3072
	ds_read_b128 v[156:159], v136
	ds_read_b128 v[160:163], v136 offset:1024
	ds_read_b128 v[164:167], v135
	ds_read_b128 v[168:171], v135 offset:1024
	ds_read_b128 v[172:175], v134
	ds_read_b128 v[176:179], v134 offset:1024
	ds_read_b128 v[180:183], v133
	ds_read_b128 v[184:187], v133 offset:1024
	v_mov_b32_e32 v129, v197
	v_lshl_add_u64 v[128:129], s[58:59], 0, v[128:129]
	s_mov_b64 s[28:29], 0xf80
	s_mov_b32 m0, s40
	v_lshl_add_u64 v[128:129], v[128:129], 0, s[28:29]
	v_mov_b32_e32 v131, v197
	v_lshl_add_u64 v[128:129], s[58:59], 0, v[130:131]
	v_lshl_add_u64 v[128:129], v[128:129], 0, s[28:29]
	s_mov_b32 m0, s39
	s_nop 0
	s_barrier
	s_waitcnt lgkmcnt(0)
	s_setprio 1
	s_waitcnt lgkmcnt(0)
	v_mfma_f32_16x16x32_bf16 v[124:127], v[140:143], v[156:159], v[124:127]
	v_mfma_f32_16x16x32_bf16 v[120:123], v[148:151], v[156:159], v[120:123]
	v_mfma_f32_16x16x32_bf16 v[116:119], v[140:143], v[164:167], v[116:119]
	v_mfma_f32_16x16x32_bf16 v[112:115], v[148:151], v[164:167], v[112:115]
	v_mfma_f32_16x16x32_bf16 v[108:111], v[140:143], v[172:175], v[108:111]
	v_mfma_f32_16x16x32_bf16 v[100:103], v[140:143], v[180:183], v[100:103]
	v_mfma_f32_16x16x32_bf16 v[96:99], v[148:151], v[180:183], v[96:99]
	v_mfma_f32_16x16x32_bf16 v[124:127], v[144:147], v[160:163], v[124:127]
	v_mfma_f32_16x16x32_bf16 v[120:123], v[152:155], v[160:163], v[120:123]
	v_mfma_f32_16x16x32_bf16 v[116:119], v[144:147], v[168:171], v[116:119]
	v_mfma_f32_16x16x32_bf16 v[112:115], v[152:155], v[168:171], v[112:115]
	v_mfma_f32_16x16x32_bf16 v[108:111], v[144:147], v[176:179], v[108:111]
	v_mfma_f32_16x16x32_bf16 v[104:107], v[148:151], v[172:175], v[104:107]
	v_mfma_f32_16x16x32_bf16 v[100:103], v[144:147], v[184:187], v[100:103]
	v_mfma_f32_16x16x32_bf16 v[96:99], v[152:155], v[184:187], v[96:99]
	v_mfma_f32_16x16x32_bf16 v[128:131], v[152:155], v[176:179], v[104:107]
	s_setprio 0
	s_barrier
	s_nop 2
	ds_read_b128 v[104:107], v139
	ds_read_b128 v[188:191], v139 offset:1024
	ds_read_b128 v[192:195], v139 offset:2048
	ds_read_b128 v[202:205], v139 offset:3072
	s_barrier
	s_waitcnt lgkmcnt(0)
	s_setprio 1
	s_waitcnt lgkmcnt(0)
	v_mfma_f32_16x16x32_bf16 v[92:95], v[104:107], v[156:159], v[92:95]
	v_mfma_f32_16x16x32_bf16 v[84:87], v[104:107], v[164:167], v[84:87]
	v_mfma_f32_16x16x32_bf16 v[76:79], v[104:107], v[172:175], v[76:79]
	v_mfma_f32_16x16x32_bf16 v[68:71], v[104:107], v[180:183], v[68:71]
	v_mfma_f32_16x16x32_bf16 v[64:67], v[192:195], v[180:183], v[64:67]
	v_mfma_f32_16x16x32_bf16 v[92:95], v[188:191], v[160:163], v[92:95]
	v_mfma_f32_16x16x32_bf16 v[88:91], v[192:195], v[156:159], v[88:91]
	v_mfma_f32_16x16x32_bf16 v[84:87], v[188:191], v[168:171], v[84:87]
	v_mfma_f32_16x16x32_bf16 v[80:83], v[192:195], v[164:167], v[80:83]
	v_mfma_f32_16x16x32_bf16 v[76:79], v[188:191], v[176:179], v[76:79]
	v_mfma_f32_16x16x32_bf16 v[72:75], v[192:195], v[172:175], v[72:75]
	v_mfma_f32_16x16x32_bf16 v[68:71], v[188:191], v[184:187], v[68:71]
	v_mfma_f32_16x16x32_bf16 v[64:67], v[202:205], v[184:187], v[64:67]
	v_mfma_f32_16x16x32_bf16 v[156:159], v[202:205], v[160:163], v[88:91]
	v_mfma_f32_16x16x32_bf16 v[160:163], v[202:205], v[168:171], v[80:83]
	v_mfma_f32_16x16x32_bf16 v[164:167], v[202:205], v[176:179], v[72:75]
	s_setprio 0
	s_barrier
	s_nop 0
	s_waitcnt vmcnt(2)
	s_barrier
	s_waitcnt lgkmcnt(0)
	s_setprio 1
	s_waitcnt lgkmcnt(0)
	s_setprio 0
	s_setprio 1
	s_setprio 0
	s_barrier
	ds_read_b128 v[16:19], v138
	ds_read_b128 v[180:183], v138 offset:1024
	ds_read_b128 v[184:187], v138 offset:2048
	ds_read_b128 v[188:191], v138 offset:3072
	ds_read_b128 v[0:3], v136 offset:32768
	ds_read_b128 v[4:7], v136 offset:33792
	ds_read_b128 v[8:11], v135 offset:32768
	ds_read_b128 v[12:15], v135 offset:33792
	ds_read_b128 v[44:47], v134 offset:32768
	ds_read_b128 v[192:195], v134 offset:33792
	ds_read_b128 v[202:205], v133 offset:32768
	ds_read_b128 v[218:221], v133 offset:33792
	s_waitcnt vmcnt(0)
	s_barrier
	s_waitcnt lgkmcnt(0)
	s_setprio 1
	s_waitcnt lgkmcnt(0)
	v_mfma_f32_16x16x32_bf16 v[28:31], v[16:19], v[0:3], v[124:127]
	v_mfma_f32_16x16x32_bf16 v[52:55], v[180:183], v[4:7], v[28:31]
	v_mfma_f32_16x16x32_bf16 v[28:31], v[184:187], v[0:3], v[120:123]
	v_mfma_f32_16x16x32_bf16 v[104:107], v[188:191], v[4:7], v[28:31]
	v_mfma_f32_16x16x32_bf16 v[28:31], v[16:19], v[8:11], v[116:119]
	v_mfma_f32_16x16x32_bf16 v[72:75], v[180:183], v[12:15], v[28:31]
	v_mfma_f32_16x16x32_bf16 v[28:31], v[184:187], v[8:11], v[112:115]
	v_mfma_f32_16x16x32_bf16 v[116:119], v[188:191], v[12:15], v[28:31]
	v_mfma_f32_16x16x32_bf16 v[28:31], v[16:19], v[44:47], v[108:111]
	v_mfma_f32_16x16x32_bf16 v[80:83], v[180:183], v[192:195], v[28:31]
	v_mfma_f32_16x16x32_bf16 v[28:31], v[184:187], v[44:47], v[128:131]
	v_mfma_f32_16x16x32_bf16 v[108:111], v[188:191], v[192:195], v[28:31]
	v_mfma_f32_16x16x32_bf16 v[28:31], v[16:19], v[202:205], v[100:103]
	v_mfma_f32_16x16x32_bf16 v[88:91], v[180:183], v[218:221], v[28:31]
	v_mfma_f32_16x16x32_bf16 v[28:31], v[184:187], v[202:205], v[96:99]
	v_mfma_f32_16x16x32_bf16 v[96:99], v[188:191], v[218:221], v[28:31]
	s_setprio 0
	s_barrier
	ds_read_b128 v[128:131], v137
	ds_read_b128 v[222:225], v137 offset:1024
	ds_read_b128 v[228:231], v137 offset:2048
	ds_read_b128 v[232:235], v137 offset:3072
	s_waitcnt vmcnt(0)
	s_barrier
	s_waitcnt lgkmcnt(0)
	s_setprio 1
	s_waitcnt lgkmcnt(0)
	v_mfma_f32_16x16x32_bf16 v[28:31], v[128:131], v[0:3], v[92:95]
	v_mfma_f32_16x16x32_bf16 v[0:3], v[228:231], v[0:3], v[156:159]
	v_mfma_f32_16x16x32_bf16 v[28:31], v[222:225], v[4:7], v[28:31]
	v_mfma_f32_16x16x32_bf16 v[0:3], v[232:235], v[4:7], v[0:3]
	v_mfma_f32_16x16x32_bf16 v[4:7], v[128:131], v[8:11], v[84:87]
	v_mfma_f32_16x16x32_bf16 v[36:39], v[222:225], v[12:15], v[4:7]
	v_mfma_f32_16x16x32_bf16 v[4:7], v[228:231], v[8:11], v[160:163]
	v_mfma_f32_16x16x32_bf16 v[4:7], v[232:235], v[12:15], v[4:7]
	v_mfma_f32_16x16x32_bf16 v[8:11], v[128:131], v[44:47], v[76:79]
	v_mfma_f32_16x16x32_bf16 v[12:15], v[128:131], v[202:205], v[68:71]
	v_mfma_f32_16x16x32_bf16 v[40:43], v[222:225], v[192:195], v[8:11]
	v_mfma_f32_16x16x32_bf16 v[8:11], v[228:231], v[44:47], v[164:167]
	v_mfma_f32_16x16x32_bf16 v[44:47], v[222:225], v[218:221], v[12:15]
	v_mfma_f32_16x16x32_bf16 v[12:15], v[228:231], v[202:205], v[64:67]
	v_mfma_f32_16x16x32_bf16 v[8:11], v[232:235], v[192:195], v[8:11]
	v_mfma_f32_16x16x32_bf16 v[12:15], v[232:235], v[218:221], v[12:15]
	s_setprio 0
	s_barrier
	s_barrier
	s_waitcnt lgkmcnt(0)
	s_setprio 1
	s_waitcnt lgkmcnt(0)
	s_setprio 0
	s_setprio 1
	s_setprio 0
	s_movk_i32 s9, 0x100
	v_cmp_gt_u32_e32 vcc, s9, v132
	s_barrier
	s_and_saveexec_b64 s[28:29], vcc
	s_cbranch_execz .Lh1_epi
	s_barrier

.LBB0_255:
	ds_read_b128 v[140:143], v129
	ds_read_b128 v[144:147], v129 offset:1024
	ds_read_b128 v[148:151], v129 offset:2048
	ds_read_b128 v[152:155], v129 offset:3072
	s_add_u32 s28, s60, s56
	s_addc_u32 s29, s61, s57
	ds_read_b128 v[156:159], v136
	ds_read_b128 v[160:163], v136 offset:1024
	ds_read_b128 v[164:167], v135
	ds_read_b128 v[168:171], v135 offset:1024
	ds_read_b128 v[172:175], v134
	ds_read_b128 v[176:179], v134 offset:1024
	ds_read_b128 v[180:183], v133
	ds_read_b128 v[184:187], v133 offset:1024
	s_add_i32 s40, s53, 0xc000
	s_mov_b32 m0, s40
	s_add_i32 s39, s53, 0xe000
	s_add_u32 s98, s28, s44
	s_addc_u32 s99, s29, s45
	global_load_lds_dwordx4 v128, s[98:99]
	s_mov_b32 m0, s39
	s_nop 0
	global_load_lds_dwordx4 v130, s[98:99]
	s_waitcnt lgkmcnt(8)
	s_barrier
	s_waitcnt lgkmcnt(0)
	s_waitcnt lgkmcnt(0)
	v_mfma_f32_16x16x32_bf16 v[124:127], v[140:143], v[156:159], v[124:127]
	v_mfma_f32_16x16x32_bf16 v[120:123], v[148:151], v[156:159], v[120:123]
	v_mfma_f32_16x16x32_bf16 v[116:119], v[140:143], v[164:167], v[116:119]
	v_mfma_f32_16x16x32_bf16 v[112:115], v[148:151], v[164:167], v[112:115]
	v_mfma_f32_16x16x32_bf16 v[108:111], v[140:143], v[172:175], v[108:111]
	v_mfma_f32_16x16x32_bf16 v[104:107], v[148:151], v[172:175], v[104:107]
	v_mfma_f32_16x16x32_bf16 v[100:103], v[140:143], v[180:183], v[100:103]
	v_mfma_f32_16x16x32_bf16 v[96:99], v[148:151], v[180:183], v[96:99]
	v_mfma_f32_16x16x32_bf16 v[124:127], v[144:147], v[160:163], v[124:127]
	v_mfma_f32_16x16x32_bf16 v[120:123], v[152:155], v[160:163], v[120:123]
	v_mfma_f32_16x16x32_bf16 v[116:119], v[144:147], v[168:171], v[116:119]
	v_mfma_f32_16x16x32_bf16 v[112:115], v[152:155], v[168:171], v[112:115]
	v_mfma_f32_16x16x32_bf16 v[108:111], v[144:147], v[176:179], v[108:111]
	v_mfma_f32_16x16x32_bf16 v[104:107], v[152:155], v[176:179], v[104:107]
	v_mfma_f32_16x16x32_bf16 v[100:103], v[144:147], v[184:187], v[100:103]
	v_mfma_f32_16x16x32_bf16 v[96:99], v[152:155], v[184:187], v[96:99]
	s_barrier
	s_add_u32 s62, s60, s36
	s_addc_u32 s63, s61, s37
	ds_read_b128 v[188:191], v139
	ds_read_b128 v[192:195], v139 offset:1024
	ds_read_b128 v[202:205], v139 offset:2048
	ds_read_b128 v[206:209], v139 offset:3072
	s_mov_b32 m0, s68
	s_add_u32 s98, s62, s46
	s_addc_u32 s99, s63, s47
	global_load_lds_dwordx4 v128, s[98:99]
	s_mov_b32 m0, s69
	s_nop 0
	global_load_lds_dwordx4 v130, s[98:99]
	s_barrier
	s_waitcnt lgkmcnt(0)
	s_waitcnt lgkmcnt(0)
	v_mfma_f32_16x16x32_bf16 v[92:95], v[188:191], v[156:159], v[92:95]
	v_mfma_f32_16x16x32_bf16 v[88:91], v[202:205], v[156:159], v[88:91]
	v_mfma_f32_16x16x32_bf16 v[84:87], v[188:191], v[164:167], v[84:87]
	v_mfma_f32_16x16x32_bf16 v[80:83], v[202:205], v[164:167], v[80:83]
	v_mfma_f32_16x16x32_bf16 v[76:79], v[188:191], v[172:175], v[76:79]
	v_mfma_f32_16x16x32_bf16 v[72:75], v[202:205], v[172:175], v[72:75]
	v_mfma_f32_16x16x32_bf16 v[68:71], v[188:191], v[180:183], v[68:71]
	v_mfma_f32_16x16x32_bf16 v[64:67], v[202:205], v[180:183], v[64:67]
	v_mfma_f32_16x16x32_bf16 v[92:95], v[192:195], v[160:163], v[92:95]
	v_mfma_f32_16x16x32_bf16 v[88:91], v[206:209], v[160:163], v[88:91]
	v_mfma_f32_16x16x32_bf16 v[84:87], v[192:195], v[168:171], v[84:87]
	v_mfma_f32_16x16x32_bf16 v[80:83], v[206:209], v[168:171], v[80:83]
	v_mfma_f32_16x16x32_bf16 v[76:79], v[192:195], v[176:179], v[76:79]
	v_mfma_f32_16x16x32_bf16 v[72:75], v[206:209], v[176:179], v[72:75]
	v_mfma_f32_16x16x32_bf16 v[68:71], v[192:195], v[184:187], v[68:71]
	v_mfma_f32_16x16x32_bf16 v[64:67], v[206:209], v[184:187], v[64:67]
	s_barrier
	ds_read_b128 v[156:159], v136 offset:16384
	ds_read_b128 v[160:163], v136 offset:17408
	ds_read_b128 v[164:167], v135 offset:16384
	ds_read_b128 v[168:171], v135 offset:17408
	ds_read_b128 v[172:175], v134 offset:16384
	ds_read_b128 v[176:179], v134 offset:17408
	ds_read_b128 v[180:183], v133 offset:16384
	ds_read_b128 v[184:187], v133 offset:17408
	s_mov_b32 m0, s53
	s_add_u32 s98, s28, s48
	s_addc_u32 s99, s29, s49
	global_load_lds_dwordx4 v128, s[98:99]
	s_mov_b32 m0, s11
	s_nop 0
	global_load_lds_dwordx4 v130, s[98:99]
	s_barrier
	s_waitcnt lgkmcnt(0)
	s_waitcnt lgkmcnt(0)
	v_mfma_f32_16x16x32_bf16 v[60:63], v[140:143], v[156:159], v[60:63]
	v_mfma_f32_16x16x32_bf16 v[56:59], v[148:151], v[156:159], v[56:59]
	v_mfma_f32_16x16x32_bf16 v[52:55], v[140:143], v[164:167], v[52:55]
	v_mfma_f32_16x16x32_bf16 v[48:51], v[148:151], v[164:167], v[48:51]
	v_mfma_f32_16x16x32_bf16 v[44:47], v[140:143], v[172:175], v[44:47]
	v_mfma_f32_16x16x32_bf16 v[40:43], v[148:151], v[172:175], v[40:43]
	v_mfma_f32_16x16x32_bf16 v[36:39], v[140:143], v[180:183], v[36:39]
	v_mfma_f32_16x16x32_bf16 v[32:35], v[148:151], v[180:183], v[32:35]
	v_mfma_f32_16x16x32_bf16 v[60:63], v[144:147], v[160:163], v[60:63]
	v_mfma_f32_16x16x32_bf16 v[56:59], v[152:155], v[160:163], v[56:59]
	v_mfma_f32_16x16x32_bf16 v[52:55], v[144:147], v[168:171], v[52:55]
	v_mfma_f32_16x16x32_bf16 v[48:51], v[152:155], v[168:171], v[48:51]
	v_mfma_f32_16x16x32_bf16 v[44:47], v[144:147], v[176:179], v[44:47]
	v_mfma_f32_16x16x32_bf16 v[40:43], v[152:155], v[176:179], v[40:43]
	v_mfma_f32_16x16x32_bf16 v[36:39], v[144:147], v[184:187], v[36:39]
	v_mfma_f32_16x16x32_bf16 v[32:35], v[152:155], v[184:187], v[32:35]
	s_barrier
	s_mov_b32 m0, s9
	s_add_u32 s98, s62, s50
	s_addc_u32 s99, s63, s51
	global_load_lds_dwordx4 v128, s[98:99]
	s_mov_b32 m0, s70
	s_nop 0
	global_load_lds_dwordx4 v130, s[98:99]
	s_waitcnt vmcnt(6)
	s_barrier
	v_mfma_f32_16x16x32_bf16 v[28:31], v[188:191], v[156:159], v[28:31]
	v_mfma_f32_16x16x32_bf16 v[24:27], v[202:205], v[156:159], v[24:27]
	v_mfma_f32_16x16x32_bf16 v[20:23], v[188:191], v[164:167], v[20:23]
	v_mfma_f32_16x16x32_bf16 v[16:19], v[202:205], v[164:167], v[16:19]
	v_mfma_f32_16x16x32_bf16 v[12:15], v[188:191], v[172:175], v[12:15]
	v_mfma_f32_16x16x32_bf16 v[8:11], v[202:205], v[172:175], v[8:11]
	v_mfma_f32_16x16x32_bf16 v[4:7], v[188:191], v[180:183], v[4:7]
	v_mfma_f32_16x16x32_bf16 v[0:3], v[202:205], v[180:183], v[0:3]
	v_mfma_f32_16x16x32_bf16 v[28:31], v[192:195], v[160:163], v[28:31]
	v_mfma_f32_16x16x32_bf16 v[24:27], v[206:209], v[160:163], v[24:27]
	v_mfma_f32_16x16x32_bf16 v[20:23], v[192:195], v[168:171], v[20:23]
	v_mfma_f32_16x16x32_bf16 v[16:19], v[206:209], v[168:171], v[16:19]
	v_mfma_f32_16x16x32_bf16 v[12:15], v[192:195], v[176:179], v[12:15]
	v_mfma_f32_16x16x32_bf16 v[8:11], v[206:209], v[176:179], v[8:11]
	v_mfma_f32_16x16x32_bf16 v[4:7], v[192:195], v[184:187], v[4:7]
	v_mfma_f32_16x16x32_bf16 v[0:3], v[206:209], v[184:187], v[0:3]
	s_barrier
	ds_read_b128 v[140:143], v138
	ds_read_b128 v[144:147], v138 offset:1024
	ds_read_b128 v[148:151], v138 offset:2048
	ds_read_b128 v[152:155], v138 offset:3072
	ds_read_b128 v[156:159], v136 offset:32768
	ds_read_b128 v[160:163], v136 offset:33792
	ds_read_b128 v[164:167], v135 offset:32768
	ds_read_b128 v[168:171], v135 offset:33792
	ds_read_b128 v[172:175], v134 offset:32768
	ds_read_b128 v[176:179], v134 offset:33792
	ds_read_b128 v[180:183], v133 offset:32768
	ds_read_b128 v[184:187], v133 offset:33792
	s_mov_b32 m0, s71
	s_add_u32 s98, s28, s74
	s_addc_u32 s99, s29, s75
	global_load_lds_dwordx4 v128, s[98:99]
	s_mov_b32 m0, s72
	s_nop 0
	global_load_lds_dwordx4 v130, s[98:99]
	s_waitcnt lgkmcnt(8)
	s_barrier
	s_waitcnt lgkmcnt(0)
	s_waitcnt lgkmcnt(0)
	v_mfma_f32_16x16x32_bf16 v[124:127], v[140:143], v[156:159], v[124:127]
	v_mfma_f32_16x16x32_bf16 v[120:123], v[148:151], v[156:159], v[120:123]
	v_mfma_f32_16x16x32_bf16 v[116:119], v[140:143], v[164:167], v[116:119]
	v_mfma_f32_16x16x32_bf16 v[112:115], v[148:151], v[164:167], v[112:115]
	v_mfma_f32_16x16x32_bf16 v[108:111], v[140:143], v[172:175], v[108:111]
	v_mfma_f32_16x16x32_bf16 v[104:107], v[148:151], v[172:175], v[104:107]
	v_mfma_f32_16x16x32_bf16 v[100:103], v[140:143], v[180:183], v[100:103]
	v_mfma_f32_16x16x32_bf16 v[96:99], v[148:151], v[180:183], v[96:99]
	v_mfma_f32_16x16x32_bf16 v[124:127], v[144:147], v[160:163], v[124:127]
	v_mfma_f32_16x16x32_bf16 v[120:123], v[152:155], v[160:163], v[120:123]
	v_mfma_f32_16x16x32_bf16 v[116:119], v[144:147], v[168:171], v[116:119]
	v_mfma_f32_16x16x32_bf16 v[112:115], v[152:155], v[168:171], v[112:115]
	v_mfma_f32_16x16x32_bf16 v[108:111], v[144:147], v[176:179], v[108:111]
	v_mfma_f32_16x16x32_bf16 v[104:107], v[152:155], v[176:179], v[104:107]
	v_mfma_f32_16x16x32_bf16 v[100:103], v[144:147], v[184:187], v[100:103]
	v_mfma_f32_16x16x32_bf16 v[96:99], v[152:155], v[184:187], v[96:99]
	s_barrier
	ds_read_b128 v[188:191], v137
	ds_read_b128 v[192:195], v137 offset:1024
	ds_read_b128 v[202:205], v137 offset:2048
	ds_read_b128 v[206:209], v137 offset:3072
	s_mov_b32 m0, s66
	s_add_u32 s98, s62, s90
	s_addc_u32 s99, s63, s91
	global_load_lds_dwordx4 v128, s[98:99]
	s_mov_b32 m0, s64
	s_nop 0
	global_load_lds_dwordx4 v130, s[98:99]
	s_barrier
	s_waitcnt lgkmcnt(0)
	s_waitcnt lgkmcnt(0)
	v_mfma_f32_16x16x32_bf16 v[92:95], v[188:191], v[156:159], v[92:95]
	v_mfma_f32_16x16x32_bf16 v[88:91], v[202:205], v[156:159], v[88:91]
	v_mfma_f32_16x16x32_bf16 v[84:87], v[188:191], v[164:167], v[84:87]
	v_mfma_f32_16x16x32_bf16 v[80:83], v[202:205], v[164:167], v[80:83]
	v_mfma_f32_16x16x32_bf16 v[76:79], v[188:191], v[172:175], v[76:79]
	v_mfma_f32_16x16x32_bf16 v[72:75], v[202:205], v[172:175], v[72:75]
	v_mfma_f32_16x16x32_bf16 v[68:71], v[188:191], v[180:183], v[68:71]
	v_mfma_f32_16x16x32_bf16 v[64:67], v[202:205], v[180:183], v[64:67]
	v_mfma_f32_16x16x32_bf16 v[92:95], v[192:195], v[160:163], v[92:95]
	v_mfma_f32_16x16x32_bf16 v[88:91], v[206:209], v[160:163], v[88:91]
	v_mfma_f32_16x16x32_bf16 v[84:87], v[192:195], v[168:171], v[84:87]
	v_mfma_f32_16x16x32_bf16 v[80:83], v[206:209], v[168:171], v[80:83]
	v_mfma_f32_16x16x32_bf16 v[76:79], v[192:195], v[176:179], v[76:79]
	v_mfma_f32_16x16x32_bf16 v[72:75], v[206:209], v[176:179], v[72:75]
	v_mfma_f32_16x16x32_bf16 v[68:71], v[192:195], v[184:187], v[68:71]
	v_mfma_f32_16x16x32_bf16 v[64:67], v[206:209], v[184:187], v[64:67]
	v_mov_b32_e32 v210, v130
	s_barrier
	ds_read_b128 v[156:159], v136 offset:49152
	ds_read_b128 v[160:163], v136 offset:50176
	ds_read_b128 v[164:167], v135 offset:49152
	ds_read_b128 v[168:171], v135 offset:50176
	ds_read_b128 v[172:175], v134 offset:49152
	ds_read_b128 v[176:179], v134 offset:50176
	ds_read_b128 v[180:183], v133 offset:49152
	ds_read_b128 v[184:187], v133 offset:50176
	v_mov_b32_e32 v211, v197
	s_mov_b32 m0, s65
	s_add_u32 s98, s28, s92
	s_addc_u32 s99, s29, s93
	global_load_lds_dwordx4 v128, s[98:99]
	s_mov_b32 m0, s67
	s_nop 0
	global_load_lds_dwordx4 v130, s[98:99]
	s_barrier
	s_waitcnt lgkmcnt(0)
	s_waitcnt lgkmcnt(0)
	v_mfma_f32_16x16x32_bf16 v[60:63], v[140:143], v[156:159], v[60:63]
	v_mfma_f32_16x16x32_bf16 v[56:59], v[148:151], v[156:159], v[56:59]
	v_mfma_f32_16x16x32_bf16 v[52:55], v[140:143], v[164:167], v[52:55]
	v_mfma_f32_16x16x32_bf16 v[48:51], v[148:151], v[164:167], v[48:51]
	v_mfma_f32_16x16x32_bf16 v[44:47], v[140:143], v[172:175], v[44:47]
	v_mfma_f32_16x16x32_bf16 v[40:43], v[148:151], v[172:175], v[40:43]
	v_mfma_f32_16x16x32_bf16 v[36:39], v[140:143], v[180:183], v[36:39]
	v_mfma_f32_16x16x32_bf16 v[32:35], v[148:151], v[180:183], v[32:35]
	v_mfma_f32_16x16x32_bf16 v[60:63], v[144:147], v[160:163], v[60:63]
	v_mfma_f32_16x16x32_bf16 v[56:59], v[152:155], v[160:163], v[56:59]
	v_mfma_f32_16x16x32_bf16 v[52:55], v[144:147], v[168:171], v[52:55]
	v_mfma_f32_16x16x32_bf16 v[48:51], v[152:155], v[168:171], v[48:51]
	v_mfma_f32_16x16x32_bf16 v[44:47], v[144:147], v[176:179], v[44:47]
	v_mfma_f32_16x16x32_bf16 v[40:43], v[152:155], v[176:179], v[40:43]
	v_mfma_f32_16x16x32_bf16 v[36:39], v[144:147], v[184:187], v[36:39]
	v_mfma_f32_16x16x32_bf16 v[32:35], v[152:155], v[184:187], v[32:35]
	s_barrier
	v_mov_b32_e32 v196, v128
	s_mov_b32 m0, s33
	s_add_u32 s98, s62, s96
	s_addc_u32 s99, s63, s97
	global_load_lds_dwordx4 v128, s[98:99]
	s_mov_b32 m0, s73
	s_nop 0
	global_load_lds_dwordx4 v130, s[98:99]
	s_waitcnt vmcnt(6)
	s_barrier
	v_mfma_f32_16x16x32_bf16 v[28:31], v[188:191], v[156:159], v[28:31]
	v_mfma_f32_16x16x32_bf16 v[24:27], v[202:205], v[156:159], v[24:27]
	v_mfma_f32_16x16x32_bf16 v[20:23], v[188:191], v[164:167], v[20:23]
	v_mfma_f32_16x16x32_bf16 v[16:19], v[202:205], v[164:167], v[16:19]
	v_mfma_f32_16x16x32_bf16 v[12:15], v[188:191], v[172:175], v[12:15]
	v_mfma_f32_16x16x32_bf16 v[8:11], v[202:205], v[172:175], v[8:11]
	v_mfma_f32_16x16x32_bf16 v[4:7], v[188:191], v[180:183], v[4:7]
	v_mfma_f32_16x16x32_bf16 v[0:3], v[202:205], v[180:183], v[0:3]
	v_mfma_f32_16x16x32_bf16 v[28:31], v[192:195], v[160:163], v[28:31]
	v_mfma_f32_16x16x32_bf16 v[24:27], v[206:209], v[160:163], v[24:27]
	v_mfma_f32_16x16x32_bf16 v[20:23], v[192:195], v[168:171], v[20:23]
	v_mfma_f32_16x16x32_bf16 v[16:19], v[206:209], v[168:171], v[16:19]
	v_mfma_f32_16x16x32_bf16 v[12:15], v[192:195], v[176:179], v[12:15]
	v_mfma_f32_16x16x32_bf16 v[8:11], v[206:209], v[176:179], v[8:11]
	v_mfma_f32_16x16x32_bf16 v[4:7], v[192:195], v[184:187], v[4:7]
	v_mfma_f32_16x16x32_bf16 v[0:3], v[206:209], v[184:187], v[0:3]
	s_add_i32 s38, s38, 2
	s_add_u32 s60, s60, 0x100
	s_addc_u32 s61, s61, 0
	s_cmp_lt_u32 s38, 28
	s_barrier
	s_cbranch_scc1 .LBB0_255
	ds_read_b128 v[140:143], v129
	ds_read_b128 v[144:147], v129 offset:1024
	ds_read_b128 v[148:151], v129 offset:2048
	ds_read_b128 v[152:155], v129 offset:3072
	ds_read_b128 v[156:159], v136
	ds_read_b128 v[160:163], v136 offset:1024
	ds_read_b128 v[164:167], v135
	ds_read_b128 v[168:171], v135 offset:1024
	ds_read_b128 v[172:175], v134
	ds_read_b128 v[176:179], v134 offset:1024
	ds_read_b128 v[180:183], v133
	ds_read_b128 v[184:187], v133 offset:1024
	v_mov_b32_e32 v129, v197
	v_lshl_add_u64 v[128:129], s[58:59], 0, v[128:129]
	s_mov_b64 s[28:29], 0xf80
	s_mov_b32 m0, s40
	v_lshl_add_u64 v[128:129], v[128:129], 0, s[28:29]
	v_mov_b32_e32 v131, v197
	global_load_lds_dwordx4 v[128:129], off
	v_lshl_add_u64 v[128:129], s[58:59], 0, v[130:131]
	v_lshl_add_u64 v[128:129], v[128:129], 0, s[28:29]
	s_mov_b32 m0, s39
	s_nop 0
	global_load_lds_dwordx4 v[128:129], off
	s_barrier
	s_waitcnt lgkmcnt(0)
	s_setprio 1
	s_waitcnt lgkmcnt(0)
	v_mfma_f32_16x16x32_bf16 v[124:127], v[140:143], v[156:159], v[124:127]
	v_mfma_f32_16x16x32_bf16 v[120:123], v[148:151], v[156:159], v[120:123]
	v_mfma_f32_16x16x32_bf16 v[116:119], v[140:143], v[164:167], v[116:119]
	v_mfma_f32_16x16x32_bf16 v[112:115], v[148:151], v[164:167], v[112:115]
	v_mfma_f32_16x16x32_bf16 v[108:111], v[140:143], v[172:175], v[108:111]
	v_mfma_f32_16x16x32_bf16 v[100:103], v[140:143], v[180:183], v[100:103]
	v_mfma_f32_16x16x32_bf16 v[96:99], v[148:151], v[180:183], v[96:99]
	v_mfma_f32_16x16x32_bf16 v[124:127], v[144:147], v[160:163], v[124:127]
	v_mfma_f32_16x16x32_bf16 v[120:123], v[152:155], v[160:163], v[120:123]
	v_mfma_f32_16x16x32_bf16 v[116:119], v[144:147], v[168:171], v[116:119]
	v_mfma_f32_16x16x32_bf16 v[112:115], v[152:155], v[168:171], v[112:115]
	v_mfma_f32_16x16x32_bf16 v[108:111], v[144:147], v[176:179], v[108:111]
	v_mfma_f32_16x16x32_bf16 v[104:107], v[148:151], v[172:175], v[104:107]
	v_mfma_f32_16x16x32_bf16 v[100:103], v[144:147], v[184:187], v[100:103]
	v_mfma_f32_16x16x32_bf16 v[96:99], v[152:155], v[184:187], v[96:99]
	v_mfma_f32_16x16x32_bf16 v[128:131], v[152:155], v[176:179], v[104:107]
	s_setprio 0
	s_barrier
	s_nop 2
	ds_read_b128 v[104:107], v139
	ds_read_b128 v[188:191], v139 offset:1024
	ds_read_b128 v[192:195], v139 offset:2048
	ds_read_b128 v[202:205], v139 offset:3072
	s_barrier
	s_waitcnt lgkmcnt(0)
	s_setprio 1
	s_waitcnt lgkmcnt(0)
	v_mfma_f32_16x16x32_bf16 v[92:95], v[104:107], v[156:159], v[92:95]
	v_mfma_f32_16x16x32_bf16 v[84:87], v[104:107], v[164:167], v[84:87]
	v_mfma_f32_16x16x32_bf16 v[76:79], v[104:107], v[172:175], v[76:79]
	v_mfma_f32_16x16x32_bf16 v[68:71], v[104:107], v[180:183], v[68:71]
	v_mfma_f32_16x16x32_bf16 v[64:67], v[192:195], v[180:183], v[64:67]
	v_mfma_f32_16x16x32_bf16 v[92:95], v[188:191], v[160:163], v[92:95]
	v_mfma_f32_16x16x32_bf16 v[88:91], v[192:195], v[156:159], v[88:91]
	v_mfma_f32_16x16x32_bf16 v[84:87], v[188:191], v[168:171], v[84:87]
	v_mfma_f32_16x16x32_bf16 v[80:83], v[192:195], v[164:167], v[80:83]
	v_mfma_f32_16x16x32_bf16 v[76:79], v[188:191], v[176:179], v[76:79]
	v_mfma_f32_16x16x32_bf16 v[72:75], v[192:195], v[172:175], v[72:75]
	v_mfma_f32_16x16x32_bf16 v[68:71], v[188:191], v[184:187], v[68:71]
	v_mfma_f32_16x16x32_bf16 v[64:67], v[202:205], v[184:187], v[64:67]
	v_mfma_f32_16x16x32_bf16 v[156:159], v[202:205], v[160:163], v[88:91]
	v_mfma_f32_16x16x32_bf16 v[160:163], v[202:205], v[168:171], v[80:83]
	v_mfma_f32_16x16x32_bf16 v[164:167], v[202:205], v[176:179], v[72:75]
	s_setprio 0
	s_barrier
	s_nop 0
	ds_read_b128 v[72:75], v136 offset:16384
	ds_read_b128 v[80:83], v136 offset:17408
	ds_read_b128 v[88:91], v135 offset:16384
	ds_read_b128 v[168:171], v135 offset:17408
	ds_read_b128 v[172:175], v134 offset:16384
	ds_read_b128 v[176:179], v134 offset:17408
	ds_read_b128 v[180:183], v133 offset:16384
	ds_read_b128 v[184:187], v133 offset:17408
	s_waitcnt vmcnt(4)
	s_barrier
	s_waitcnt lgkmcnt(0)
	s_setprio 1
	s_waitcnt lgkmcnt(0)
	v_mfma_f32_16x16x32_bf16 v[60:63], v[140:143], v[72:75], v[60:63]
	v_mfma_f32_16x16x32_bf16 v[56:59], v[148:151], v[72:75], v[56:59]
	v_mfma_f32_16x16x32_bf16 v[48:51], v[148:151], v[88:91], v[48:51]
	v_mfma_f32_16x16x32_bf16 v[32:35], v[148:151], v[180:183], v[32:35]
	v_mfma_f32_16x16x32_bf16 v[60:63], v[144:147], v[80:83], v[60:63]
	v_mfma_f32_16x16x32_bf16 v[56:59], v[152:155], v[80:83], v[56:59]
	v_mfma_f32_16x16x32_bf16 v[52:55], v[140:143], v[88:91], v[52:55]
	v_mfma_f32_16x16x32_bf16 v[48:51], v[152:155], v[168:171], v[48:51]
	v_mfma_f32_16x16x32_bf16 v[44:47], v[140:143], v[172:175], v[44:47]
	v_mfma_f32_16x16x32_bf16 v[40:43], v[148:151], v[172:175], v[40:43]
	v_mfma_f32_16x16x32_bf16 v[36:39], v[140:143], v[180:183], v[36:39]
	v_mfma_f32_16x16x32_bf16 v[32:35], v[152:155], v[184:187], v[32:35]
	v_mfma_f32_16x16x32_bf16 v[206:209], v[144:147], v[168:171], v[52:55]
	v_mfma_f32_16x16x32_bf16 v[210:213], v[144:147], v[176:179], v[44:47]
	v_mfma_f32_16x16x32_bf16 v[214:217], v[152:155], v[176:179], v[40:43]
	v_mfma_f32_16x16x32_bf16 v[140:143], v[144:147], v[184:187], v[36:39]
	s_setprio 0
	s_setprio 1
	v_mfma_f32_16x16x32_bf16 v[24:27], v[192:195], v[72:75], v[24:27]
	v_mfma_f32_16x16x32_bf16 v[20:23], v[104:107], v[88:91], v[20:23]
	v_mfma_f32_16x16x32_bf16 v[28:31], v[104:107], v[72:75], v[28:31]
	v_mfma_f32_16x16x32_bf16 v[24:27], v[202:205], v[80:83], v[24:27]
	v_mfma_f32_16x16x32_bf16 v[20:23], v[188:191], v[168:171], v[20:23]
	v_mfma_f32_16x16x32_bf16 v[16:19], v[192:195], v[88:91], v[16:19]
	v_mfma_f32_16x16x32_bf16 v[12:15], v[104:107], v[172:175], v[12:15]
	v_mfma_f32_16x16x32_bf16 v[8:11], v[192:195], v[172:175], v[8:11]
	v_mfma_f32_16x16x32_bf16 v[4:7], v[104:107], v[180:183], v[4:7]
	v_mfma_f32_16x16x32_bf16 v[0:3], v[192:195], v[180:183], v[0:3]
	v_mfma_f32_16x16x32_bf16 v[144:147], v[188:191], v[80:83], v[28:31]
	v_mfma_f32_16x16x32_bf16 v[148:151], v[202:205], v[168:171], v[16:19]
	v_mfma_f32_16x16x32_bf16 v[152:155], v[188:191], v[176:179], v[12:15]
	v_mfma_f32_16x16x32_bf16 v[168:171], v[202:205], v[176:179], v[8:11]
	v_mfma_f32_16x16x32_bf16 v[172:175], v[188:191], v[184:187], v[4:7]
	v_mfma_f32_16x16x32_bf16 v[176:179], v[202:205], v[184:187], v[0:3]
	s_setprio 0
	s_barrier
	ds_read_b128 v[16:19], v138
	ds_read_b128 v[180:183], v138 offset:1024
	ds_read_b128 v[184:187], v138 offset:2048
	ds_read_b128 v[188:191], v138 offset:3072
	ds_read_b128 v[0:3], v136 offset:32768
	ds_read_b128 v[4:7], v136 offset:33792
	ds_read_b128 v[8:11], v135 offset:32768
	ds_read_b128 v[12:15], v135 offset:33792
	ds_read_b128 v[44:47], v134 offset:32768
	ds_read_b128 v[192:195], v134 offset:33792
	ds_read_b128 v[202:205], v133 offset:32768
	ds_read_b128 v[218:221], v133 offset:33792
	s_waitcnt vmcnt(2)
	s_barrier
	s_waitcnt lgkmcnt(0)
	s_setprio 1
	s_waitcnt lgkmcnt(0)
	v_mfma_f32_16x16x32_bf16 v[28:31], v[16:19], v[0:3], v[124:127]
	v_mfma_f32_16x16x32_bf16 v[52:55], v[180:183], v[4:7], v[28:31]
	v_mfma_f32_16x16x32_bf16 v[28:31], v[184:187], v[0:3], v[120:123]
	v_mfma_f32_16x16x32_bf16 v[104:107], v[188:191], v[4:7], v[28:31]
	v_mfma_f32_16x16x32_bf16 v[28:31], v[16:19], v[8:11], v[116:119]
	v_mfma_f32_16x16x32_bf16 v[72:75], v[180:183], v[12:15], v[28:31]
	v_mfma_f32_16x16x32_bf16 v[28:31], v[184:187], v[8:11], v[112:115]
	v_mfma_f32_16x16x32_bf16 v[116:119], v[188:191], v[12:15], v[28:31]
	v_mfma_f32_16x16x32_bf16 v[28:31], v[16:19], v[44:47], v[108:111]
	v_mfma_f32_16x16x32_bf16 v[80:83], v[180:183], v[192:195], v[28:31]
	v_mfma_f32_16x16x32_bf16 v[28:31], v[184:187], v[44:47], v[128:131]
	v_mfma_f32_16x16x32_bf16 v[108:111], v[188:191], v[192:195], v[28:31]
	v_mfma_f32_16x16x32_bf16 v[28:31], v[16:19], v[202:205], v[100:103]
	v_mfma_f32_16x16x32_bf16 v[88:91], v[180:183], v[218:221], v[28:31]
	v_mfma_f32_16x16x32_bf16 v[28:31], v[184:187], v[202:205], v[96:99]
	v_mfma_f32_16x16x32_bf16 v[96:99], v[188:191], v[218:221], v[28:31]
	s_setprio 0
	s_barrier
	ds_read_b128 v[128:131], v137
	ds_read_b128 v[222:225], v137 offset:1024
	ds_read_b128 v[228:231], v137 offset:2048
	ds_read_b128 v[232:235], v137 offset:3072
	s_waitcnt vmcnt(0)
	s_barrier
	s_waitcnt lgkmcnt(0)
	s_setprio 1
	s_waitcnt lgkmcnt(0)
	v_mfma_f32_16x16x32_bf16 v[28:31], v[128:131], v[0:3], v[92:95]
	v_mfma_f32_16x16x32_bf16 v[0:3], v[228:231], v[0:3], v[156:159]
	v_mfma_f32_16x16x32_bf16 v[28:31], v[222:225], v[4:7], v[28:31]
	v_mfma_f32_16x16x32_bf16 v[0:3], v[232:235], v[4:7], v[0:3]
	v_mfma_f32_16x16x32_bf16 v[4:7], v[128:131], v[8:11], v[84:87]
	v_mfma_f32_16x16x32_bf16 v[36:39], v[222:225], v[12:15], v[4:7]
	v_mfma_f32_16x16x32_bf16 v[4:7], v[228:231], v[8:11], v[160:163]
	v_mfma_f32_16x16x32_bf16 v[4:7], v[232:235], v[12:15], v[4:7]
	v_mfma_f32_16x16x32_bf16 v[8:11], v[128:131], v[44:47], v[76:79]
	v_mfma_f32_16x16x32_bf16 v[12:15], v[128:131], v[202:205], v[68:71]
	v_mfma_f32_16x16x32_bf16 v[40:43], v[222:225], v[192:195], v[8:11]
	v_mfma_f32_16x16x32_bf16 v[8:11], v[228:231], v[44:47], v[164:167]
	v_mfma_f32_16x16x32_bf16 v[44:47], v[222:225], v[218:221], v[12:15]
	v_mfma_f32_16x16x32_bf16 v[12:15], v[228:231], v[202:205], v[64:67]
	v_mfma_f32_16x16x32_bf16 v[8:11], v[232:235], v[192:195], v[8:11]
	v_mfma_f32_16x16x32_bf16 v[12:15], v[232:235], v[218:221], v[12:15]
	s_setprio 0
	s_barrier
	ds_read_b128 v[64:67], v136 offset:49152
	ds_read_b128 v[136:139], v136 offset:50176
	ds_read_b128 v[156:159], v135 offset:49152
	ds_read_b128 v[160:163], v135 offset:50176
	ds_read_b128 v[164:167], v134 offset:49152
	ds_read_b128 v[192:195], v134 offset:50176
	ds_read_b128 v[202:205], v133 offset:49152
	ds_read_b128 v[218:221], v133 offset:50176
	s_barrier
	s_waitcnt lgkmcnt(0)
	s_setprio 1
	s_waitcnt lgkmcnt(0)
	v_mfma_f32_16x16x32_bf16 v[56:59], v[184:187], v[64:67], v[56:59]
	v_mfma_f32_16x16x32_bf16 v[48:51], v[184:187], v[156:159], v[48:51]
	v_mfma_f32_16x16x32_bf16 v[60:63], v[16:19], v[64:67], v[60:63]
	v_mfma_f32_16x16x32_bf16 v[92:95], v[188:191], v[136:139], v[56:59]
	v_mfma_f32_16x16x32_bf16 v[56:59], v[16:19], v[156:159], v[206:209]
	v_mfma_f32_16x16x32_bf16 v[84:87], v[188:191], v[160:163], v[48:51]
	v_mfma_f32_16x16x32_bf16 v[48:51], v[16:19], v[164:167], v[210:213]
	v_mfma_f32_16x16x32_bf16 v[16:19], v[16:19], v[202:205], v[140:143]
	v_mfma_f32_16x16x32_bf16 v[120:123], v[180:183], v[192:195], v[48:51]
	v_mfma_f32_16x16x32_bf16 v[48:51], v[184:187], v[164:167], v[214:217]
	v_mfma_f32_16x16x32_bf16 v[124:127], v[180:183], v[218:221], v[16:19]
	v_mfma_f32_16x16x32_bf16 v[16:19], v[184:187], v[202:205], v[32:35]
	v_mfma_f32_16x16x32_bf16 v[100:103], v[180:183], v[136:139], v[60:63]
	v_mfma_f32_16x16x32_bf16 v[112:115], v[180:183], v[160:163], v[56:59]
	v_mfma_f32_16x16x32_bf16 v[76:79], v[188:191], v[192:195], v[48:51]
	v_mfma_f32_16x16x32_bf16 v[68:71], v[188:191], v[218:221], v[16:19]
	s_setprio 0
	s_setprio 1
	v_mfma_f32_16x16x32_bf16 v[16:19], v[128:131], v[64:67], v[144:147]
	v_mfma_f32_16x16x32_bf16 v[48:51], v[222:225], v[136:139], v[16:19]
	v_mfma_f32_16x16x32_bf16 v[16:19], v[228:231], v[64:67], v[24:27]
	v_mfma_f32_16x16x32_bf16 v[20:23], v[128:131], v[156:159], v[20:23]
	v_mfma_f32_16x16x32_bf16 v[24:27], v[128:131], v[164:167], v[152:155]
	v_mfma_f32_16x16x32_bf16 v[32:35], v[128:131], v[202:205], v[172:175]
	v_mfma_f32_16x16x32_bf16 v[56:59], v[222:225], v[160:163], v[20:23]
	v_mfma_f32_16x16x32_bf16 v[20:23], v[228:231], v[156:159], v[148:151]
	v_mfma_f32_16x16x32_bf16 v[60:63], v[222:225], v[192:195], v[24:27]
	v_mfma_f32_16x16x32_bf16 v[24:27], v[228:231], v[164:167], v[168:171]
	v_mfma_f32_16x16x32_bf16 v[64:67], v[222:225], v[218:221], v[32:35]
	v_mfma_f32_16x16x32_bf16 v[32:35], v[228:231], v[202:205], v[176:179]
	v_mfma_f32_16x16x32_bf16 v[16:19], v[232:235], v[136:139], v[16:19]
	v_mfma_f32_16x16x32_bf16 v[20:23], v[232:235], v[160:163], v[20:23]
	v_mfma_f32_16x16x32_bf16 v[24:27], v[232:235], v[192:195], v[24:27]
	v_mfma_f32_16x16x32_bf16 v[32:35], v[232:235], v[218:221], v[32:35]
	s_setprio 0
	s_movk_i32 s9, 0x100
	v_cmp_gt_u32_e32 vcc, s9, v132
	s_barrier
	s_and_saveexec_b64 s[28:29], vcc
	s_cbranch_execz .LBB0_212
	s_barrier
	s_branch .LBB0_212

.LBB0_314:
	ds_read_b128 v[172:175], v170
	ds_read_b128 v[176:179], v170 offset:1024
	ds_read_b128 v[180:183], v170 offset:2048
	ds_read_b128 v[184:187], v170 offset:3072
	s_add_u32 s8, s37, vcc_lo
	s_addc_u32 s9, s38, vcc_hi
	ds_read_b128 v[188:191], v166
	ds_read_b128 v[192:195], v166 offset:1024
	ds_read_b128 v[202:205], v165
	ds_read_b128 v[206:209], v165 offset:1024
	ds_read_b128 v[210:213], v163
	ds_read_b128 v[214:217], v163 offset:1024
	ds_read_b128 v[218:221], v162
	ds_read_b128 v[236:239], v162 offset:1024
	s_add_i32 s40, s34, 0xc000
	s_mov_b32 m0, s40
	s_add_i32 s41, s34, 0xe000
	s_add_u32 s98, s8, s94
	s_addc_u32 s99, s9, s95
	global_load_lds_dwordx4 v160, s[98:99]
	s_mov_b32 m0, s41
	s_nop 0
	global_load_lds_dwordx4 v161, s[98:99]
	s_waitcnt lgkmcnt(8)
	s_barrier
	s_waitcnt lgkmcnt(0)
	s_waitcnt lgkmcnt(0)
	v_mfma_f32_16x16x32_bf16 v[44:47], v[172:175], v[188:191], v[44:47]
	v_mfma_f32_16x16x32_bf16 v[40:43], v[180:183], v[188:191], v[40:43]
	v_mfma_f32_16x16x32_bf16 v[60:63], v[172:175], v[202:205], v[60:63]
	v_mfma_f32_16x16x32_bf16 v[56:59], v[180:183], v[202:205], v[56:59]
	v_mfma_f32_16x16x32_bf16 v[76:79], v[172:175], v[210:213], v[76:79]
	v_mfma_f32_16x16x32_bf16 v[72:75], v[180:183], v[210:213], v[72:75]
	v_mfma_f32_16x16x32_bf16 v[92:95], v[172:175], v[218:221], v[92:95]
	v_mfma_f32_16x16x32_bf16 v[88:91], v[180:183], v[218:221], v[88:91]
	v_mfma_f32_16x16x32_bf16 v[44:47], v[176:179], v[192:195], v[44:47]
	v_mfma_f32_16x16x32_bf16 v[40:43], v[184:187], v[192:195], v[40:43]
	v_mfma_f32_16x16x32_bf16 v[60:63], v[176:179], v[206:209], v[60:63]
	v_mfma_f32_16x16x32_bf16 v[56:59], v[184:187], v[206:209], v[56:59]
	v_mfma_f32_16x16x32_bf16 v[76:79], v[176:179], v[214:217], v[76:79]
	v_mfma_f32_16x16x32_bf16 v[72:75], v[184:187], v[214:217], v[72:75]
	v_mfma_f32_16x16x32_bf16 v[92:95], v[176:179], v[236:239], v[92:95]
	v_mfma_f32_16x16x32_bf16 v[88:91], v[184:187], v[236:239], v[88:91]
	s_barrier
	s_add_i32 s39, s39, 2
	s_add_u32 s28, s6, vcc_lo
	s_addc_u32 s29, s7, vcc_hi
	ds_read_b128 v[240:243], v169
	ds_read_b128 v[244:247], v169 offset:1024
	ds_read_b128 v[248:251], v169 offset:2048
	ds_read_b128 v[228:231], v169 offset:3072
	s_mov_b32 m0, s59
	s_add_u32 s98, s28, s0
	s_addc_u32 s99, s29, s1
	global_load_lds_dwordx4 v160, s[98:99]
	s_mov_b32 m0, s61
	s_nop 0
	global_load_lds_dwordx4 v161, s[98:99]
	s_barrier
	s_waitcnt lgkmcnt(0)
	s_waitcnt lgkmcnt(0)
	v_mfma_f32_16x16x32_bf16 v[32:35], v[240:243], v[188:191], v[32:35]
	v_mfma_f32_16x16x32_bf16 v[36:39], v[248:251], v[188:191], v[36:39]
	v_mfma_f32_16x16x32_bf16 v[48:51], v[240:243], v[202:205], v[48:51]
	v_mfma_f32_16x16x32_bf16 v[52:55], v[248:251], v[202:205], v[52:55]
	v_mfma_f32_16x16x32_bf16 v[64:67], v[240:243], v[210:213], v[64:67]
	v_mfma_f32_16x16x32_bf16 v[68:71], v[248:251], v[210:213], v[68:71]
	v_mfma_f32_16x16x32_bf16 v[80:83], v[240:243], v[218:221], v[80:83]
	v_mfma_f32_16x16x32_bf16 v[84:87], v[248:251], v[218:221], v[84:87]
	v_mfma_f32_16x16x32_bf16 v[32:35], v[244:247], v[192:195], v[32:35]
	v_mfma_f32_16x16x32_bf16 v[36:39], v[228:231], v[192:195], v[36:39]
	v_mfma_f32_16x16x32_bf16 v[48:51], v[244:247], v[206:209], v[48:51]
	v_mfma_f32_16x16x32_bf16 v[52:55], v[228:231], v[206:209], v[52:55]
	v_mfma_f32_16x16x32_bf16 v[64:67], v[244:247], v[214:217], v[64:67]
	v_mfma_f32_16x16x32_bf16 v[68:71], v[228:231], v[214:217], v[68:71]
	v_mfma_f32_16x16x32_bf16 v[80:83], v[244:247], v[236:239], v[80:83]
	v_mfma_f32_16x16x32_bf16 v[84:87], v[228:231], v[236:239], v[84:87]
	s_add_u32 s92, s90, vcc_lo
	s_addc_u32 s93, s91, vcc_hi
	s_barrier
	ds_read_b128 v[188:191], v166 offset:16384
	ds_read_b128 v[192:195], v166 offset:17408
	ds_read_b128 v[202:205], v165 offset:16384
	ds_read_b128 v[206:209], v165 offset:17408
	ds_read_b128 v[210:213], v163 offset:16384
	ds_read_b128 v[214:217], v163 offset:17408
	ds_read_b128 v[218:221], v162 offset:16384
	ds_read_b128 v[236:239], v162 offset:17408
	s_mov_b32 m0, s34
	s_add_u32 s98, s92, s0
	s_addc_u32 s99, s93, s1
	global_load_lds_dwordx4 v160, s[98:99]
	s_mov_b32 m0, s79
	s_nop 0
	global_load_lds_dwordx4 v161, s[98:99]
	s_barrier
	s_waitcnt lgkmcnt(0)
	s_waitcnt lgkmcnt(0)
	v_mfma_f32_16x16x32_bf16 v[108:111], v[172:175], v[188:191], v[108:111]
	v_mfma_f32_16x16x32_bf16 v[104:107], v[180:183], v[188:191], v[104:107]
	v_mfma_f32_16x16x32_bf16 v[124:127], v[172:175], v[202:205], v[124:127]
	v_mfma_f32_16x16x32_bf16 v[120:123], v[180:183], v[202:205], v[120:123]
	v_mfma_f32_16x16x32_bf16 v[140:143], v[172:175], v[210:213], v[140:143]
	v_mfma_f32_16x16x32_bf16 v[136:139], v[180:183], v[210:213], v[136:139]
	v_mfma_f32_16x16x32_bf16 v[156:159], v[172:175], v[218:221], v[156:159]
	v_mfma_f32_16x16x32_bf16 v[152:155], v[180:183], v[218:221], v[152:155]
	v_mfma_f32_16x16x32_bf16 v[108:111], v[176:179], v[192:195], v[108:111]
	v_mfma_f32_16x16x32_bf16 v[104:107], v[184:187], v[192:195], v[104:107]
	v_mfma_f32_16x16x32_bf16 v[124:127], v[176:179], v[206:209], v[124:127]
	v_mfma_f32_16x16x32_bf16 v[120:123], v[184:187], v[206:209], v[120:123]
	v_mfma_f32_16x16x32_bf16 v[140:143], v[176:179], v[214:217], v[140:143]
	v_mfma_f32_16x16x32_bf16 v[136:139], v[184:187], v[214:217], v[136:139]
	v_mfma_f32_16x16x32_bf16 v[156:159], v[176:179], v[236:239], v[156:159]
	v_mfma_f32_16x16x32_bf16 v[152:155], v[184:187], v[236:239], v[152:155]
	s_barrier
	s_add_u32 s96, s82, vcc_lo
	s_addc_u32 s97, s36, vcc_hi
	s_mov_b32 m0, s52
	s_add_u32 s98, s96, s0
	s_addc_u32 s99, s97, s1
	global_load_lds_dwordx4 v160, s[98:99]
	s_mov_b32 m0, s53
	s_nop 0
	global_load_lds_dwordx4 v161, s[98:99]
	s_waitcnt vmcnt(6)
	s_barrier
	v_mfma_f32_16x16x32_bf16 v[96:99], v[240:243], v[188:191], v[96:99]
	v_mfma_f32_16x16x32_bf16 v[100:103], v[248:251], v[188:191], v[100:103]
	v_mfma_f32_16x16x32_bf16 v[112:115], v[240:243], v[202:205], v[112:115]
	v_mfma_f32_16x16x32_bf16 v[116:119], v[248:251], v[202:205], v[116:119]
	v_mfma_f32_16x16x32_bf16 v[128:131], v[240:243], v[210:213], v[128:131]
	v_mfma_f32_16x16x32_bf16 v[132:135], v[248:251], v[210:213], v[132:135]
	v_mfma_f32_16x16x32_bf16 v[144:147], v[240:243], v[218:221], v[144:147]
	v_mfma_f32_16x16x32_bf16 v[148:151], v[248:251], v[218:221], v[148:151]
	v_mfma_f32_16x16x32_bf16 v[96:99], v[244:247], v[192:195], v[96:99]
	v_mfma_f32_16x16x32_bf16 v[100:103], v[228:231], v[192:195], v[100:103]
	v_mfma_f32_16x16x32_bf16 v[112:115], v[244:247], v[206:209], v[112:115]
	v_mfma_f32_16x16x32_bf16 v[116:119], v[228:231], v[206:209], v[116:119]
	v_mfma_f32_16x16x32_bf16 v[128:131], v[244:247], v[214:217], v[128:131]
	v_mfma_f32_16x16x32_bf16 v[132:135], v[228:231], v[214:217], v[132:135]
	v_mfma_f32_16x16x32_bf16 v[144:147], v[244:247], v[236:239], v[144:147]
	v_mfma_f32_16x16x32_bf16 v[148:151], v[228:231], v[236:239], v[148:151]
	s_barrier
	ds_read_b128 v[172:175], v168
	ds_read_b128 v[176:179], v168 offset:1024
	ds_read_b128 v[180:183], v168 offset:2048
	ds_read_b128 v[184:187], v168 offset:3072
	ds_read_b128 v[188:191], v166 offset:32768
	ds_read_b128 v[192:195], v166 offset:33792
	ds_read_b128 v[202:205], v165 offset:32768
	ds_read_b128 v[206:209], v165 offset:33792
	ds_read_b128 v[210:213], v163 offset:32768
	ds_read_b128 v[214:217], v163 offset:33792
	ds_read_b128 v[218:221], v162 offset:32768
	ds_read_b128 v[228:231], v162 offset:33792
	s_mov_b32 m0, s68
	s_add_u32 s98, s8, s0
	s_addc_u32 s99, s9, s1
	global_load_lds_dwordx4 v160, s[98:99]
	s_mov_b32 m0, s69
	s_nop 0
	global_load_lds_dwordx4 v161, s[98:99]
	s_waitcnt lgkmcnt(8)
	s_barrier
	s_waitcnt lgkmcnt(0)
	s_waitcnt lgkmcnt(0)
	v_mfma_f32_16x16x32_bf16 v[44:47], v[172:175], v[188:191], v[44:47]
	v_mfma_f32_16x16x32_bf16 v[40:43], v[180:183], v[188:191], v[40:43]
	v_mfma_f32_16x16x32_bf16 v[60:63], v[172:175], v[202:205], v[60:63]
	v_mfma_f32_16x16x32_bf16 v[56:59], v[180:183], v[202:205], v[56:59]
	v_mfma_f32_16x16x32_bf16 v[76:79], v[172:175], v[210:213], v[76:79]
	v_mfma_f32_16x16x32_bf16 v[72:75], v[180:183], v[210:213], v[72:75]
	v_mfma_f32_16x16x32_bf16 v[92:95], v[172:175], v[218:221], v[92:95]
	v_mfma_f32_16x16x32_bf16 v[88:91], v[180:183], v[218:221], v[88:91]
	v_mfma_f32_16x16x32_bf16 v[44:47], v[176:179], v[192:195], v[44:47]
	v_mfma_f32_16x16x32_bf16 v[40:43], v[184:187], v[192:195], v[40:43]
	v_mfma_f32_16x16x32_bf16 v[60:63], v[176:179], v[206:209], v[60:63]
	v_mfma_f32_16x16x32_bf16 v[56:59], v[184:187], v[206:209], v[56:59]
	v_mfma_f32_16x16x32_bf16 v[76:79], v[176:179], v[214:217], v[76:79]
	v_mfma_f32_16x16x32_bf16 v[72:75], v[184:187], v[214:217], v[72:75]
	v_mfma_f32_16x16x32_bf16 v[92:95], v[176:179], v[228:231], v[92:95]
	v_mfma_f32_16x16x32_bf16 v[88:91], v[184:187], v[228:231], v[88:91]
	s_barrier
	ds_read_b128 v[236:239], v167
	ds_read_b128 v[240:243], v167 offset:1024
	ds_read_b128 v[244:247], v167 offset:2048
	ds_read_b128 v[248:251], v167 offset:3072
	s_mov_b32 m0, s70
	s_add_u32 s98, s28, s30
	s_addc_u32 s99, s29, s31
	global_load_lds_dwordx4 v160, s[98:99]
	s_mov_b32 m0, s71
	s_nop 0
	global_load_lds_dwordx4 v161, s[98:99]
	s_barrier
	s_waitcnt lgkmcnt(0)
	s_waitcnt lgkmcnt(0)
	v_mfma_f32_16x16x32_bf16 v[32:35], v[236:239], v[188:191], v[32:35]
	v_mfma_f32_16x16x32_bf16 v[36:39], v[244:247], v[188:191], v[36:39]
	v_mfma_f32_16x16x32_bf16 v[48:51], v[236:239], v[202:205], v[48:51]
	v_mfma_f32_16x16x32_bf16 v[52:55], v[244:247], v[202:205], v[52:55]
	v_mfma_f32_16x16x32_bf16 v[64:67], v[236:239], v[210:213], v[64:67]
	v_mfma_f32_16x16x32_bf16 v[68:71], v[244:247], v[210:213], v[68:71]
	v_mfma_f32_16x16x32_bf16 v[80:83], v[236:239], v[218:221], v[80:83]
	v_mfma_f32_16x16x32_bf16 v[84:87], v[244:247], v[218:221], v[84:87]
	v_mfma_f32_16x16x32_bf16 v[32:35], v[240:243], v[192:195], v[32:35]
	v_mfma_f32_16x16x32_bf16 v[36:39], v[248:251], v[192:195], v[36:39]
	v_mfma_f32_16x16x32_bf16 v[48:51], v[240:243], v[206:209], v[48:51]
	v_mfma_f32_16x16x32_bf16 v[52:55], v[248:251], v[206:209], v[52:55]
	v_mfma_f32_16x16x32_bf16 v[64:67], v[240:243], v[214:217], v[64:67]
	v_mfma_f32_16x16x32_bf16 v[68:71], v[248:251], v[214:217], v[68:71]
	v_mfma_f32_16x16x32_bf16 v[80:83], v[240:243], v[228:231], v[80:83]
	v_mfma_f32_16x16x32_bf16 v[84:87], v[248:251], v[228:231], v[84:87]
	v_mov_b32_e32 v222, v161
	s_barrier
	ds_read_b128 v[188:191], v166 offset:49152
	ds_read_b128 v[192:195], v166 offset:50176
	ds_read_b128 v[202:205], v165 offset:49152
	ds_read_b128 v[206:209], v165 offset:50176
	ds_read_b128 v[210:213], v163 offset:49152
	ds_read_b128 v[214:217], v163 offset:50176
	ds_read_b128 v[218:221], v162 offset:49152
	ds_read_b128 v[228:231], v162 offset:50176
	v_mov_b32_e32 v223, v197
	s_mov_b32 m0, s72
	s_add_u32 s98, s92, s30
	s_addc_u32 s99, s93, s31
	global_load_lds_dwordx4 v160, s[98:99]
	s_mov_b32 m0, s73
	s_nop 0
	global_load_lds_dwordx4 v161, s[98:99]
	s_barrier
	s_waitcnt lgkmcnt(0)
	s_waitcnt lgkmcnt(0)
	v_mfma_f32_16x16x32_bf16 v[108:111], v[172:175], v[188:191], v[108:111]
	v_mfma_f32_16x16x32_bf16 v[104:107], v[180:183], v[188:191], v[104:107]
	v_mfma_f32_16x16x32_bf16 v[124:127], v[172:175], v[202:205], v[124:127]
	v_mfma_f32_16x16x32_bf16 v[120:123], v[180:183], v[202:205], v[120:123]
	v_mfma_f32_16x16x32_bf16 v[140:143], v[172:175], v[210:213], v[140:143]
	v_mfma_f32_16x16x32_bf16 v[136:139], v[180:183], v[210:213], v[136:139]
	v_mfma_f32_16x16x32_bf16 v[156:159], v[172:175], v[218:221], v[156:159]
	v_mfma_f32_16x16x32_bf16 v[152:155], v[180:183], v[218:221], v[152:155]
	v_mfma_f32_16x16x32_bf16 v[108:111], v[176:179], v[192:195], v[108:111]
	v_mfma_f32_16x16x32_bf16 v[104:107], v[184:187], v[192:195], v[104:107]
	v_mfma_f32_16x16x32_bf16 v[124:127], v[176:179], v[206:209], v[124:127]
	v_mfma_f32_16x16x32_bf16 v[120:123], v[184:187], v[206:209], v[120:123]
	v_mfma_f32_16x16x32_bf16 v[140:143], v[176:179], v[214:217], v[140:143]
	v_mfma_f32_16x16x32_bf16 v[136:139], v[184:187], v[214:217], v[136:139]
	v_mfma_f32_16x16x32_bf16 v[156:159], v[176:179], v[228:231], v[156:159]
	v_mfma_f32_16x16x32_bf16 v[152:155], v[184:187], v[228:231], v[152:155]
	s_barrier
	v_mov_b32_e32 v196, v160
	s_mov_b32 m0, s75
	s_add_u32 s98, s96, s30
	s_addc_u32 s99, s97, s31
	global_load_lds_dwordx4 v160, s[98:99]
	s_mov_b32 m0, s89
	s_nop 0
	global_load_lds_dwordx4 v161, s[98:99]
	s_waitcnt vmcnt(6)
	s_barrier
	v_mfma_f32_16x16x32_bf16 v[96:99], v[236:239], v[188:191], v[96:99]
	v_mfma_f32_16x16x32_bf16 v[100:103], v[244:247], v[188:191], v[100:103]
	v_mfma_f32_16x16x32_bf16 v[112:115], v[236:239], v[202:205], v[112:115]
	v_mfma_f32_16x16x32_bf16 v[116:119], v[244:247], v[202:205], v[116:119]
	v_mfma_f32_16x16x32_bf16 v[128:131], v[236:239], v[210:213], v[128:131]
	v_mfma_f32_16x16x32_bf16 v[132:135], v[244:247], v[210:213], v[132:135]
	v_mfma_f32_16x16x32_bf16 v[144:147], v[236:239], v[218:221], v[144:147]
	v_mfma_f32_16x16x32_bf16 v[148:151], v[244:247], v[218:221], v[148:151]
	v_mfma_f32_16x16x32_bf16 v[96:99], v[240:243], v[192:195], v[96:99]
	v_mfma_f32_16x16x32_bf16 v[100:103], v[248:251], v[192:195], v[100:103]
	v_mfma_f32_16x16x32_bf16 v[112:115], v[240:243], v[206:209], v[112:115]
	v_mfma_f32_16x16x32_bf16 v[116:119], v[248:251], v[206:209], v[116:119]
	v_mfma_f32_16x16x32_bf16 v[128:131], v[240:243], v[214:217], v[128:131]
	v_mfma_f32_16x16x32_bf16 v[132:135], v[248:251], v[214:217], v[132:135]
	v_mfma_f32_16x16x32_bf16 v[144:147], v[240:243], v[228:231], v[144:147]
	v_mfma_f32_16x16x32_bf16 v[148:151], v[248:251], v[228:231], v[148:151]
	s_add_u32 vcc_lo, vcc_lo, 0x100
	s_addc_u32 vcc_hi, vcc_hi, 0
	s_cmp_lt_u32 s39, s74
	s_barrier
	s_cbranch_scc1 .LBB0_314
	s_add_i32 s34, s33, -1
	s_lshl_b64 s[6:7], s[34:35], 7
	s_add_u32 s6, s84, s6
	s_addc_u32 s7, s85, s7
	s_mov_b32 m0, s40
	ds_read_b128 v[172:175], v170
	ds_read_b128 v[176:179], v170 offset:1024
	ds_read_b128 v[180:183], v170 offset:2048
	ds_read_b128 v[184:187], v170 offset:3072
	ds_read_b128 v[188:191], v166
	ds_read_b128 v[192:195], v166 offset:1024
	ds_read_b128 v[202:205], v165
	ds_read_b128 v[206:209], v165 offset:1024
	ds_read_b128 v[210:213], v163
	ds_read_b128 v[214:217], v163 offset:1024
	ds_read_b128 v[218:221], v162
	ds_read_b128 v[228:231], v162 offset:1024
	s_nop 0
	global_load_lds_dwordx4 v160, s[6:7]
	s_mov_b32 m0, s41
	s_nop 0
	global_load_lds_dwordx4 v161, s[6:7]
	s_barrier
	s_waitcnt lgkmcnt(0)
	s_setprio 1
	s_waitcnt lgkmcnt(0)
	v_mfma_f32_16x16x32_bf16 v[40:43], v[180:183], v[188:191], v[40:43]
	v_mfma_f32_16x16x32_bf16 v[56:59], v[180:183], v[202:205], v[56:59]
	v_mfma_f32_16x16x32_bf16 v[72:75], v[180:183], v[210:213], v[72:75]
	v_mfma_f32_16x16x32_bf16 v[92:95], v[172:175], v[218:221], v[92:95]
	v_mfma_f32_16x16x32_bf16 v[88:91], v[180:183], v[218:221], v[88:91]
	v_mfma_f32_16x16x32_bf16 v[44:47], v[172:175], v[188:191], v[44:47]
	v_mfma_f32_16x16x32_bf16 v[40:43], v[184:187], v[192:195], v[40:43]
	v_mfma_f32_16x16x32_bf16 v[60:63], v[172:175], v[202:205], v[60:63]
	v_mfma_f32_16x16x32_bf16 v[56:59], v[184:187], v[206:209], v[56:59]
	v_mfma_f32_16x16x32_bf16 v[76:79], v[172:175], v[210:213], v[76:79]
	v_mfma_f32_16x16x32_bf16 v[72:75], v[184:187], v[214:217], v[72:75]
	v_mfma_f32_16x16x32_bf16 v[92:95], v[176:179], v[228:231], v[92:95]
	v_mfma_f32_16x16x32_bf16 v[88:91], v[184:187], v[228:231], v[88:91]
	v_mfma_f32_16x16x32_bf16 v[44:47], v[176:179], v[192:195], v[44:47]
	v_mfma_f32_16x16x32_bf16 v[60:63], v[176:179], v[206:209], v[60:63]
	v_mfma_f32_16x16x32_bf16 v[76:79], v[176:179], v[214:217], v[76:79]
	s_setprio 0
	s_barrier
	ds_read_b128 v[236:239], v169
	ds_read_b128 v[240:243], v169 offset:1024
	ds_read_b128 v[244:247], v169 offset:2048
	ds_read_b128 v[248:251], v169 offset:3072
	s_barrier
	s_waitcnt lgkmcnt(0)
	s_setprio 1
	s_waitcnt lgkmcnt(0)
	v_mfma_f32_16x16x32_bf16 v[36:39], v[244:247], v[188:191], v[36:39]
	v_mfma_f32_16x16x32_bf16 v[32:35], v[236:239], v[188:191], v[32:35]
	v_mfma_f32_16x16x32_bf16 v[188:191], v[248:251], v[192:195], v[36:39]
	v_mfma_f32_16x16x32_bf16 v[36:39], v[236:239], v[202:205], v[48:51]
	v_mfma_f32_16x16x32_bf16 v[48:51], v[240:243], v[206:209], v[36:39]
	v_mfma_f32_16x16x32_bf16 v[36:39], v[244:247], v[202:205], v[52:55]
	v_mfma_f32_16x16x32_bf16 v[32:35], v[240:243], v[192:195], v[32:35]
	v_mfma_f32_16x16x32_bf16 v[192:195], v[248:251], v[206:209], v[36:39]
	v_mfma_f32_16x16x32_bf16 v[36:39], v[236:239], v[210:213], v[64:67]
	v_mfma_f32_16x16x32_bf16 v[64:67], v[240:243], v[214:217], v[36:39]
	v_mfma_f32_16x16x32_bf16 v[36:39], v[244:247], v[210:213], v[68:71]
	v_mfma_f32_16x16x32_bf16 v[202:205], v[248:251], v[214:217], v[36:39]
	v_mfma_f32_16x16x32_bf16 v[36:39], v[236:239], v[218:221], v[80:83]
	v_mfma_f32_16x16x32_bf16 v[80:83], v[240:243], v[228:231], v[36:39]
	v_mfma_f32_16x16x32_bf16 v[36:39], v[244:247], v[218:221], v[84:87]
	v_mfma_f32_16x16x32_bf16 v[206:209], v[248:251], v[228:231], v[36:39]
	s_setprio 0
	s_barrier
	s_nop 4
	ds_read_b128 v[36:39], v166 offset:16384
	ds_read_b128 v[52:55], v166 offset:17408
	ds_read_b128 v[68:71], v165 offset:16384
	ds_read_b128 v[84:87], v165 offset:17408
	ds_read_b128 v[210:213], v163 offset:16384
	ds_read_b128 v[214:217], v163 offset:17408
	ds_read_b128 v[218:221], v162 offset:16384
	ds_read_b128 v[228:231], v162 offset:17408
	s_waitcnt vmcnt(4)
	s_barrier
	s_waitcnt lgkmcnt(0)
	s_setprio 1
	s_waitcnt lgkmcnt(0)
	v_mfma_f32_16x16x32_bf16 v[108:111], v[172:175], v[36:39], v[108:111]
	v_mfma_f32_16x16x32_bf16 v[222:225], v[176:179], v[52:55], v[108:111]
	v_mfma_f32_16x16x32_bf16 v[108:111], v[172:175], v[68:71], v[124:127]
	v_mfma_f32_16x16x32_bf16 v[124:127], v[176:179], v[84:87], v[108:111]
	v_mfma_f32_16x16x32_bf16 v[108:111], v[180:183], v[68:71], v[120:123]
	v_mfma_f32_16x16x32_bf16 v[120:123], v[184:187], v[84:87], v[108:111]
	v_mfma_f32_16x16x32_bf16 v[108:111], v[172:175], v[210:213], v[140:143]
	v_mfma_f32_16x16x32_bf16 v[140:143], v[176:179], v[214:217], v[108:111]
	v_mfma_f32_16x16x32_bf16 v[108:111], v[180:183], v[210:213], v[136:139]
	v_mfma_f32_16x16x32_bf16 v[136:139], v[184:187], v[214:217], v[108:111]
	v_mfma_f32_16x16x32_bf16 v[108:111], v[172:175], v[218:221], v[156:159]
	v_mfma_f32_16x16x32_bf16 v[104:107], v[180:183], v[36:39], v[104:107]
	v_mfma_f32_16x16x32_bf16 v[156:159], v[176:179], v[228:231], v[108:111]
	v_mfma_f32_16x16x32_bf16 v[108:111], v[180:183], v[218:221], v[152:155]
	v_mfma_f32_16x16x32_bf16 v[104:107], v[184:187], v[52:55], v[104:107]
	v_mfma_f32_16x16x32_bf16 v[152:155], v[184:187], v[228:231], v[108:111]
	s_setprio 0
	s_setprio 1
	v_mfma_f32_16x16x32_bf16 v[96:99], v[236:239], v[36:39], v[96:99]
	v_mfma_f32_16x16x32_bf16 v[36:39], v[244:247], v[36:39], v[100:103]
	v_mfma_f32_16x16x32_bf16 v[172:175], v[248:251], v[52:55], v[36:39]
	v_mfma_f32_16x16x32_bf16 v[36:39], v[236:239], v[68:71], v[112:115]
	v_mfma_f32_16x16x32_bf16 v[112:115], v[240:243], v[84:87], v[36:39]
	v_mfma_f32_16x16x32_bf16 v[36:39], v[244:247], v[68:71], v[116:119]
	v_mfma_f32_16x16x32_bf16 v[180:183], v[248:251], v[84:87], v[36:39]
	v_mfma_f32_16x16x32_bf16 v[36:39], v[236:239], v[210:213], v[128:131]
	v_mfma_f32_16x16x32_bf16 v[128:131], v[240:243], v[214:217], v[36:39]
	v_mfma_f32_16x16x32_bf16 v[36:39], v[244:247], v[210:213], v[132:135]
	v_mfma_f32_16x16x32_bf16 v[184:187], v[248:251], v[214:217], v[36:39]
	v_mfma_f32_16x16x32_bf16 v[36:39], v[236:239], v[218:221], v[144:147]
	v_mfma_f32_16x16x32_bf16 v[96:99], v[240:243], v[52:55], v[96:99]
	v_mfma_f32_16x16x32_bf16 v[144:147], v[240:243], v[228:231], v[36:39]
	v_mfma_f32_16x16x32_bf16 v[36:39], v[244:247], v[218:221], v[148:151]
	v_mfma_f32_16x16x32_bf16 v[210:213], v[248:251], v[228:231], v[36:39]
	s_setprio 0
	s_barrier
	ds_read_b128 v[148:151], v168
	ds_read_b128 v[214:217], v168 offset:1024
	ds_read_b128 v[218:221], v168 offset:2048
	ds_read_b128 v[228:231], v168 offset:3072
	ds_read_b128 v[100:103], v166 offset:32768
	ds_read_b128 v[108:111], v166 offset:33792
	ds_read_b128 v[116:119], v165 offset:32768
	ds_read_b128 v[132:135], v165 offset:33792
	ds_read_b128 v[236:239], v163 offset:32768
	ds_read_b128 v[240:243], v163 offset:33792
	ds_read_b128 v[244:247], v162 offset:32768
	ds_read_b128 v[248:251], v162 offset:33792
	s_waitcnt vmcnt(2)
	s_barrier
	s_waitcnt lgkmcnt(0)
	s_setprio 1
	s_waitcnt lgkmcnt(0)
	v_mfma_f32_16x16x32_bf16 v[36:39], v[148:151], v[100:103], v[44:47]
	v_mfma_f32_16x16x32_bf16 v[44:47], v[148:151], v[116:119], v[60:63]
	v_mfma_f32_16x16x32_bf16 v[52:55], v[214:217], v[132:135], v[44:47]
	v_mfma_f32_16x16x32_bf16 v[44:47], v[218:221], v[116:119], v[56:59]
	v_mfma_f32_16x16x32_bf16 v[56:59], v[228:231], v[132:135], v[44:47]
	v_mfma_f32_16x16x32_bf16 v[44:47], v[148:151], v[236:239], v[76:79]
	v_mfma_f32_16x16x32_bf16 v[68:71], v[214:217], v[240:243], v[44:47]
	v_mfma_f32_16x16x32_bf16 v[44:47], v[218:221], v[236:239], v[72:75]
	v_mfma_f32_16x16x32_bf16 v[72:75], v[228:231], v[240:243], v[44:47]
	v_mfma_f32_16x16x32_bf16 v[44:47], v[148:151], v[244:247], v[92:95]
	v_mfma_f32_16x16x32_bf16 v[40:43], v[218:221], v[100:103], v[40:43]
	v_mfma_f32_16x16x32_bf16 v[84:87], v[214:217], v[248:251], v[44:47]
	v_mfma_f32_16x16x32_bf16 v[44:47], v[218:221], v[244:247], v[88:91]
	v_mfma_f32_16x16x32_bf16 v[36:39], v[214:217], v[108:111], v[36:39]
	v_mfma_f32_16x16x32_bf16 v[40:43], v[228:231], v[108:111], v[40:43]
	v_mfma_f32_16x16x32_bf16 v[88:91], v[228:231], v[248:251], v[44:47]
	s_setprio 0
	s_barrier
	s_nop 2
	ds_read_b128 v[44:47], v167
	ds_read_b128 v[60:63], v167 offset:1024
	ds_read_b128 v[76:79], v167 offset:2048
	ds_read_b128 v[232:235], v167 offset:3072
	s_waitcnt vmcnt(0)
	s_barrier
	s_waitcnt lgkmcnt(0)
	s_setprio 1
	s_waitcnt lgkmcnt(0)
	v_mfma_f32_16x16x32_bf16 v[92:95], v[76:79], v[100:103], v[188:191]
	v_mfma_f32_16x16x32_bf16 v[176:179], v[232:235], v[108:111], v[92:95]
	v_mfma_f32_16x16x32_bf16 v[92:95], v[76:79], v[116:119], v[192:195]
	v_mfma_f32_16x16x32_bf16 v[32:35], v[44:47], v[100:103], v[32:35]
	v_mfma_f32_16x16x32_bf16 v[48:51], v[44:47], v[116:119], v[48:51]
	v_mfma_f32_16x16x32_bf16 v[168:171], v[232:235], v[132:135], v[92:95]
	v_mfma_f32_16x16x32_bf16 v[64:67], v[44:47], v[236:239], v[64:67]
	v_mfma_f32_16x16x32_bf16 v[92:95], v[76:79], v[236:239], v[202:205]
	v_mfma_f32_16x16x32_bf16 v[80:83], v[44:47], v[244:247], v[80:83]
	v_mfma_f32_16x16x32_bf16 v[100:103], v[76:79], v[244:247], v[206:209]
	v_mfma_f32_16x16x32_bf16 v[32:35], v[60:63], v[108:111], v[32:35]
	v_mfma_f32_16x16x32_bf16 v[48:51], v[60:63], v[132:135], v[48:51]
	v_mfma_f32_16x16x32_bf16 v[64:67], v[60:63], v[240:243], v[64:67]
	v_mfma_f32_16x16x32_bf16 v[92:95], v[232:235], v[240:243], v[92:95]
	v_mfma_f32_16x16x32_bf16 v[80:83], v[60:63], v[248:251], v[80:83]
	v_mfma_f32_16x16x32_bf16 v[108:111], v[232:235], v[248:251], v[100:103]
	s_setprio 0
	s_barrier
	ds_read_b128 v[188:191], v166 offset:49152
	ds_read_b128 v[192:195], v166 offset:50176
	ds_read_b128 v[202:205], v165 offset:49152
	ds_read_b128 v[206:209], v165 offset:50176
	ds_read_b128 v[236:239], v163 offset:49152
	ds_read_b128 v[240:243], v163 offset:50176
	ds_read_b128 v[244:247], v162 offset:49152
	ds_read_b128 v[160:163], v162 offset:50176
	s_barrier
	s_waitcnt lgkmcnt(0)
	s_setprio 1
	s_waitcnt lgkmcnt(0)
	v_mfma_f32_16x16x32_bf16 v[116:119], v[148:151], v[202:205], v[124:127]
	v_mfma_f32_16x16x32_bf16 v[124:127], v[148:151], v[236:239], v[140:143]
	v_mfma_f32_16x16x32_bf16 v[132:135], v[214:217], v[240:243], v[124:127]
	v_mfma_f32_16x16x32_bf16 v[124:127], v[218:221], v[236:239], v[136:139]
	v_mfma_f32_16x16x32_bf16 v[136:139], v[228:231], v[240:243], v[124:127]
	v_mfma_f32_16x16x32_bf16 v[124:127], v[148:151], v[244:247], v[156:159]
	v_mfma_f32_16x16x32_bf16 v[100:103], v[148:151], v[188:191], v[222:225]
	v_mfma_f32_16x16x32_bf16 v[104:107], v[218:221], v[188:191], v[104:107]
	v_mfma_f32_16x16x32_bf16 v[120:123], v[218:221], v[202:205], v[120:123]
	v_mfma_f32_16x16x32_bf16 v[148:151], v[214:217], v[160:163], v[124:127]
	v_mfma_f32_16x16x32_bf16 v[124:127], v[218:221], v[244:247], v[152:155]
	v_mfma_f32_16x16x32_bf16 v[100:103], v[214:217], v[192:195], v[100:103]
	v_mfma_f32_16x16x32_bf16 v[104:107], v[228:231], v[192:195], v[104:107]
	v_mfma_f32_16x16x32_bf16 v[116:119], v[214:217], v[206:209], v[116:119]
	v_mfma_f32_16x16x32_bf16 v[120:123], v[228:231], v[206:209], v[120:123]
	v_mfma_f32_16x16x32_bf16 v[152:155], v[228:231], v[160:163], v[124:127]
	s_setprio 0
	s_setprio 1
	v_mfma_f32_16x16x32_bf16 v[96:99], v[44:47], v[188:191], v[96:99]
	v_mfma_f32_16x16x32_bf16 v[112:115], v[44:47], v[202:205], v[112:115]
	v_mfma_f32_16x16x32_bf16 v[128:131], v[44:47], v[236:239], v[128:131]
	v_mfma_f32_16x16x32_bf16 v[44:47], v[44:47], v[244:247], v[144:147]
	v_mfma_f32_16x16x32_bf16 v[124:127], v[76:79], v[188:191], v[172:175]
	v_mfma_f32_16x16x32_bf16 v[140:143], v[76:79], v[202:205], v[180:183]
	v_mfma_f32_16x16x32_bf16 v[156:159], v[76:79], v[236:239], v[184:187]
	v_mfma_f32_16x16x32_bf16 v[144:147], v[60:63], v[160:163], v[44:47]
	v_mfma_f32_16x16x32_bf16 v[44:47], v[76:79], v[244:247], v[210:213]
	v_mfma_f32_16x16x32_bf16 v[96:99], v[60:63], v[192:195], v[96:99]
	v_mfma_f32_16x16x32_bf16 v[124:127], v[232:235], v[192:195], v[124:127]
	v_mfma_f32_16x16x32_bf16 v[112:115], v[60:63], v[206:209], v[112:115]
	v_mfma_f32_16x16x32_bf16 v[140:143], v[232:235], v[206:209], v[140:143]
	v_mfma_f32_16x16x32_bf16 v[128:131], v[60:63], v[240:243], v[128:131]
	v_mfma_f32_16x16x32_bf16 v[156:159], v[232:235], v[240:243], v[156:159]
	v_mfma_f32_16x16x32_bf16 v[160:163], v[232:235], v[160:163], v[44:47]
	s_setprio 0
	s_movk_i32 s6, 0x100
	v_cmp_gt_u32_e32 vcc, s6, v164
	s_barrier
	s_and_saveexec_b64 s[6:7], vcc
	s_cbranch_execz .LBB0_317
	s_barrier

.LBB0_568:
	ds_read_b128 v[140:143], v129
	ds_read_b128 v[144:147], v129 offset:1024
	ds_read_b128 v[148:151], v129 offset:2048
	ds_read_b128 v[152:155], v129 offset:3072
	s_add_u32 s28, s8, s10
	s_addc_u32 s29, s9, s11
	ds_read_b128 v[156:159], v136
	ds_read_b128 v[160:163], v136 offset:1024
	ds_read_b128 v[164:167], v135
	ds_read_b128 v[168:171], v135 offset:1024
	ds_read_b128 v[172:175], v134
	ds_read_b128 v[176:179], v134 offset:1024
	ds_read_b128 v[180:183], v133
	ds_read_b128 v[184:187], v133 offset:1024
	s_add_i32 s39, s68, 0xc000
	s_mov_b32 m0, s39
	s_add_i32 s38, s68, 0xe000
	s_add_u32 s98, s28, s44
	s_addc_u32 s99, s29, s45
	global_load_lds_dwordx4 v128, s[98:99]
	s_mov_b32 m0, s38
	s_nop 0
	global_load_lds_dwordx4 v130, s[98:99]
	s_waitcnt lgkmcnt(8)
	s_barrier
	s_waitcnt lgkmcnt(0)
	s_waitcnt lgkmcnt(0)
	v_mfma_f32_16x16x32_bf16 v[124:127], v[140:143], v[156:159], v[124:127]
	v_mfma_f32_16x16x32_bf16 v[120:123], v[148:151], v[156:159], v[120:123]
	v_mfma_f32_16x16x32_bf16 v[116:119], v[140:143], v[164:167], v[116:119]
	v_mfma_f32_16x16x32_bf16 v[112:115], v[148:151], v[164:167], v[112:115]
	v_mfma_f32_16x16x32_bf16 v[108:111], v[140:143], v[172:175], v[108:111]
	v_mfma_f32_16x16x32_bf16 v[104:107], v[148:151], v[172:175], v[104:107]
	v_mfma_f32_16x16x32_bf16 v[100:103], v[140:143], v[180:183], v[100:103]
	v_mfma_f32_16x16x32_bf16 v[96:99], v[148:151], v[180:183], v[96:99]
	v_mfma_f32_16x16x32_bf16 v[124:127], v[144:147], v[160:163], v[124:127]
	v_mfma_f32_16x16x32_bf16 v[120:123], v[152:155], v[160:163], v[120:123]
	v_mfma_f32_16x16x32_bf16 v[116:119], v[144:147], v[168:171], v[116:119]
	v_mfma_f32_16x16x32_bf16 v[112:115], v[152:155], v[168:171], v[112:115]
	v_mfma_f32_16x16x32_bf16 v[108:111], v[144:147], v[176:179], v[108:111]
	v_mfma_f32_16x16x32_bf16 v[104:107], v[152:155], v[176:179], v[104:107]
	v_mfma_f32_16x16x32_bf16 v[100:103], v[144:147], v[184:187], v[100:103]
	v_mfma_f32_16x16x32_bf16 v[96:99], v[152:155], v[184:187], v[96:99]
	s_barrier
	s_add_u32 s56, s6, s10
	s_addc_u32 s57, s7, s11
	ds_read_b128 v[188:191], v139
	ds_read_b128 v[192:195], v139 offset:1024
	ds_read_b128 v[202:205], v139 offset:2048
	ds_read_b128 v[206:209], v139 offset:3072
	s_add_i32 m0, s68, 0x10000
	s_add_u32 s98, s56, s0
	s_addc_u32 s99, s57, s1
	global_load_lds_dwordx4 v128, s[98:99]
	s_add_i32 m0, s68, 0x12000
	s_nop 0
	global_load_lds_dwordx4 v130, s[98:99]
	s_barrier
	s_waitcnt lgkmcnt(0)
	s_waitcnt lgkmcnt(0)
	v_mfma_f32_16x16x32_bf16 v[92:95], v[188:191], v[156:159], v[92:95]
	v_mfma_f32_16x16x32_bf16 v[88:91], v[202:205], v[156:159], v[88:91]
	v_mfma_f32_16x16x32_bf16 v[84:87], v[188:191], v[164:167], v[84:87]
	v_mfma_f32_16x16x32_bf16 v[80:83], v[202:205], v[164:167], v[80:83]
	v_mfma_f32_16x16x32_bf16 v[76:79], v[188:191], v[172:175], v[76:79]
	v_mfma_f32_16x16x32_bf16 v[72:75], v[202:205], v[172:175], v[72:75]
	v_mfma_f32_16x16x32_bf16 v[68:71], v[188:191], v[180:183], v[68:71]
	v_mfma_f32_16x16x32_bf16 v[64:67], v[202:205], v[180:183], v[64:67]
	v_mfma_f32_16x16x32_bf16 v[92:95], v[192:195], v[160:163], v[92:95]
	v_mfma_f32_16x16x32_bf16 v[88:91], v[206:209], v[160:163], v[88:91]
	v_mfma_f32_16x16x32_bf16 v[84:87], v[192:195], v[168:171], v[84:87]
	v_mfma_f32_16x16x32_bf16 v[80:83], v[206:209], v[168:171], v[80:83]
	v_mfma_f32_16x16x32_bf16 v[76:79], v[192:195], v[176:179], v[76:79]
	v_mfma_f32_16x16x32_bf16 v[72:75], v[206:209], v[176:179], v[72:75]
	v_mfma_f32_16x16x32_bf16 v[68:71], v[192:195], v[184:187], v[68:71]
	v_mfma_f32_16x16x32_bf16 v[64:67], v[206:209], v[184:187], v[64:67]
	s_barrier
	ds_read_b128 v[156:159], v136 offset:16384
	ds_read_b128 v[160:163], v136 offset:17408
	ds_read_b128 v[164:167], v135 offset:16384
	ds_read_b128 v[168:171], v135 offset:17408
	ds_read_b128 v[172:175], v134 offset:16384
	ds_read_b128 v[176:179], v134 offset:17408
	ds_read_b128 v[180:183], v133 offset:16384
	ds_read_b128 v[184:187], v133 offset:17408
	s_mov_b32 m0, s68
	s_add_u32 s98, s28, s0
	s_addc_u32 s99, s29, s1
	global_load_lds_dwordx4 v128, s[98:99]
	s_add_i32 m0, s68, 0x2000
	s_nop 0
	global_load_lds_dwordx4 v130, s[98:99]
	s_barrier
	s_waitcnt lgkmcnt(0)
	s_waitcnt lgkmcnt(0)
	v_mfma_f32_16x16x32_bf16 v[60:63], v[140:143], v[156:159], v[60:63]
	v_mfma_f32_16x16x32_bf16 v[56:59], v[148:151], v[156:159], v[56:59]
	v_mfma_f32_16x16x32_bf16 v[52:55], v[140:143], v[164:167], v[52:55]
	v_mfma_f32_16x16x32_bf16 v[48:51], v[148:151], v[164:167], v[48:51]
	v_mfma_f32_16x16x32_bf16 v[44:47], v[140:143], v[172:175], v[44:47]
	v_mfma_f32_16x16x32_bf16 v[40:43], v[148:151], v[172:175], v[40:43]
	v_mfma_f32_16x16x32_bf16 v[36:39], v[140:143], v[180:183], v[36:39]
	v_mfma_f32_16x16x32_bf16 v[32:35], v[148:151], v[180:183], v[32:35]
	v_mfma_f32_16x16x32_bf16 v[60:63], v[144:147], v[160:163], v[60:63]
	v_mfma_f32_16x16x32_bf16 v[56:59], v[152:155], v[160:163], v[56:59]
	v_mfma_f32_16x16x32_bf16 v[52:55], v[144:147], v[168:171], v[52:55]
	v_mfma_f32_16x16x32_bf16 v[48:51], v[152:155], v[168:171], v[48:51]
	v_mfma_f32_16x16x32_bf16 v[44:47], v[144:147], v[176:179], v[44:47]
	v_mfma_f32_16x16x32_bf16 v[40:43], v[152:155], v[176:179], v[40:43]
	v_mfma_f32_16x16x32_bf16 v[36:39], v[144:147], v[184:187], v[36:39]
	v_mfma_f32_16x16x32_bf16 v[32:35], v[152:155], v[184:187], v[32:35]
	s_barrier
	s_add_i32 m0, s68, 0x14000
	s_add_u32 s98, s56, s46
	s_addc_u32 s99, s57, s47
	global_load_lds_dwordx4 v128, s[98:99]
	s_add_i32 m0, s68, 0x16000
	s_nop 0
	global_load_lds_dwordx4 v130, s[98:99]
	s_waitcnt vmcnt(6)
	s_barrier
	v_mfma_f32_16x16x32_bf16 v[28:31], v[188:191], v[156:159], v[28:31]
	v_mfma_f32_16x16x32_bf16 v[24:27], v[202:205], v[156:159], v[24:27]
	v_mfma_f32_16x16x32_bf16 v[20:23], v[188:191], v[164:167], v[20:23]
	v_mfma_f32_16x16x32_bf16 v[16:19], v[202:205], v[164:167], v[16:19]
	v_mfma_f32_16x16x32_bf16 v[12:15], v[188:191], v[172:175], v[12:15]
	v_mfma_f32_16x16x32_bf16 v[8:11], v[202:205], v[172:175], v[8:11]
	v_mfma_f32_16x16x32_bf16 v[4:7], v[188:191], v[180:183], v[4:7]
	v_mfma_f32_16x16x32_bf16 v[0:3], v[202:205], v[180:183], v[0:3]
	v_mfma_f32_16x16x32_bf16 v[28:31], v[192:195], v[160:163], v[28:31]
	v_mfma_f32_16x16x32_bf16 v[24:27], v[206:209], v[160:163], v[24:27]
	v_mfma_f32_16x16x32_bf16 v[20:23], v[192:195], v[168:171], v[20:23]
	v_mfma_f32_16x16x32_bf16 v[16:19], v[206:209], v[168:171], v[16:19]
	v_mfma_f32_16x16x32_bf16 v[12:15], v[192:195], v[176:179], v[12:15]
	v_mfma_f32_16x16x32_bf16 v[8:11], v[206:209], v[176:179], v[8:11]
	v_mfma_f32_16x16x32_bf16 v[4:7], v[192:195], v[184:187], v[4:7]
	v_mfma_f32_16x16x32_bf16 v[0:3], v[206:209], v[184:187], v[0:3]
	s_barrier
	ds_read_b128 v[140:143], v138
	ds_read_b128 v[144:147], v138 offset:1024
	ds_read_b128 v[148:151], v138 offset:2048
	ds_read_b128 v[152:155], v138 offset:3072
	ds_read_b128 v[156:159], v136 offset:32768
	ds_read_b128 v[160:163], v136 offset:33792
	ds_read_b128 v[164:167], v135 offset:32768
	ds_read_b128 v[168:171], v135 offset:33792
	ds_read_b128 v[172:175], v134 offset:32768
	ds_read_b128 v[176:179], v134 offset:33792
	ds_read_b128 v[180:183], v133 offset:32768
	ds_read_b128 v[184:187], v133 offset:33792
	s_add_i32 m0, s68, 0x4000
	s_add_u32 s98, s28, s46
	s_addc_u32 s99, s29, s47
	global_load_lds_dwordx4 v128, s[98:99]
	s_add_i32 m0, s68, 0x6000
	s_nop 0
	global_load_lds_dwordx4 v130, s[98:99]
	s_waitcnt lgkmcnt(8)
	s_barrier
	s_waitcnt lgkmcnt(0)
	s_waitcnt lgkmcnt(0)
	v_mfma_f32_16x16x32_bf16 v[124:127], v[140:143], v[156:159], v[124:127]
	v_mfma_f32_16x16x32_bf16 v[120:123], v[148:151], v[156:159], v[120:123]
	v_mfma_f32_16x16x32_bf16 v[116:119], v[140:143], v[164:167], v[116:119]
	v_mfma_f32_16x16x32_bf16 v[112:115], v[148:151], v[164:167], v[112:115]
	v_mfma_f32_16x16x32_bf16 v[108:111], v[140:143], v[172:175], v[108:111]
	v_mfma_f32_16x16x32_bf16 v[104:107], v[148:151], v[172:175], v[104:107]
	v_mfma_f32_16x16x32_bf16 v[100:103], v[140:143], v[180:183], v[100:103]
	v_mfma_f32_16x16x32_bf16 v[96:99], v[148:151], v[180:183], v[96:99]
	v_mfma_f32_16x16x32_bf16 v[124:127], v[144:147], v[160:163], v[124:127]
	v_mfma_f32_16x16x32_bf16 v[120:123], v[152:155], v[160:163], v[120:123]
	v_mfma_f32_16x16x32_bf16 v[116:119], v[144:147], v[168:171], v[116:119]
	v_mfma_f32_16x16x32_bf16 v[112:115], v[152:155], v[168:171], v[112:115]
	v_mfma_f32_16x16x32_bf16 v[108:111], v[144:147], v[176:179], v[108:111]
	v_mfma_f32_16x16x32_bf16 v[104:107], v[152:155], v[176:179], v[104:107]
	v_mfma_f32_16x16x32_bf16 v[100:103], v[144:147], v[184:187], v[100:103]
	v_mfma_f32_16x16x32_bf16 v[96:99], v[152:155], v[184:187], v[96:99]
	s_barrier
	ds_read_b128 v[188:191], v137
	ds_read_b128 v[192:195], v137 offset:1024
	ds_read_b128 v[202:205], v137 offset:2048
	ds_read_b128 v[206:209], v137 offset:3072
	s_mov_b32 m0, s69
	s_add_u32 s98, s56, s30
	s_addc_u32 s99, s57, s31
	global_load_lds_dwordx4 v128, s[98:99]
	s_mov_b32 m0, s70
	s_nop 0
	global_load_lds_dwordx4 v130, s[98:99]
	s_barrier
	s_waitcnt lgkmcnt(0)
	s_waitcnt lgkmcnt(0)
	v_mfma_f32_16x16x32_bf16 v[92:95], v[188:191], v[156:159], v[92:95]
	v_mfma_f32_16x16x32_bf16 v[88:91], v[202:205], v[156:159], v[88:91]
	v_mfma_f32_16x16x32_bf16 v[84:87], v[188:191], v[164:167], v[84:87]
	v_mfma_f32_16x16x32_bf16 v[80:83], v[202:205], v[164:167], v[80:83]
	v_mfma_f32_16x16x32_bf16 v[76:79], v[188:191], v[172:175], v[76:79]
	v_mfma_f32_16x16x32_bf16 v[72:75], v[202:205], v[172:175], v[72:75]
	v_mfma_f32_16x16x32_bf16 v[68:71], v[188:191], v[180:183], v[68:71]
	v_mfma_f32_16x16x32_bf16 v[64:67], v[202:205], v[180:183], v[64:67]
	v_mfma_f32_16x16x32_bf16 v[92:95], v[192:195], v[160:163], v[92:95]
	v_mfma_f32_16x16x32_bf16 v[88:91], v[206:209], v[160:163], v[88:91]
	v_mfma_f32_16x16x32_bf16 v[84:87], v[192:195], v[168:171], v[84:87]
	v_mfma_f32_16x16x32_bf16 v[80:83], v[206:209], v[168:171], v[80:83]
	v_mfma_f32_16x16x32_bf16 v[76:79], v[192:195], v[176:179], v[76:79]
	v_mfma_f32_16x16x32_bf16 v[72:75], v[206:209], v[176:179], v[72:75]
	v_mfma_f32_16x16x32_bf16 v[68:71], v[192:195], v[184:187], v[68:71]
	v_mfma_f32_16x16x32_bf16 v[64:67], v[206:209], v[184:187], v[64:67]
	v_mov_b32_e32 v210, v130
	s_barrier
	ds_read_b128 v[156:159], v136 offset:49152
	ds_read_b128 v[160:163], v136 offset:50176
	ds_read_b128 v[164:167], v135 offset:49152
	ds_read_b128 v[168:171], v135 offset:50176
	ds_read_b128 v[172:175], v134 offset:49152
	ds_read_b128 v[176:179], v134 offset:50176
	ds_read_b128 v[180:183], v133 offset:49152
	ds_read_b128 v[184:187], v133 offset:50176
	v_mov_b32_e32 v211, v197
	s_mov_b32 m0, s71
	s_add_u32 s98, s28, s30
	s_addc_u32 s99, s29, s31
	global_load_lds_dwordx4 v128, s[98:99]
	s_mov_b32 m0, s33
	s_nop 0
	global_load_lds_dwordx4 v130, s[98:99]
	s_barrier
	s_waitcnt lgkmcnt(0)
	s_waitcnt lgkmcnt(0)
	v_mfma_f32_16x16x32_bf16 v[60:63], v[140:143], v[156:159], v[60:63]
	v_mfma_f32_16x16x32_bf16 v[56:59], v[148:151], v[156:159], v[56:59]
	v_mfma_f32_16x16x32_bf16 v[52:55], v[140:143], v[164:167], v[52:55]
	v_mfma_f32_16x16x32_bf16 v[48:51], v[148:151], v[164:167], v[48:51]
	v_mfma_f32_16x16x32_bf16 v[44:47], v[140:143], v[172:175], v[44:47]
	v_mfma_f32_16x16x32_bf16 v[40:43], v[148:151], v[172:175], v[40:43]
	v_mfma_f32_16x16x32_bf16 v[36:39], v[140:143], v[180:183], v[36:39]
	v_mfma_f32_16x16x32_bf16 v[32:35], v[148:151], v[180:183], v[32:35]
	v_mfma_f32_16x16x32_bf16 v[60:63], v[144:147], v[160:163], v[60:63]
	v_mfma_f32_16x16x32_bf16 v[56:59], v[152:155], v[160:163], v[56:59]
	v_mfma_f32_16x16x32_bf16 v[52:55], v[144:147], v[168:171], v[52:55]
	v_mfma_f32_16x16x32_bf16 v[48:51], v[152:155], v[168:171], v[48:51]
	v_mfma_f32_16x16x32_bf16 v[44:47], v[144:147], v[176:179], v[44:47]
	v_mfma_f32_16x16x32_bf16 v[40:43], v[152:155], v[176:179], v[40:43]
	v_mfma_f32_16x16x32_bf16 v[36:39], v[144:147], v[184:187], v[36:39]
	v_mfma_f32_16x16x32_bf16 v[32:35], v[152:155], v[184:187], v[32:35]
	s_barrier
	v_mov_b32_e32 v196, v128
	s_mov_b32 m0, s72
	s_add_u32 s98, s56, s48
	s_addc_u32 s99, s57, s49
	global_load_lds_dwordx4 v128, s[98:99]
	s_mov_b32 m0, s36
	s_nop 0
	global_load_lds_dwordx4 v130, s[98:99]
	s_waitcnt vmcnt(6)
	s_barrier
	v_mfma_f32_16x16x32_bf16 v[28:31], v[188:191], v[156:159], v[28:31]
	v_mfma_f32_16x16x32_bf16 v[24:27], v[202:205], v[156:159], v[24:27]
	v_mfma_f32_16x16x32_bf16 v[20:23], v[188:191], v[164:167], v[20:23]
	v_mfma_f32_16x16x32_bf16 v[16:19], v[202:205], v[164:167], v[16:19]
	v_mfma_f32_16x16x32_bf16 v[12:15], v[188:191], v[172:175], v[12:15]
	v_mfma_f32_16x16x32_bf16 v[8:11], v[202:205], v[172:175], v[8:11]
	v_mfma_f32_16x16x32_bf16 v[4:7], v[188:191], v[180:183], v[4:7]
	v_mfma_f32_16x16x32_bf16 v[0:3], v[202:205], v[180:183], v[0:3]
	v_mfma_f32_16x16x32_bf16 v[28:31], v[192:195], v[160:163], v[28:31]
	v_mfma_f32_16x16x32_bf16 v[24:27], v[206:209], v[160:163], v[24:27]
	v_mfma_f32_16x16x32_bf16 v[20:23], v[192:195], v[168:171], v[20:23]
	v_mfma_f32_16x16x32_bf16 v[16:19], v[206:209], v[168:171], v[16:19]
	v_mfma_f32_16x16x32_bf16 v[12:15], v[192:195], v[176:179], v[12:15]
	v_mfma_f32_16x16x32_bf16 v[8:11], v[206:209], v[176:179], v[8:11]
	v_mfma_f32_16x16x32_bf16 v[4:7], v[192:195], v[184:187], v[4:7]
	v_mfma_f32_16x16x32_bf16 v[0:3], v[206:209], v[184:187], v[0:3]
	s_add_i32 s37, s37, 2
	s_add_u32 s10, s10, 0x100
	s_addc_u32 s11, s11, 0
	s_cmp_lt_u32 s37, 28
	s_barrier
	s_cbranch_scc1 .LBB0_568
	s_lshl_b64 s[4:5], s[4:5], 12
	s_add_u32 s4, s67, s4
	s_addc_u32 s5, s53, s5
	ds_read_b128 v[140:143], v129
	ds_read_b128 v[144:147], v129 offset:1024
	ds_read_b128 v[148:151], v129 offset:2048
	ds_read_b128 v[152:155], v129 offset:3072
	ds_read_b128 v[156:159], v136
	ds_read_b128 v[160:163], v136 offset:1024
	ds_read_b128 v[164:167], v135
	ds_read_b128 v[168:171], v135 offset:1024
	ds_read_b128 v[172:175], v134
	ds_read_b128 v[176:179], v134 offset:1024
	ds_read_b128 v[180:183], v133
	ds_read_b128 v[184:187], v133 offset:1024
	v_mov_b32_e32 v129, v197
	v_lshl_add_u64 v[128:129], s[4:5], 0, v[128:129]
	s_mov_b64 s[6:7], 0xf80
	s_mov_b32 m0, s39
	v_lshl_add_u64 v[128:129], v[128:129], 0, s[6:7]
	v_mov_b32_e32 v131, v197
	global_load_lds_dwordx4 v[128:129], off
	v_lshl_add_u64 v[128:129], s[4:5], 0, v[130:131]
	v_lshl_add_u64 v[128:129], v[128:129], 0, s[6:7]
	s_mov_b32 m0, s38
	s_nop 0
	global_load_lds_dwordx4 v[128:129], off
	s_barrier
	s_waitcnt lgkmcnt(0)
	s_setprio 1
	s_waitcnt lgkmcnt(0)
	v_mfma_f32_16x16x32_bf16 v[124:127], v[140:143], v[156:159], v[124:127]
	v_mfma_f32_16x16x32_bf16 v[120:123], v[148:151], v[156:159], v[120:123]
	v_mfma_f32_16x16x32_bf16 v[116:119], v[140:143], v[164:167], v[116:119]
	v_mfma_f32_16x16x32_bf16 v[112:115], v[148:151], v[164:167], v[112:115]
	v_mfma_f32_16x16x32_bf16 v[100:103], v[140:143], v[180:183], v[100:103]
	v_mfma_f32_16x16x32_bf16 v[96:99], v[148:151], v[180:183], v[96:99]
	v_mfma_f32_16x16x32_bf16 v[124:127], v[144:147], v[160:163], v[124:127]
	v_mfma_f32_16x16x32_bf16 v[120:123], v[152:155], v[160:163], v[120:123]
	v_mfma_f32_16x16x32_bf16 v[116:119], v[144:147], v[168:171], v[116:119]
	v_mfma_f32_16x16x32_bf16 v[112:115], v[152:155], v[168:171], v[112:115]
	v_mfma_f32_16x16x32_bf16 v[108:111], v[140:143], v[172:175], v[108:111]
	v_mfma_f32_16x16x32_bf16 v[104:107], v[148:151], v[172:175], v[104:107]
	v_mfma_f32_16x16x32_bf16 v[100:103], v[144:147], v[184:187], v[100:103]
	v_mfma_f32_16x16x32_bf16 v[96:99], v[152:155], v[184:187], v[96:99]
	v_mfma_f32_16x16x32_bf16 v[128:131], v[144:147], v[176:179], v[108:111]
	v_mfma_f32_16x16x32_bf16 v[188:191], v[152:155], v[176:179], v[104:107]
	s_setprio 0
	s_barrier
	s_nop 1
	ds_read_b128 v[104:107], v139
	ds_read_b128 v[108:111], v139 offset:1024
	ds_read_b128 v[192:195], v139 offset:2048
	ds_read_b128 v[202:205], v139 offset:3072
	s_barrier
	s_waitcnt lgkmcnt(0)
	s_setprio 1
	s_waitcnt lgkmcnt(0)
	v_mfma_f32_16x16x32_bf16 v[84:87], v[104:107], v[164:167], v[84:87]
	v_mfma_f32_16x16x32_bf16 v[80:83], v[192:195], v[164:167], v[80:83]
	v_mfma_f32_16x16x32_bf16 v[68:71], v[104:107], v[180:183], v[68:71]
	v_mfma_f32_16x16x32_bf16 v[64:67], v[192:195], v[180:183], v[64:67]
	v_mfma_f32_16x16x32_bf16 v[92:95], v[104:107], v[156:159], v[92:95]
	v_mfma_f32_16x16x32_bf16 v[88:91], v[192:195], v[156:159], v[88:91]
	v_mfma_f32_16x16x32_bf16 v[84:87], v[108:111], v[168:171], v[84:87]
	v_mfma_f32_16x16x32_bf16 v[80:83], v[202:205], v[168:171], v[80:83]
	v_mfma_f32_16x16x32_bf16 v[76:79], v[104:107], v[172:175], v[76:79]
	v_mfma_f32_16x16x32_bf16 v[72:75], v[192:195], v[172:175], v[72:75]
	v_mfma_f32_16x16x32_bf16 v[68:71], v[108:111], v[184:187], v[68:71]
	v_mfma_f32_16x16x32_bf16 v[64:67], v[202:205], v[184:187], v[64:67]
	v_mfma_f32_16x16x32_bf16 v[206:209], v[108:111], v[160:163], v[92:95]
	v_mfma_f32_16x16x32_bf16 v[156:159], v[202:205], v[160:163], v[88:91]
	v_mfma_f32_16x16x32_bf16 v[160:163], v[108:111], v[176:179], v[76:79]
	v_mfma_f32_16x16x32_bf16 v[164:167], v[202:205], v[176:179], v[72:75]
	s_setprio 0
	s_barrier
	s_nop 0
	ds_read_b128 v[72:75], v136 offset:16384
	ds_read_b128 v[76:79], v136 offset:17408
	ds_read_b128 v[88:91], v135 offset:16384
	ds_read_b128 v[92:95], v135 offset:17408
	ds_read_b128 v[168:171], v134 offset:16384
	ds_read_b128 v[172:175], v134 offset:17408
	ds_read_b128 v[176:179], v133 offset:16384
	ds_read_b128 v[180:183], v133 offset:17408
	s_waitcnt vmcnt(4)
	s_barrier
	s_waitcnt lgkmcnt(0)
	s_setprio 1
	s_waitcnt lgkmcnt(0)
	v_mfma_f32_16x16x32_bf16 v[60:63], v[140:143], v[72:75], v[60:63]
	v_mfma_f32_16x16x32_bf16 v[56:59], v[148:151], v[72:75], v[56:59]
	v_mfma_f32_16x16x32_bf16 v[52:55], v[140:143], v[88:91], v[52:55]
	v_mfma_f32_16x16x32_bf16 v[48:51], v[148:151], v[88:91], v[48:51]
	v_mfma_f32_16x16x32_bf16 v[36:39], v[140:143], v[176:179], v[36:39]
	v_mfma_f32_16x16x32_bf16 v[32:35], v[148:151], v[176:179], v[32:35]
	v_mfma_f32_16x16x32_bf16 v[60:63], v[144:147], v[76:79], v[60:63]
	v_mfma_f32_16x16x32_bf16 v[56:59], v[152:155], v[76:79], v[56:59]
	v_mfma_f32_16x16x32_bf16 v[52:55], v[144:147], v[92:95], v[52:55]
	v_mfma_f32_16x16x32_bf16 v[48:51], v[152:155], v[92:95], v[48:51]
	v_mfma_f32_16x16x32_bf16 v[44:47], v[140:143], v[168:171], v[44:47]
	v_mfma_f32_16x16x32_bf16 v[40:43], v[148:151], v[168:171], v[40:43]
	v_mfma_f32_16x16x32_bf16 v[36:39], v[144:147], v[180:183], v[36:39]
	v_mfma_f32_16x16x32_bf16 v[32:35], v[152:155], v[180:183], v[32:35]
	v_mfma_f32_16x16x32_bf16 v[184:187], v[144:147], v[172:175], v[44:47]
	v_mfma_f32_16x16x32_bf16 v[210:213], v[152:155], v[172:175], v[40:43]
	s_setprio 0
	s_setprio 1
	v_mfma_f32_16x16x32_bf16 v[20:23], v[104:107], v[88:91], v[20:23]
	v_mfma_f32_16x16x32_bf16 v[16:19], v[192:195], v[88:91], v[16:19]
	v_mfma_f32_16x16x32_bf16 v[4:7], v[104:107], v[176:179], v[4:7]
	v_mfma_f32_16x16x32_bf16 v[0:3], v[192:195], v[176:179], v[0:3]
	v_mfma_f32_16x16x32_bf16 v[28:31], v[104:107], v[72:75], v[28:31]
	v_mfma_f32_16x16x32_bf16 v[24:27], v[192:195], v[72:75], v[24:27]
	v_mfma_f32_16x16x32_bf16 v[20:23], v[108:111], v[92:95], v[20:23]
	v_mfma_f32_16x16x32_bf16 v[16:19], v[202:205], v[92:95], v[16:19]
	v_mfma_f32_16x16x32_bf16 v[12:15], v[104:107], v[168:171], v[12:15]
	v_mfma_f32_16x16x32_bf16 v[8:11], v[192:195], v[168:171], v[8:11]
	v_mfma_f32_16x16x32_bf16 v[4:7], v[108:111], v[180:183], v[4:7]
	v_mfma_f32_16x16x32_bf16 v[0:3], v[202:205], v[180:183], v[0:3]
	v_mfma_f32_16x16x32_bf16 v[140:143], v[108:111], v[76:79], v[28:31]
	v_mfma_f32_16x16x32_bf16 v[144:147], v[202:205], v[76:79], v[24:27]
	v_mfma_f32_16x16x32_bf16 v[148:151], v[108:111], v[172:175], v[12:15]
	v_mfma_f32_16x16x32_bf16 v[152:155], v[202:205], v[172:175], v[8:11]
	s_setprio 0
	s_barrier
	s_nop 0
	ds_read_b128 v[8:11], v138
	ds_read_b128 v[12:15], v138 offset:1024
	ds_read_b128 v[168:171], v138 offset:2048
	ds_read_b128 v[172:175], v138 offset:3072
	ds_read_b128 v[24:27], v136 offset:32768
	ds_read_b128 v[28:31], v136 offset:33792
	ds_read_b128 v[40:43], v135 offset:32768
	ds_read_b128 v[44:47], v135 offset:33792
	ds_read_b128 v[176:179], v134 offset:32768
	ds_read_b128 v[180:183], v134 offset:33792
	ds_read_b128 v[192:195], v133 offset:32768
	ds_read_b128 v[202:205], v133 offset:33792
	s_waitcnt vmcnt(2)
	s_barrier
	s_waitcnt lgkmcnt(0)
	s_setprio 1
	s_waitcnt lgkmcnt(0)
	v_mfma_f32_16x16x32_bf16 v[72:75], v[8:11], v[24:27], v[124:127]
	v_mfma_f32_16x16x32_bf16 v[124:127], v[12:15], v[28:31], v[72:75]
	v_mfma_f32_16x16x32_bf16 v[72:75], v[168:171], v[24:27], v[120:123]
	v_mfma_f32_16x16x32_bf16 v[120:123], v[172:175], v[28:31], v[72:75]
	v_mfma_f32_16x16x32_bf16 v[72:75], v[8:11], v[40:43], v[116:119]
	v_mfma_f32_16x16x32_bf16 v[108:111], v[12:15], v[44:47], v[72:75]
	v_mfma_f32_16x16x32_bf16 v[72:75], v[168:171], v[40:43], v[112:115]
	v_mfma_f32_16x16x32_bf16 v[104:107], v[172:175], v[44:47], v[72:75]
	v_mfma_f32_16x16x32_bf16 v[72:75], v[8:11], v[176:179], v[128:131]
	v_mfma_f32_16x16x32_bf16 v[92:95], v[12:15], v[180:183], v[72:75]
	v_mfma_f32_16x16x32_bf16 v[72:75], v[168:171], v[176:179], v[188:191]
	v_mfma_f32_16x16x32_bf16 v[88:91], v[172:175], v[180:183], v[72:75]
	v_mfma_f32_16x16x32_bf16 v[72:75], v[8:11], v[192:195], v[100:103]
	v_mfma_f32_16x16x32_bf16 v[76:79], v[12:15], v[202:205], v[72:75]
	v_mfma_f32_16x16x32_bf16 v[72:75], v[168:171], v[192:195], v[96:99]
	v_mfma_f32_16x16x32_bf16 v[72:75], v[172:175], v[202:205], v[72:75]
	s_setprio 0
	s_barrier
	ds_read_b128 v[128:131], v137
	ds_read_b128 v[188:191], v137 offset:1024
	ds_read_b128 v[214:217], v137 offset:2048
	ds_read_b128 v[218:221], v137 offset:3072
	s_waitcnt vmcnt(0)
	s_barrier
	s_waitcnt lgkmcnt(0)
	s_setprio 1
	s_waitcnt lgkmcnt(0)
	v_mfma_f32_16x16x32_bf16 v[96:99], v[128:131], v[24:27], v[206:209]
	v_mfma_f32_16x16x32_bf16 v[24:27], v[214:217], v[24:27], v[156:159]
	v_mfma_f32_16x16x32_bf16 v[112:115], v[218:221], v[28:31], v[24:27]
	v_mfma_f32_16x16x32_bf16 v[24:27], v[128:131], v[40:43], v[84:87]
	v_mfma_f32_16x16x32_bf16 v[100:103], v[188:191], v[44:47], v[24:27]
	v_mfma_f32_16x16x32_bf16 v[24:27], v[214:217], v[40:43], v[80:83]
	v_mfma_f32_16x16x32_bf16 v[116:119], v[188:191], v[28:31], v[96:99]
	v_mfma_f32_16x16x32_bf16 v[96:99], v[218:221], v[44:47], v[24:27]
	v_mfma_f32_16x16x32_bf16 v[24:27], v[128:131], v[176:179], v[160:163]
	v_mfma_f32_16x16x32_bf16 v[84:87], v[188:191], v[180:183], v[24:27]
	v_mfma_f32_16x16x32_bf16 v[24:27], v[214:217], v[176:179], v[164:167]
	v_mfma_f32_16x16x32_bf16 v[80:83], v[218:221], v[180:183], v[24:27]
	v_mfma_f32_16x16x32_bf16 v[24:27], v[128:131], v[192:195], v[68:71]
	v_mfma_f32_16x16x32_bf16 v[68:71], v[188:191], v[202:205], v[24:27]
	v_mfma_f32_16x16x32_bf16 v[24:27], v[214:217], v[192:195], v[64:67]
	v_mfma_f32_16x16x32_bf16 v[64:67], v[218:221], v[202:205], v[24:27]
	s_setprio 0
	s_barrier
	ds_read_b128 v[156:159], v136 offset:49152
	ds_read_b128 v[136:139], v136 offset:50176
	ds_read_b128 v[160:163], v135 offset:49152
	ds_read_b128 v[164:167], v135 offset:50176
	ds_read_b128 v[176:179], v134 offset:49152
	ds_read_b128 v[180:183], v134 offset:50176
	ds_read_b128 v[192:195], v133 offset:49152
	ds_read_b128 v[202:205], v133 offset:50176
	s_barrier
	s_waitcnt lgkmcnt(0)
	s_setprio 1
	s_waitcnt lgkmcnt(0)
	v_mfma_f32_16x16x32_bf16 v[24:27], v[8:11], v[156:159], v[60:63]
	v_mfma_f32_16x16x32_bf16 v[60:63], v[12:15], v[136:139], v[24:27]
	v_mfma_f32_16x16x32_bf16 v[24:27], v[168:171], v[156:159], v[56:59]
	v_mfma_f32_16x16x32_bf16 v[56:59], v[172:175], v[136:139], v[24:27]
	v_mfma_f32_16x16x32_bf16 v[24:27], v[8:11], v[160:163], v[52:55]
	v_mfma_f32_16x16x32_bf16 v[44:47], v[12:15], v[164:167], v[24:27]
	v_mfma_f32_16x16x32_bf16 v[24:27], v[168:171], v[160:163], v[48:51]
	v_mfma_f32_16x16x32_bf16 v[40:43], v[172:175], v[164:167], v[24:27]
	v_mfma_f32_16x16x32_bf16 v[24:27], v[8:11], v[176:179], v[184:187]
	v_mfma_f32_16x16x32_bf16 v[8:11], v[8:11], v[192:195], v[36:39]
	v_mfma_f32_16x16x32_bf16 v[28:31], v[12:15], v[180:183], v[24:27]
	v_mfma_f32_16x16x32_bf16 v[24:27], v[168:171], v[176:179], v[210:213]
	v_mfma_f32_16x16x32_bf16 v[12:15], v[12:15], v[202:205], v[8:11]
	v_mfma_f32_16x16x32_bf16 v[8:11], v[168:171], v[192:195], v[32:35]
	v_mfma_f32_16x16x32_bf16 v[24:27], v[172:175], v[180:183], v[24:27]
	v_mfma_f32_16x16x32_bf16 v[8:11], v[172:175], v[202:205], v[8:11]
	s_setprio 0
	s_setprio 1
	v_mfma_f32_16x16x32_bf16 v[32:35], v[128:131], v[156:159], v[140:143]
	v_mfma_f32_16x16x32_bf16 v[52:55], v[188:191], v[136:139], v[32:35]
	v_mfma_f32_16x16x32_bf16 v[32:35], v[214:217], v[156:159], v[144:147]
	v_mfma_f32_16x16x32_bf16 v[16:19], v[214:217], v[160:163], v[16:19]
	v_mfma_f32_16x16x32_bf16 v[48:51], v[218:221], v[136:139], v[32:35]
	v_mfma_f32_16x16x32_bf16 v[20:23], v[128:131], v[160:163], v[20:23]
	v_mfma_f32_16x16x32_bf16 v[32:35], v[218:221], v[164:167], v[16:19]
	v_mfma_f32_16x16x32_bf16 v[16:19], v[128:131], v[176:179], v[148:151]
	v_mfma_f32_16x16x32_bf16 v[36:39], v[188:191], v[164:167], v[20:23]
	v_mfma_f32_16x16x32_bf16 v[20:23], v[188:191], v[180:183], v[16:19]
	v_mfma_f32_16x16x32_bf16 v[16:19], v[214:217], v[176:179], v[152:155]
	v_mfma_f32_16x16x32_bf16 v[4:7], v[128:131], v[192:195], v[4:7]
	v_mfma_f32_16x16x32_bf16 v[0:3], v[214:217], v[192:195], v[0:3]
	v_mfma_f32_16x16x32_bf16 v[16:19], v[218:221], v[180:183], v[16:19]
	v_mfma_f32_16x16x32_bf16 v[4:7], v[188:191], v[202:205], v[4:7]
	v_mfma_f32_16x16x32_bf16 v[0:3], v[218:221], v[202:205], v[0:3]
	s_setprio 0
	s_movk_i32 s4, 0x100
	v_cmp_gt_u32_e32 vcc, s4, v132
	s_barrier
	s_and_saveexec_b64 s[4:5], vcc
	s_cbranch_execz .LBB0_571
	s_barrier
